# L-slot pattern: 2 ds_reads ahead of each LDS-DMA, remaining 8 reads after the last DMA
# baseline (speedup 1.0000x reference)
; #define PG8_STAGE(bufoff, gbase, voff) do { _Pragma("unroll") for (int _i = 0; _i < 2; ++_i) \
;         __builtin_amdgcn_global_load_lds((const unsigned*)((const char*)(gbase) + (voff)[_i]), (PG8_LAS unsigned*)(lds + (bufoff) + ldsw + _i * 8192), 16, 0, 0); } while (0)
; #define PG8_LDA(dst, b, h) do { _Pragma("unroll") for (int m = 0; m < 4; ++m) _Pragma("unroll") for (int k = 0; k < 2; ++k) dst[m][k] = *(const PG8_LAS bf16x8*)(lds + PG8_SA(b, h) + aoff + m * 2048 + k * 1024); } while (0)
; #define PG8_LDB(dst, b, h) do { _Pragma("unroll") for (int n = 0; n < 2; ++n) _Pragma("unroll") for (int k = 0; k < 2; ++k) dst[n][k] = *(const PG8_LAS bf16x8*)(lds + PG8_SB(b, h) + boff + n * 2048 + k * 1024); } while (0)
; #define PG8_MMA(ai, bj, At, Bt) do { __builtin_amdgcn_s_setprio(1); _Pragma("unroll") for (int m = 0; m < 4; ++m) _Pragma("unroll") for (int n = 0; n < 2; ++n) _Pragma("unroll") for (int k = 0; k < 2; ++k) \
;         acc[ai][bj][m][n] = __builtin_amdgcn_mfma_f32_16x16x32_bf16(Bt[n][k], At[m][k], acc[ai][bj][m][n], 0, 0, 0); __builtin_amdgcn_s_setprio(0); } while (0)
; #define PG8_WAIT_V(n) asm volatile("s_waitcnt vmcnt(" #n ")" ::: "memory")
; #define PG8_WAIT_L(n) asm volatile("s_waitcnt lgkmcnt(" #n ")" ::: "memory")
; #define PG8_BAR __builtin_amdgcn_s_barrier()
; #define PG8_SCHED __builtin_amdgcn_sched_barrier(0)
; template <class Epi, class Sched, bool ALIGN_EPI>
; __device__ __forceinline__ void gemm_phase(PG8_LAS unsigned char* lds, const Gemm g, const Sched& S, const Epi& E) {
;     ...
;             PG8_LDB(B0, 0, 0); PG8_LDB(B1, 0, 1); PG8_SCHED; PG8_LDA(At, 0, 0); PG8_STAGE(PG8_SA(1, 1), a1 + hstepA, voffA);
;             PG8_WAIT_V(8); PG8_WAIT_L(0); PG8_BAR; PG8_MMA(0, 0, At, B0); PG8_MMA(0, 1, At, B1); PG8_BAR; PG8_SCHED;
;             PG8_LDA(At, 0, 1); PG8_STAGE(PG8_SB(0, 0), b2, voffB); PG8_STAGE(PG8_SB(0, 1), b2 + hstepB, voffB); PG8_STAGE(PG8_SA(0, 0), a2, voffA);
;             PG8_WAIT_V(8); PG8_WAIT_L(0); PG8_BAR; PG8_MMA(1, 0, At, B0); PG8_MMA(1, 1, At, B1); PG8_BAR; PG8_SCHED;
;     ...
; #pragma unroll
;         for (int a = 0; a < 2; ++a)
; #pragma unroll
;             for (int b = 0; b < 2; ++b)
; #pragma unroll
;                 for (int m = 0; m < 4; ++m)
; #pragma unroll
;                     for (int n = 0; n < 2; ++n) acc[a][b][m][n] = (f32x4){0.f, 0.f, 0.f, 0.f};
.Lp8k_A_first:
	s_add_u32 s28, s30, 0x80
	s_addc_u32 s29, s31, 0
	ds_read_b128 v[190:193], v155 offset:0
	ds_read_b128 v[194:197], v155 offset:1024
	s_add_i32 m0, s2, 0x18000
	s_nop 0
	global_load_lds_dwordx4 v134, s[28:29]
	ds_read_b128 v[198:201], v155 offset:2048
	ds_read_b128 v[202:205], v155 offset:3072
	s_add_i32 m0, s2, 0x1a000
	s_nop 0
	global_load_lds_dwordx4 v130, s[28:29]
	ds_read_b128 v[206:209], v155 offset:4096
	ds_read_b128 v[210:213], v155 offset:5120
	s_add_u32 s30, s28, 0x20000
	s_addc_u32 s31, s29, 0
	s_add_i32 m0, s2, 0x19000
	s_nop 0
	global_load_lds_dwordx4 v134, s[30:31]
	ds_read_b128 v[214:217], v155 offset:6144
	ds_read_b128 v[218:221], v155 offset:7168
	s_add_i32 m0, s2, 0x1b000
	s_nop 0
	global_load_lds_dwordx4 v130, s[30:31]
	ds_read_b128 v[156:159], v153 offset:0
	ds_read_b128 v[160:163], v153 offset:1024
	s_add_u32 s30, s28, 0x80000
	s_addc_u32 s31, s29, 0
	s_add_i32 m0, s2, 0x1c000
	s_nop 0
	global_load_lds_dwordx4 v134, s[30:31]
	ds_read_b128 v[164:167], v153 offset:2048
	ds_read_b128 v[168:171], v153 offset:3072
	s_add_i32 m0, s2, 0x1e000
	s_nop 0
	global_load_lds_dwordx4 v130, s[30:31]
	ds_read_b128 v[174:177], v153 offset:16384
	ds_read_b128 v[178:181], v153 offset:17408
	s_add_u32 s30, s28, 0xa0000
	s_addc_u32 s31, s29, 0
	s_add_i32 m0, s2, 0x1d000
	s_nop 0
	global_load_lds_dwordx4 v134, s[30:31]
	ds_read_b128 v[182:185], v153 offset:18432
	ds_read_b128 v[186:189], v153 offset:19456
	s_add_i32 m0, s2, 0x1f000
	s_nop 0
	global_load_lds_dwordx4 v130, s[30:31]
	ds_read_b128 v[222:225], v155 offset:16384
	ds_read_b128 v[226:229], v155 offset:17408
	ds_read_b128 v[230:233], v155 offset:18432
	ds_read_b128 v[234:237], v155 offset:19456
	ds_read_b128 v[238:241], v155 offset:20480
	ds_read_b128 v[242:245], v155 offset:21504
	ds_read_b128 v[246:249], v155 offset:22528
	ds_read_b128 v[250:253], v155 offset:23552
	s_add_u32 s28, s28, 0x80
	s_addc_u32 s29, s29, 0
.Lp8k_A_entry:
	s_waitcnt vmcnt(8) lgkmcnt(0)
	s_barrier
	v_mfma_f32_16x16x32_bf16 v[126:129], v[156:159], v[190:193], 0
	v_mfma_f32_16x16x32_bf16 v[126:129], v[160:163], v[194:197], v[126:129]
	v_mfma_f32_16x16x32_bf16 v[122:125], v[168:171], v[194:197], 0
	v_mfma_f32_16x16x32_bf16 v[122:125], v[164:167], v[190:193], v[122:125]
	v_mfma_f32_16x16x32_bf16 v[118:121], v[174:177], v[190:193], 0
	v_mfma_f32_16x16x32_bf16 v[118:121], v[178:181], v[194:197], v[118:121]
	v_mfma_f32_16x16x32_bf16 v[114:117], v[186:189], v[194:197], 0
	v_mfma_f32_16x16x32_bf16 v[114:117], v[182:185], v[190:193], v[114:117]
	v_mfma_f32_16x16x32_bf16 v[98:101], v[182:185], v[198:201], 0
	v_mfma_f32_16x16x32_bf16 v[98:101], v[186:189], v[202:205], v[98:101]
	v_mfma_f32_16x16x32_bf16 v[102:105], v[178:181], v[202:205], 0
	v_mfma_f32_16x16x32_bf16 v[102:105], v[174:177], v[198:201], v[102:105]
	v_mfma_f32_16x16x32_bf16 v[106:109], v[164:167], v[198:201], 0
	v_mfma_f32_16x16x32_bf16 v[106:109], v[168:171], v[202:205], v[106:109]
	v_mfma_f32_16x16x32_bf16 v[110:113], v[160:163], v[202:205], 0
	v_mfma_f32_16x16x32_bf16 v[110:113], v[156:159], v[198:201], v[110:113]
	v_mfma_f32_16x16x32_bf16 v[94:97], v[156:159], v[206:209], 0
	v_mfma_f32_16x16x32_bf16 v[94:97], v[160:163], v[210:213], v[94:97]
	v_mfma_f32_16x16x32_bf16 v[90:93], v[168:171], v[210:213], 0
	v_mfma_f32_16x16x32_bf16 v[90:93], v[164:167], v[206:209], v[90:93]
	v_mfma_f32_16x16x32_bf16 v[86:89], v[174:177], v[206:209], 0
	v_mfma_f32_16x16x32_bf16 v[86:89], v[178:181], v[210:213], v[86:89]
	v_mfma_f32_16x16x32_bf16 v[82:85], v[186:189], v[210:213], 0
	v_mfma_f32_16x16x32_bf16 v[82:85], v[182:185], v[206:209], v[82:85]
	v_mfma_f32_16x16x32_bf16 v[66:69], v[182:185], v[214:217], 0
	v_mfma_f32_16x16x32_bf16 v[66:69], v[186:189], v[218:221], v[66:69]
	v_mfma_f32_16x16x32_bf16 v[70:73], v[178:181], v[218:221], 0
	v_mfma_f32_16x16x32_bf16 v[70:73], v[174:177], v[214:217], v[70:73]
	v_mfma_f32_16x16x32_bf16 v[74:77], v[164:167], v[214:217], 0
	v_mfma_f32_16x16x32_bf16 v[74:77], v[168:171], v[218:221], v[74:77]
	v_mfma_f32_16x16x32_bf16 v[78:81], v[160:163], v[218:221], 0
	v_mfma_f32_16x16x32_bf16 v[78:81], v[156:159], v[214:217], v[78:81]
	v_mfma_f32_16x16x32_bf16 v[62:65], v[156:159], v[222:225], 0
	v_mfma_f32_16x16x32_bf16 v[62:65], v[160:163], v[226:229], v[62:65]
	v_mfma_f32_16x16x32_bf16 v[58:61], v[168:171], v[226:229], 0
	v_mfma_f32_16x16x32_bf16 v[58:61], v[164:167], v[222:225], v[58:61]
	v_mfma_f32_16x16x32_bf16 v[54:57], v[174:177], v[222:225], 0
	v_mfma_f32_16x16x32_bf16 v[54:57], v[178:181], v[226:229], v[54:57]
	v_mfma_f32_16x16x32_bf16 v[50:53], v[186:189], v[226:229], 0
	v_mfma_f32_16x16x32_bf16 v[50:53], v[182:185], v[222:225], v[50:53]
	v_mfma_f32_16x16x32_bf16 v[34:37], v[182:185], v[230:233], 0
	v_mfma_f32_16x16x32_bf16 v[34:37], v[186:189], v[234:237], v[34:37]
	v_mfma_f32_16x16x32_bf16 v[38:41], v[178:181], v[234:237], 0
	v_mfma_f32_16x16x32_bf16 v[38:41], v[174:177], v[230:233], v[38:41]
	v_mfma_f32_16x16x32_bf16 v[42:45], v[164:167], v[230:233], 0
	v_mfma_f32_16x16x32_bf16 v[42:45], v[168:171], v[234:237], v[42:45]
	v_mfma_f32_16x16x32_bf16 v[46:49], v[160:163], v[234:237], 0
	v_mfma_f32_16x16x32_bf16 v[46:49], v[156:159], v[230:233], v[46:49]
	v_mfma_f32_16x16x32_bf16 v[30:33], v[156:159], v[238:241], 0
	v_mfma_f32_16x16x32_bf16 v[30:33], v[160:163], v[242:245], v[30:33]
	v_mfma_f32_16x16x32_bf16 v[26:29], v[168:171], v[242:245], 0
	v_mfma_f32_16x16x32_bf16 v[26:29], v[164:167], v[238:241], v[26:29]
	v_mfma_f32_16x16x32_bf16 v[22:25], v[174:177], v[238:241], 0
	v_mfma_f32_16x16x32_bf16 v[22:25], v[178:181], v[242:245], v[22:25]
	v_mfma_f32_16x16x32_bf16 v[18:21], v[186:189], v[242:245], 0
	v_mfma_f32_16x16x32_bf16 v[18:21], v[182:185], v[238:241], v[18:21]
	v_mfma_f32_16x16x32_bf16 v[2:5], v[182:185], v[246:249], 0
	v_mfma_f32_16x16x32_bf16 v[2:5], v[186:189], v[250:253], v[2:5]
	v_mfma_f32_16x16x32_bf16 v[6:9], v[178:181], v[250:253], 0
	v_mfma_f32_16x16x32_bf16 v[6:9], v[174:177], v[246:249], v[6:9]
	v_mfma_f32_16x16x32_bf16 v[10:13], v[164:167], v[246:249], 0
	v_mfma_f32_16x16x32_bf16 v[10:13], v[168:171], v[250:253], v[10:13]
	v_mfma_f32_16x16x32_bf16 v[14:17], v[160:163], v[250:253], 0
	v_mfma_f32_16x16x32_bf16 v[14:17], v[156:159], v[246:249], v[14:17]
	s_waitcnt vmcnt(0)
	s_barrier
; #define PG8_STAGE(bufoff, gbase, voff) do { _Pragma("unroll") for (int _i = 0; _i < 2; ++_i) \
;         __builtin_amdgcn_global_load_lds((const unsigned*)((const char*)(gbase) + (voff)[_i]), (PG8_LAS unsigned*)(lds + (bufoff) + ldsw + _i * 8192), 16, 0, 0); } while (0)
; #define PG8_LDA(dst, b, h) do { _Pragma("unroll") for (int m = 0; m < 4; ++m) _Pragma("unroll") for (int k = 0; k < 2; ++k) dst[m][k] = *(const PG8_LAS bf16x8*)(lds + PG8_SA(b, h) + aoff + m * 2048 + k * 1024); } while (0)
; #define PG8_LDB(dst, b, h) do { _Pragma("unroll") for (int n = 0; n < 2; ++n) _Pragma("unroll") for (int k = 0; k < 2; ++k) dst[n][k] = *(const PG8_LAS bf16x8*)(lds + PG8_SB(b, h) + boff + n * 2048 + k * 1024); } while (0)
; #define PG8_MMA(ai, bj, At, Bt) do { __builtin_amdgcn_s_setprio(1); _Pragma("unroll") for (int m = 0; m < 4; ++m) _Pragma("unroll") for (int n = 0; n < 2; ++n) _Pragma("unroll") for (int k = 0; k < 2; ++k) \
;         acc[ai][bj][m][n] = __builtin_amdgcn_mfma_f32_16x16x32_bf16(Bt[n][k], At[m][k], acc[ai][bj][m][n], 0, 0, 0); __builtin_amdgcn_s_setprio(0); } while (0)
; #define PG8_WAIT_V(n) asm volatile("s_waitcnt vmcnt(" #n ")" ::: "memory")
; #define PG8_WAIT_L(n) asm volatile("s_waitcnt lgkmcnt(" #n ")" ::: "memory")
; #define PG8_BAR __builtin_amdgcn_s_barrier()
; #define PG8_SCHED __builtin_amdgcn_sched_barrier(0)
; template <class Epi, class Sched, bool ALIGN_EPI>
; __device__ __forceinline__ void gemm_phase(PG8_LAS unsigned char* lds, const Gemm g, const Sched& S, const Epi& E) {
;     ...
;             PG8_LDA(At, 0, 1); PG8_STAGE(PG8_SB(0, 0), b2, voffB); PG8_STAGE(PG8_SB(0, 1), b2 + hstepB, voffB); PG8_STAGE(PG8_SA(0, 0), a2, voffA);
;             PG8_WAIT_V(8); PG8_WAIT_L(0); PG8_BAR; PG8_MMA(1, 0, At, B0); PG8_MMA(1, 1, At, B1); PG8_BAR; PG8_SCHED;
;             PG8_LDB(B0, 1, 0); PG8_LDB(B1, 1, 1); PG8_SCHED; PG8_LDA(At, 1, 0); PG8_STAGE(PG8_SA(0, 1), a2 + hstepA, voffA);
;             PG8_WAIT_V(8); PG8_WAIT_L(0); PG8_BAR; PG8_MMA(0, 0, At, B0); PG8_MMA(0, 1, At, B1); PG8_BAR; PG8_SCHED;
	ds_read_b128 v[190:193], v155 offset:32768
	ds_read_b128 v[194:197], v155 offset:33792
	s_cmp_eq_u32 s49, 15
	s_cselect_b32 s28, s50, s28
	s_cselect_b32 s29, s51, s29
	s_add_i32 m0, s2, 0x10000
	s_nop 0
	global_load_lds_dwordx4 v134, s[28:29]
	ds_read_b128 v[198:201], v155 offset:34816
	ds_read_b128 v[202:205], v155 offset:35840
	s_add_i32 m0, s2, 0x12000
	s_nop 0
	global_load_lds_dwordx4 v130, s[28:29]
	ds_read_b128 v[206:209], v155 offset:36864
	ds_read_b128 v[210:213], v155 offset:37888
	s_add_u32 s30, s28, 0x20000
	s_addc_u32 s31, s29, 0
	s_add_i32 m0, s2, 0x11000
	s_nop 0
	global_load_lds_dwordx4 v134, s[30:31]
	ds_read_b128 v[214:217], v155 offset:38912
	ds_read_b128 v[218:221], v155 offset:39936
	s_add_i32 m0, s2, 0x13000
	s_nop 0
	global_load_lds_dwordx4 v130, s[30:31]
	ds_read_b128 v[156:159], v153 offset:32768
	ds_read_b128 v[160:163], v153 offset:33792
	s_add_u32 s30, s28, 0x80000
	s_addc_u32 s31, s29, 0
	s_add_i32 m0, s2, 0x14000
	s_nop 0
	global_load_lds_dwordx4 v134, s[30:31]
	ds_read_b128 v[164:167], v153 offset:34816
	ds_read_b128 v[168:171], v153 offset:35840
	s_add_i32 m0, s2, 0x16000
	s_nop 0
	global_load_lds_dwordx4 v130, s[30:31]
	ds_read_b128 v[174:177], v153 offset:49152
	ds_read_b128 v[178:181], v153 offset:50176
	s_add_u32 s30, s28, 0xa0000
	s_addc_u32 s31, s29, 0
	s_add_i32 m0, s2, 0x15000
	s_nop 0
	global_load_lds_dwordx4 v134, s[30:31]
	ds_read_b128 v[182:185], v153 offset:51200
	ds_read_b128 v[186:189], v153 offset:52224
	s_add_i32 m0, s2, 0x17000
	s_nop 0
	global_load_lds_dwordx4 v130, s[30:31]
	ds_read_b128 v[222:225], v155 offset:49152
	ds_read_b128 v[226:229], v155 offset:50176
	ds_read_b128 v[230:233], v155 offset:51200
	ds_read_b128 v[234:237], v155 offset:52224
	ds_read_b128 v[238:241], v155 offset:53248
	ds_read_b128 v[242:245], v155 offset:54272
	ds_read_b128 v[246:249], v155 offset:55296
	ds_read_b128 v[250:253], v155 offset:56320
	s_add_u32 s28, s28, 0x80
	s_addc_u32 s29, s29, 0
	s_waitcnt vmcnt(8) lgkmcnt(0)
	s_barrier
	v_mfma_f32_16x16x32_bf16 v[126:129], v[156:159], v[190:193], v[126:129]
	v_mfma_f32_16x16x32_bf16 v[126:129], v[160:163], v[194:197], v[126:129]
	v_mfma_f32_16x16x32_bf16 v[122:125], v[168:171], v[194:197], v[122:125]
	v_mfma_f32_16x16x32_bf16 v[122:125], v[164:167], v[190:193], v[122:125]
	v_mfma_f32_16x16x32_bf16 v[118:121], v[174:177], v[190:193], v[118:121]
	v_mfma_f32_16x16x32_bf16 v[118:121], v[178:181], v[194:197], v[118:121]
	v_mfma_f32_16x16x32_bf16 v[114:117], v[186:189], v[194:197], v[114:117]
	v_mfma_f32_16x16x32_bf16 v[114:117], v[182:185], v[190:193], v[114:117]
	v_mfma_f32_16x16x32_bf16 v[98:101], v[182:185], v[198:201], v[98:101]
	v_mfma_f32_16x16x32_bf16 v[98:101], v[186:189], v[202:205], v[98:101]
	v_mfma_f32_16x16x32_bf16 v[102:105], v[178:181], v[202:205], v[102:105]
	v_mfma_f32_16x16x32_bf16 v[102:105], v[174:177], v[198:201], v[102:105]
	v_mfma_f32_16x16x32_bf16 v[106:109], v[164:167], v[198:201], v[106:109]
	v_mfma_f32_16x16x32_bf16 v[106:109], v[168:171], v[202:205], v[106:109]
	v_mfma_f32_16x16x32_bf16 v[110:113], v[160:163], v[202:205], v[110:113]
	v_mfma_f32_16x16x32_bf16 v[110:113], v[156:159], v[198:201], v[110:113]
	v_mfma_f32_16x16x32_bf16 v[94:97], v[156:159], v[206:209], v[94:97]
	v_mfma_f32_16x16x32_bf16 v[94:97], v[160:163], v[210:213], v[94:97]
	v_mfma_f32_16x16x32_bf16 v[90:93], v[168:171], v[210:213], v[90:93]
	v_mfma_f32_16x16x32_bf16 v[90:93], v[164:167], v[206:209], v[90:93]
	v_mfma_f32_16x16x32_bf16 v[86:89], v[174:177], v[206:209], v[86:89]
	v_mfma_f32_16x16x32_bf16 v[86:89], v[178:181], v[210:213], v[86:89]
	v_mfma_f32_16x16x32_bf16 v[82:85], v[186:189], v[210:213], v[82:85]
	v_mfma_f32_16x16x32_bf16 v[82:85], v[182:185], v[206:209], v[82:85]
	v_mfma_f32_16x16x32_bf16 v[66:69], v[182:185], v[214:217], v[66:69]
	v_mfma_f32_16x16x32_bf16 v[66:69], v[186:189], v[218:221], v[66:69]
	v_mfma_f32_16x16x32_bf16 v[70:73], v[178:181], v[218:221], v[70:73]
	v_mfma_f32_16x16x32_bf16 v[70:73], v[174:177], v[214:217], v[70:73]
	v_mfma_f32_16x16x32_bf16 v[74:77], v[164:167], v[214:217], v[74:77]
	v_mfma_f32_16x16x32_bf16 v[74:77], v[168:171], v[218:221], v[74:77]
	v_mfma_f32_16x16x32_bf16 v[78:81], v[160:163], v[218:221], v[78:81]
	v_mfma_f32_16x16x32_bf16 v[78:81], v[156:159], v[214:217], v[78:81]
	v_mfma_f32_16x16x32_bf16 v[62:65], v[156:159], v[222:225], v[62:65]
	v_mfma_f32_16x16x32_bf16 v[62:65], v[160:163], v[226:229], v[62:65]
	v_mfma_f32_16x16x32_bf16 v[58:61], v[168:171], v[226:229], v[58:61]
	v_mfma_f32_16x16x32_bf16 v[58:61], v[164:167], v[222:225], v[58:61]
	v_mfma_f32_16x16x32_bf16 v[54:57], v[174:177], v[222:225], v[54:57]
	v_mfma_f32_16x16x32_bf16 v[54:57], v[178:181], v[226:229], v[54:57]
	v_mfma_f32_16x16x32_bf16 v[50:53], v[186:189], v[226:229], v[50:53]
	v_mfma_f32_16x16x32_bf16 v[50:53], v[182:185], v[222:225], v[50:53]
	v_mfma_f32_16x16x32_bf16 v[34:37], v[182:185], v[230:233], v[34:37]
	v_mfma_f32_16x16x32_bf16 v[34:37], v[186:189], v[234:237], v[34:37]
	v_mfma_f32_16x16x32_bf16 v[38:41], v[178:181], v[234:237], v[38:41]
	v_mfma_f32_16x16x32_bf16 v[38:41], v[174:177], v[230:233], v[38:41]
	v_mfma_f32_16x16x32_bf16 v[42:45], v[164:167], v[230:233], v[42:45]
	v_mfma_f32_16x16x32_bf16 v[42:45], v[168:171], v[234:237], v[42:45]
	v_mfma_f32_16x16x32_bf16 v[46:49], v[160:163], v[234:237], v[46:49]
	v_mfma_f32_16x16x32_bf16 v[46:49], v[156:159], v[230:233], v[46:49]
	v_mfma_f32_16x16x32_bf16 v[30:33], v[156:159], v[238:241], v[30:33]
	v_mfma_f32_16x16x32_bf16 v[30:33], v[160:163], v[242:245], v[30:33]
	v_mfma_f32_16x16x32_bf16 v[26:29], v[168:171], v[242:245], v[26:29]
	v_mfma_f32_16x16x32_bf16 v[26:29], v[164:167], v[238:241], v[26:29]
	v_mfma_f32_16x16x32_bf16 v[22:25], v[174:177], v[238:241], v[22:25]
	v_mfma_f32_16x16x32_bf16 v[22:25], v[178:181], v[242:245], v[22:25]
	v_mfma_f32_16x16x32_bf16 v[18:21], v[186:189], v[242:245], v[18:21]
	v_mfma_f32_16x16x32_bf16 v[18:21], v[182:185], v[238:241], v[18:21]
	v_mfma_f32_16x16x32_bf16 v[2:5], v[182:185], v[246:249], v[2:5]
	v_mfma_f32_16x16x32_bf16 v[2:5], v[186:189], v[250:253], v[2:5]
	v_mfma_f32_16x16x32_bf16 v[6:9], v[178:181], v[250:253], v[6:9]
	v_mfma_f32_16x16x32_bf16 v[6:9], v[174:177], v[246:249], v[6:9]
	v_mfma_f32_16x16x32_bf16 v[10:13], v[164:167], v[246:249], v[10:13]
	v_mfma_f32_16x16x32_bf16 v[10:13], v[168:171], v[250:253], v[10:13]
	v_mfma_f32_16x16x32_bf16 v[14:17], v[160:163], v[250:253], v[14:17]
	v_mfma_f32_16x16x32_bf16 v[14:17], v[156:159], v[246:249], v[14:17]
	s_waitcnt vmcnt(0)
	s_barrier
	s_add_i32 s49, s49, 1
; #define PG8_STAGE(bufoff, gbase, voff) do { _Pragma("unroll") for (int _i = 0; _i < 2; ++_i) \
;         __builtin_amdgcn_global_load_lds((const unsigned*)((const char*)(gbase) + (voff)[_i]), (PG8_LAS unsigned*)(lds + (bufoff) + ldsw + _i * 8192), 16, 0, 0); } while (0)
; #define PG8_LDA(dst, b, h) do { _Pragma("unroll") for (int m = 0; m < 4; ++m) _Pragma("unroll") for (int k = 0; k < 2; ++k) dst[m][k] = *(const PG8_LAS bf16x8*)(lds + PG8_SA(b, h) + aoff + m * 2048 + k * 1024); } while (0)
; #define PG8_LDB(dst, b, h) do { _Pragma("unroll") for (int n = 0; n < 2; ++n) _Pragma("unroll") for (int k = 0; k < 2; ++k) dst[n][k] = *(const PG8_LAS bf16x8*)(lds + PG8_SB(b, h) + boff + n * 2048 + k * 1024); } while (0)
; #define PG8_MMA(ai, bj, At, Bt) do { __builtin_amdgcn_s_setprio(1); _Pragma("unroll") for (int m = 0; m < 4; ++m) _Pragma("unroll") for (int n = 0; n < 2; ++n) _Pragma("unroll") for (int k = 0; k < 2; ++k) \
;         acc[ai][bj][m][n] = __builtin_amdgcn_mfma_f32_16x16x32_bf16(Bt[n][k], At[m][k], acc[ai][bj][m][n], 0, 0, 0); __builtin_amdgcn_s_setprio(0); } while (0)
; #define PG8_WAIT_V(n) asm volatile("s_waitcnt vmcnt(" #n ")" ::: "memory")
; #define PG8_WAIT_L(n) asm volatile("s_waitcnt lgkmcnt(" #n ")" ::: "memory")
; #define PG8_BAR __builtin_amdgcn_s_barrier()
; #define PG8_SCHED __builtin_amdgcn_sched_barrier(0)
; template <class Epi, class Sched, bool ALIGN_EPI>
; __device__ __forceinline__ void gemm_phase(PG8_LAS unsigned char* lds, const Gemm g, const Sched& S, const Epi& E) {
;     ...
;             PG8_LDB(B0, 0, 0); PG8_LDB(B1, 0, 1); PG8_SCHED; PG8_LDA(At, 0, 0); PG8_STAGE(PG8_SA(1, 1), a1 + hstepA, voffA);
;             PG8_WAIT_V(8); PG8_WAIT_L(0); PG8_BAR; PG8_MMA(0, 0, At, B0); PG8_MMA(0, 1, At, B1); PG8_BAR; PG8_SCHED;
;             PG8_LDA(At, 0, 1); PG8_STAGE(PG8_SB(0, 0), b2, voffB); PG8_STAGE(PG8_SB(0, 1), b2 + hstepB, voffB); PG8_STAGE(PG8_SA(0, 0), a2, voffA);
;             PG8_WAIT_V(8); PG8_WAIT_L(0); PG8_BAR; PG8_MMA(1, 0, At, B0); PG8_MMA(1, 1, At, B1); PG8_BAR; PG8_SCHED;
.Lp8k_A_loop:
	ds_read_b128 v[190:193], v155 offset:0
	ds_read_b128 v[194:197], v155 offset:1024
	s_add_i32 m0, s2, 0x18000
	s_nop 0
	global_load_lds_dwordx4 v134, s[28:29]
	ds_read_b128 v[198:201], v155 offset:2048
	ds_read_b128 v[202:205], v155 offset:3072
	s_add_i32 m0, s2, 0x1a000
	s_nop 0
	global_load_lds_dwordx4 v130, s[28:29]
	ds_read_b128 v[206:209], v155 offset:4096
	ds_read_b128 v[210:213], v155 offset:5120
	s_add_u32 s30, s28, 0x20000
	s_addc_u32 s31, s29, 0
	s_add_i32 m0, s2, 0x19000
	s_nop 0
	global_load_lds_dwordx4 v134, s[30:31]
	ds_read_b128 v[214:217], v155 offset:6144
	ds_read_b128 v[218:221], v155 offset:7168
	s_add_i32 m0, s2, 0x1b000
	s_nop 0
	global_load_lds_dwordx4 v130, s[30:31]
	ds_read_b128 v[156:159], v153 offset:0
	ds_read_b128 v[160:163], v153 offset:1024
	s_add_u32 s30, s28, 0x80000
	s_addc_u32 s31, s29, 0
	s_add_i32 m0, s2, 0x1c000
	s_nop 0
	global_load_lds_dwordx4 v134, s[30:31]
	ds_read_b128 v[164:167], v153 offset:2048
	ds_read_b128 v[168:171], v153 offset:3072
	s_add_i32 m0, s2, 0x1e000
	s_nop 0
	global_load_lds_dwordx4 v130, s[30:31]
	ds_read_b128 v[174:177], v153 offset:16384
	ds_read_b128 v[178:181], v153 offset:17408
	s_add_u32 s30, s28, 0xa0000
	s_addc_u32 s31, s29, 0
	s_add_i32 m0, s2, 0x1d000
	s_nop 0
	global_load_lds_dwordx4 v134, s[30:31]
	ds_read_b128 v[182:185], v153 offset:18432
	ds_read_b128 v[186:189], v153 offset:19456
	s_add_i32 m0, s2, 0x1f000
	s_nop 0
	global_load_lds_dwordx4 v130, s[30:31]
	ds_read_b128 v[222:225], v155 offset:16384
	ds_read_b128 v[226:229], v155 offset:17408
	ds_read_b128 v[230:233], v155 offset:18432
	ds_read_b128 v[234:237], v155 offset:19456
	ds_read_b128 v[238:241], v155 offset:20480
	ds_read_b128 v[242:245], v155 offset:21504
	ds_read_b128 v[246:249], v155 offset:22528
	ds_read_b128 v[250:253], v155 offset:23552
	s_add_u32 s28, s28, 0x80
	s_addc_u32 s29, s29, 0
	s_waitcnt vmcnt(8) lgkmcnt(0)
	s_barrier
	v_mfma_f32_16x16x32_bf16 v[126:129], v[156:159], v[190:193], v[126:129]
	v_mfma_f32_16x16x32_bf16 v[126:129], v[160:163], v[194:197], v[126:129]
	v_mfma_f32_16x16x32_bf16 v[122:125], v[168:171], v[194:197], v[122:125]
	v_mfma_f32_16x16x32_bf16 v[122:125], v[164:167], v[190:193], v[122:125]
	v_mfma_f32_16x16x32_bf16 v[118:121], v[174:177], v[190:193], v[118:121]
	v_mfma_f32_16x16x32_bf16 v[118:121], v[178:181], v[194:197], v[118:121]
	v_mfma_f32_16x16x32_bf16 v[114:117], v[186:189], v[194:197], v[114:117]
	v_mfma_f32_16x16x32_bf16 v[114:117], v[182:185], v[190:193], v[114:117]
	v_mfma_f32_16x16x32_bf16 v[98:101], v[182:185], v[198:201], v[98:101]
	v_mfma_f32_16x16x32_bf16 v[98:101], v[186:189], v[202:205], v[98:101]
	v_mfma_f32_16x16x32_bf16 v[102:105], v[178:181], v[202:205], v[102:105]
	v_mfma_f32_16x16x32_bf16 v[102:105], v[174:177], v[198:201], v[102:105]
	v_mfma_f32_16x16x32_bf16 v[106:109], v[164:167], v[198:201], v[106:109]
	v_mfma_f32_16x16x32_bf16 v[106:109], v[168:171], v[202:205], v[106:109]
	v_mfma_f32_16x16x32_bf16 v[110:113], v[160:163], v[202:205], v[110:113]
	v_mfma_f32_16x16x32_bf16 v[110:113], v[156:159], v[198:201], v[110:113]
	v_mfma_f32_16x16x32_bf16 v[94:97], v[156:159], v[206:209], v[94:97]
	v_mfma_f32_16x16x32_bf16 v[94:97], v[160:163], v[210:213], v[94:97]
	v_mfma_f32_16x16x32_bf16 v[90:93], v[168:171], v[210:213], v[90:93]
	v_mfma_f32_16x16x32_bf16 v[90:93], v[164:167], v[206:209], v[90:93]
	v_mfma_f32_16x16x32_bf16 v[86:89], v[174:177], v[206:209], v[86:89]
	v_mfma_f32_16x16x32_bf16 v[86:89], v[178:181], v[210:213], v[86:89]
	v_mfma_f32_16x16x32_bf16 v[82:85], v[186:189], v[210:213], v[82:85]
	v_mfma_f32_16x16x32_bf16 v[82:85], v[182:185], v[206:209], v[82:85]
	v_mfma_f32_16x16x32_bf16 v[66:69], v[182:185], v[214:217], v[66:69]
	v_mfma_f32_16x16x32_bf16 v[66:69], v[186:189], v[218:221], v[66:69]
	v_mfma_f32_16x16x32_bf16 v[70:73], v[178:181], v[218:221], v[70:73]
	v_mfma_f32_16x16x32_bf16 v[70:73], v[174:177], v[214:217], v[70:73]
	v_mfma_f32_16x16x32_bf16 v[74:77], v[164:167], v[214:217], v[74:77]
	v_mfma_f32_16x16x32_bf16 v[74:77], v[168:171], v[218:221], v[74:77]
	v_mfma_f32_16x16x32_bf16 v[78:81], v[160:163], v[218:221], v[78:81]
	v_mfma_f32_16x16x32_bf16 v[78:81], v[156:159], v[214:217], v[78:81]
	v_mfma_f32_16x16x32_bf16 v[62:65], v[156:159], v[222:225], v[62:65]
	v_mfma_f32_16x16x32_bf16 v[62:65], v[160:163], v[226:229], v[62:65]
	v_mfma_f32_16x16x32_bf16 v[58:61], v[168:171], v[226:229], v[58:61]
	v_mfma_f32_16x16x32_bf16 v[58:61], v[164:167], v[222:225], v[58:61]
	v_mfma_f32_16x16x32_bf16 v[54:57], v[174:177], v[222:225], v[54:57]
	v_mfma_f32_16x16x32_bf16 v[54:57], v[178:181], v[226:229], v[54:57]
	v_mfma_f32_16x16x32_bf16 v[50:53], v[186:189], v[226:229], v[50:53]
	v_mfma_f32_16x16x32_bf16 v[50:53], v[182:185], v[222:225], v[50:53]
	v_mfma_f32_16x16x32_bf16 v[34:37], v[182:185], v[230:233], v[34:37]
	v_mfma_f32_16x16x32_bf16 v[34:37], v[186:189], v[234:237], v[34:37]
	v_mfma_f32_16x16x32_bf16 v[38:41], v[178:181], v[234:237], v[38:41]
	v_mfma_f32_16x16x32_bf16 v[38:41], v[174:177], v[230:233], v[38:41]
	v_mfma_f32_16x16x32_bf16 v[42:45], v[164:167], v[230:233], v[42:45]
	v_mfma_f32_16x16x32_bf16 v[42:45], v[168:171], v[234:237], v[42:45]
	v_mfma_f32_16x16x32_bf16 v[46:49], v[160:163], v[234:237], v[46:49]
	v_mfma_f32_16x16x32_bf16 v[46:49], v[156:159], v[230:233], v[46:49]
	v_mfma_f32_16x16x32_bf16 v[30:33], v[156:159], v[238:241], v[30:33]
	v_mfma_f32_16x16x32_bf16 v[30:33], v[160:163], v[242:245], v[30:33]
	v_mfma_f32_16x16x32_bf16 v[26:29], v[168:171], v[242:245], v[26:29]
	v_mfma_f32_16x16x32_bf16 v[26:29], v[164:167], v[238:241], v[26:29]
	v_mfma_f32_16x16x32_bf16 v[22:25], v[174:177], v[238:241], v[22:25]
	v_mfma_f32_16x16x32_bf16 v[22:25], v[178:181], v[242:245], v[22:25]
	v_mfma_f32_16x16x32_bf16 v[18:21], v[186:189], v[242:245], v[18:21]
	v_mfma_f32_16x16x32_bf16 v[18:21], v[182:185], v[238:241], v[18:21]
	v_mfma_f32_16x16x32_bf16 v[2:5], v[182:185], v[246:249], v[2:5]
	v_mfma_f32_16x16x32_bf16 v[2:5], v[186:189], v[250:253], v[2:5]
	v_mfma_f32_16x16x32_bf16 v[6:9], v[178:181], v[250:253], v[6:9]
	v_mfma_f32_16x16x32_bf16 v[6:9], v[174:177], v[246:249], v[6:9]
	v_mfma_f32_16x16x32_bf16 v[10:13], v[164:167], v[246:249], v[10:13]
	v_mfma_f32_16x16x32_bf16 v[10:13], v[168:171], v[250:253], v[10:13]
	v_mfma_f32_16x16x32_bf16 v[14:17], v[160:163], v[250:253], v[14:17]
	v_mfma_f32_16x16x32_bf16 v[14:17], v[156:159], v[246:249], v[14:17]
	s_waitcnt vmcnt(0)
	s_barrier
; #define PG8_STAGE(bufoff, gbase, voff) do { _Pragma("unroll") for (int _i = 0; _i < 2; ++_i) \
;         __builtin_amdgcn_global_load_lds((const unsigned*)((const char*)(gbase) + (voff)[_i]), (PG8_LAS unsigned*)(lds + (bufoff) + ldsw + _i * 8192), 16, 0, 0); } while (0)
; #define PG8_LDA(dst, b, h) do { _Pragma("unroll") for (int m = 0; m < 4; ++m) _Pragma("unroll") for (int k = 0; k < 2; ++k) dst[m][k] = *(const PG8_LAS bf16x8*)(lds + PG8_SA(b, h) + aoff + m * 2048 + k * 1024); } while (0)
; #define PG8_LDB(dst, b, h) do { _Pragma("unroll") for (int n = 0; n < 2; ++n) _Pragma("unroll") for (int k = 0; k < 2; ++k) dst[n][k] = *(const PG8_LAS bf16x8*)(lds + PG8_SB(b, h) + boff + n * 2048 + k * 1024); } while (0)
; #define PG8_MMA(ai, bj, At, Bt) do { __builtin_amdgcn_s_setprio(1); _Pragma("unroll") for (int m = 0; m < 4; ++m) _Pragma("unroll") for (int n = 0; n < 2; ++n) _Pragma("unroll") for (int k = 0; k < 2; ++k) \
;         acc[ai][bj][m][n] = __builtin_amdgcn_mfma_f32_16x16x32_bf16(Bt[n][k], At[m][k], acc[ai][bj][m][n], 0, 0, 0); __builtin_amdgcn_s_setprio(0); } while (0)
; #define PG8_WAIT_V(n) asm volatile("s_waitcnt vmcnt(" #n ")" ::: "memory")
; #define PG8_WAIT_L(n) asm volatile("s_waitcnt lgkmcnt(" #n ")" ::: "memory")
; #define PG8_BAR __builtin_amdgcn_s_barrier()
; #define PG8_SCHED __builtin_amdgcn_sched_barrier(0)
; template <class Epi, class Sched, bool ALIGN_EPI>
; __device__ __forceinline__ void gemm_phase(PG8_LAS unsigned char* lds, const Gemm g, const Sched& S, const Epi& E) {
;     ...
;             PG8_LDB(B0, 1, 0); PG8_LDB(B1, 1, 1); PG8_SCHED; PG8_LDA(At, 1, 0); PG8_STAGE(PG8_SA(0, 1), a2 + hstepA, voffA);
;             PG8_WAIT_V(8); PG8_WAIT_L(0); PG8_BAR; PG8_MMA(0, 0, At, B0); PG8_MMA(0, 1, At, B1); PG8_BAR; PG8_SCHED;
;             PG8_LDA(At, 1, 1); PG8_STAGE(PG8_SB(1, 0), b3, voffB); PG8_STAGE(PG8_SB(1, 1), b3 + hstepB, voffB); PG8_STAGE(PG8_SA(1, 0), a3, voffA);
	ds_read_b128 v[190:193], v155 offset:32768
	ds_read_b128 v[194:197], v155 offset:33792
	s_cmp_eq_u32 s49, 15
	s_cselect_b32 s28, s50, s28
	s_cselect_b32 s29, s51, s29
	s_add_i32 m0, s2, 0x10000
	s_nop 0
	global_load_lds_dwordx4 v134, s[28:29]
	ds_read_b128 v[198:201], v155 offset:34816
	ds_read_b128 v[202:205], v155 offset:35840
	s_add_i32 m0, s2, 0x12000
	s_nop 0
	global_load_lds_dwordx4 v130, s[28:29]
	ds_read_b128 v[206:209], v155 offset:36864
	ds_read_b128 v[210:213], v155 offset:37888
	s_add_u32 s30, s28, 0x20000
	s_addc_u32 s31, s29, 0
	s_add_i32 m0, s2, 0x11000
	s_nop 0
	global_load_lds_dwordx4 v134, s[30:31]
	ds_read_b128 v[214:217], v155 offset:38912
	ds_read_b128 v[218:221], v155 offset:39936
	s_add_i32 m0, s2, 0x13000
	s_nop 0
	global_load_lds_dwordx4 v130, s[30:31]
	ds_read_b128 v[156:159], v153 offset:32768
	ds_read_b128 v[160:163], v153 offset:33792
	s_add_u32 s30, s28, 0x80000
	s_addc_u32 s31, s29, 0
	s_add_i32 m0, s2, 0x14000
	s_nop 0
	global_load_lds_dwordx4 v134, s[30:31]
	ds_read_b128 v[164:167], v153 offset:34816
	ds_read_b128 v[168:171], v153 offset:35840
	s_add_i32 m0, s2, 0x16000
	s_nop 0
	global_load_lds_dwordx4 v130, s[30:31]
	ds_read_b128 v[174:177], v153 offset:49152
	ds_read_b128 v[178:181], v153 offset:50176
	s_add_u32 s30, s28, 0xa0000
	s_addc_u32 s31, s29, 0
	s_add_i32 m0, s2, 0x15000
	s_nop 0
	global_load_lds_dwordx4 v134, s[30:31]
	ds_read_b128 v[182:185], v153 offset:51200
	ds_read_b128 v[186:189], v153 offset:52224
	s_add_i32 m0, s2, 0x17000
	s_nop 0
	global_load_lds_dwordx4 v130, s[30:31]
	ds_read_b128 v[222:225], v155 offset:49152
	ds_read_b128 v[226:229], v155 offset:50176
	ds_read_b128 v[230:233], v155 offset:51200
	ds_read_b128 v[234:237], v155 offset:52224
	ds_read_b128 v[238:241], v155 offset:53248
	ds_read_b128 v[242:245], v155 offset:54272
	ds_read_b128 v[246:249], v155 offset:55296
	ds_read_b128 v[250:253], v155 offset:56320
	s_add_u32 s28, s28, 0x80
	s_addc_u32 s29, s29, 0
	s_waitcnt vmcnt(8) lgkmcnt(0)
	s_barrier
; #define PG8_STAGE(bufoff, gbase, voff) do { _Pragma("unroll") for (int _i = 0; _i < 2; ++_i) \
;         __builtin_amdgcn_global_load_lds((const unsigned*)((const char*)(gbase) + (voff)[_i]), (PG8_LAS unsigned*)(lds + (bufoff) + ldsw + _i * 8192), 16, 0, 0); } while (0)
; #define PG8_LDA(dst, b, h) do { _Pragma("unroll") for (int m = 0; m < 4; ++m) _Pragma("unroll") for (int k = 0; k < 2; ++k) dst[m][k] = *(const PG8_LAS bf16x8*)(lds + PG8_SA(b, h) + aoff + m * 2048 + k * 1024); } while (0)
; #define PG8_MMA(ai, bj, At, Bt) do { __builtin_amdgcn_s_setprio(1); _Pragma("unroll") for (int m = 0; m < 4; ++m) _Pragma("unroll") for (int n = 0; n < 2; ++n) _Pragma("unroll") for (int k = 0; k < 2; ++k) \
;         acc[ai][bj][m][n] = __builtin_amdgcn_mfma_f32_16x16x32_bf16(Bt[n][k], At[m][k], acc[ai][bj][m][n], 0, 0, 0); __builtin_amdgcn_s_setprio(0); } while (0)
; #define PG8_WAIT_V(n) asm volatile("s_waitcnt vmcnt(" #n ")" ::: "memory")
; #define PG8_WAIT_L(n) asm volatile("s_waitcnt lgkmcnt(" #n ")" ::: "memory")
; #define PG8_BAR __builtin_amdgcn_s_barrier()
; #define PG8_SCHED __builtin_amdgcn_sched_barrier(0)
; template <class Epi, class Sched, bool ALIGN_EPI>
; __device__ __forceinline__ void gemm_phase(PG8_LAS unsigned char* lds, const Gemm g, const Sched& S, const Epi& E) {
;     ...
;             PG8_WAIT_V(8); PG8_WAIT_L(0); PG8_BAR; PG8_MMA(0, 0, At, B0); PG8_MMA(0, 1, At, B1); PG8_BAR; PG8_SCHED;
;             PG8_LDA(At, 1, 1); PG8_STAGE(PG8_SB(1, 0), b3, voffB); PG8_STAGE(PG8_SB(1, 1), b3 + hstepB, voffB); PG8_STAGE(PG8_SA(1, 0), a3, voffA);
;             PG8_WAIT_V(8); PG8_WAIT_L(0); PG8_BAR; PG8_MMA(1, 0, At, B0); PG8_MMA(1, 1, At, B1); PG8_BAR; PG8_SCHED;
;         }
;         if constexpr (ALIGN_EPI) { if (wr == 0) PG8_BAR; }
;         E(acc, cur, wr, wc, fr, fq);
;         if (!has_next) break;
	v_mfma_f32_16x16x32_bf16 v[126:129], v[156:159], v[190:193], v[126:129]
	v_mfma_f32_16x16x32_bf16 v[126:129], v[160:163], v[194:197], v[126:129]
	v_mfma_f32_16x16x32_bf16 v[122:125], v[168:171], v[194:197], v[122:125]
	v_mfma_f32_16x16x32_bf16 v[122:125], v[164:167], v[190:193], v[122:125]
	v_mfma_f32_16x16x32_bf16 v[118:121], v[174:177], v[190:193], v[118:121]
	v_mfma_f32_16x16x32_bf16 v[118:121], v[178:181], v[194:197], v[118:121]
	v_mfma_f32_16x16x32_bf16 v[114:117], v[186:189], v[194:197], v[114:117]
	v_mfma_f32_16x16x32_bf16 v[114:117], v[182:185], v[190:193], v[114:117]
	v_mfma_f32_16x16x32_bf16 v[98:101], v[182:185], v[198:201], v[98:101]
	v_mfma_f32_16x16x32_bf16 v[98:101], v[186:189], v[202:205], v[98:101]
	v_mfma_f32_16x16x32_bf16 v[102:105], v[178:181], v[202:205], v[102:105]
	v_mfma_f32_16x16x32_bf16 v[102:105], v[174:177], v[198:201], v[102:105]
	v_mfma_f32_16x16x32_bf16 v[106:109], v[164:167], v[198:201], v[106:109]
	v_mfma_f32_16x16x32_bf16 v[106:109], v[168:171], v[202:205], v[106:109]
	v_mfma_f32_16x16x32_bf16 v[110:113], v[160:163], v[202:205], v[110:113]
	v_mfma_f32_16x16x32_bf16 v[110:113], v[156:159], v[198:201], v[110:113]
	v_mfma_f32_16x16x32_bf16 v[94:97], v[156:159], v[206:209], v[94:97]
	v_mfma_f32_16x16x32_bf16 v[94:97], v[160:163], v[210:213], v[94:97]
	v_mfma_f32_16x16x32_bf16 v[90:93], v[168:171], v[210:213], v[90:93]
	v_mfma_f32_16x16x32_bf16 v[90:93], v[164:167], v[206:209], v[90:93]
	v_mfma_f32_16x16x32_bf16 v[86:89], v[174:177], v[206:209], v[86:89]
	v_mfma_f32_16x16x32_bf16 v[86:89], v[178:181], v[210:213], v[86:89]
	v_mfma_f32_16x16x32_bf16 v[82:85], v[186:189], v[210:213], v[82:85]
	v_mfma_f32_16x16x32_bf16 v[82:85], v[182:185], v[206:209], v[82:85]
	v_mfma_f32_16x16x32_bf16 v[66:69], v[182:185], v[214:217], v[66:69]
	v_mfma_f32_16x16x32_bf16 v[66:69], v[186:189], v[218:221], v[66:69]
	v_mfma_f32_16x16x32_bf16 v[70:73], v[178:181], v[218:221], v[70:73]
	v_mfma_f32_16x16x32_bf16 v[70:73], v[174:177], v[214:217], v[70:73]
	v_mfma_f32_16x16x32_bf16 v[74:77], v[164:167], v[214:217], v[74:77]
	v_mfma_f32_16x16x32_bf16 v[74:77], v[168:171], v[218:221], v[74:77]
	v_mfma_f32_16x16x32_bf16 v[78:81], v[160:163], v[218:221], v[78:81]
	v_mfma_f32_16x16x32_bf16 v[78:81], v[156:159], v[214:217], v[78:81]
	v_mfma_f32_16x16x32_bf16 v[62:65], v[156:159], v[222:225], v[62:65]
	v_mfma_f32_16x16x32_bf16 v[62:65], v[160:163], v[226:229], v[62:65]
	v_mfma_f32_16x16x32_bf16 v[58:61], v[168:171], v[226:229], v[58:61]
	v_mfma_f32_16x16x32_bf16 v[58:61], v[164:167], v[222:225], v[58:61]
	v_mfma_f32_16x16x32_bf16 v[54:57], v[174:177], v[222:225], v[54:57]
	v_mfma_f32_16x16x32_bf16 v[54:57], v[178:181], v[226:229], v[54:57]
	v_mfma_f32_16x16x32_bf16 v[50:53], v[186:189], v[226:229], v[50:53]
	v_mfma_f32_16x16x32_bf16 v[50:53], v[182:185], v[222:225], v[50:53]
	v_mfma_f32_16x16x32_bf16 v[34:37], v[182:185], v[230:233], v[34:37]
	v_mfma_f32_16x16x32_bf16 v[34:37], v[186:189], v[234:237], v[34:37]
	v_mfma_f32_16x16x32_bf16 v[38:41], v[178:181], v[234:237], v[38:41]
	v_mfma_f32_16x16x32_bf16 v[38:41], v[174:177], v[230:233], v[38:41]
	v_mfma_f32_16x16x32_bf16 v[42:45], v[164:167], v[230:233], v[42:45]
	v_mfma_f32_16x16x32_bf16 v[42:45], v[168:171], v[234:237], v[42:45]
	v_mfma_f32_16x16x32_bf16 v[46:49], v[160:163], v[234:237], v[46:49]
	v_mfma_f32_16x16x32_bf16 v[46:49], v[156:159], v[230:233], v[46:49]
	v_mfma_f32_16x16x32_bf16 v[30:33], v[156:159], v[238:241], v[30:33]
	v_mfma_f32_16x16x32_bf16 v[30:33], v[160:163], v[242:245], v[30:33]
	v_mfma_f32_16x16x32_bf16 v[26:29], v[168:171], v[242:245], v[26:29]
	v_mfma_f32_16x16x32_bf16 v[26:29], v[164:167], v[238:241], v[26:29]
	v_mfma_f32_16x16x32_bf16 v[22:25], v[174:177], v[238:241], v[22:25]
	v_mfma_f32_16x16x32_bf16 v[22:25], v[178:181], v[242:245], v[22:25]
	v_mfma_f32_16x16x32_bf16 v[18:21], v[186:189], v[242:245], v[18:21]
	v_mfma_f32_16x16x32_bf16 v[18:21], v[182:185], v[238:241], v[18:21]
	v_mfma_f32_16x16x32_bf16 v[2:5], v[182:185], v[246:249], v[2:5]
	v_mfma_f32_16x16x32_bf16 v[2:5], v[186:189], v[250:253], v[2:5]
	v_mfma_f32_16x16x32_bf16 v[6:9], v[178:181], v[250:253], v[6:9]
	v_mfma_f32_16x16x32_bf16 v[6:9], v[174:177], v[246:249], v[6:9]
	v_mfma_f32_16x16x32_bf16 v[10:13], v[164:167], v[246:249], v[10:13]
	v_mfma_f32_16x16x32_bf16 v[10:13], v[168:171], v[250:253], v[10:13]
	v_mfma_f32_16x16x32_bf16 v[14:17], v[160:163], v[250:253], v[14:17]
	v_mfma_f32_16x16x32_bf16 v[14:17], v[156:159], v[246:249], v[14:17]
	s_waitcnt vmcnt(0)
	s_barrier
	s_add_i32 s49, s49, 1
	s_cmp_lt_u32 s49, 16
	s_cbranch_scc1 .Lp8k_A_loop
	ds_read_b128 v[190:193], v155 offset:0
	ds_read_b128 v[194:197], v155 offset:1024
	s_add_i32 m0, s2, 0x18000
	s_nop 0
	global_load_lds_dwordx4 v134, s[28:29]
	ds_read_b128 v[198:201], v155 offset:2048
	ds_read_b128 v[202:205], v155 offset:3072
	s_add_i32 m0, s2, 0x1a000
	s_nop 0
	global_load_lds_dwordx4 v130, s[28:29]
	ds_read_b128 v[206:209], v155 offset:4096
	ds_read_b128 v[210:213], v155 offset:5120
	s_add_u32 s30, s28, 0x20000
	s_addc_u32 s31, s29, 0
	s_add_i32 m0, s2, 0x19000
	s_nop 0
	global_load_lds_dwordx4 v134, s[30:31]
	ds_read_b128 v[214:217], v155 offset:6144
	ds_read_b128 v[218:221], v155 offset:7168
	s_add_i32 m0, s2, 0x1b000
	s_nop 0
	global_load_lds_dwordx4 v130, s[30:31]
	ds_read_b128 v[164:167], v153 offset:2048
	ds_read_b128 v[168:171], v153 offset:3072
	s_add_u32 s30, s28, 0x80000
	s_addc_u32 s31, s29, 0
	s_add_i32 m0, s2, 0x1c000
	s_nop 0
	global_load_lds_dwordx4 v134, s[30:31]
	ds_read_b128 v[174:177], v153 offset:16384
	ds_read_b128 v[178:181], v153 offset:17408
	s_add_i32 m0, s2, 0x1e000
	s_nop 0
	global_load_lds_dwordx4 v130, s[30:31]
	ds_read_b128 v[182:185], v153 offset:18432
	ds_read_b128 v[186:189], v153 offset:19456
	s_add_u32 s30, s28, 0xa0000
	s_addc_u32 s31, s29, 0
	s_add_i32 m0, s2, 0x1d000
	s_nop 0
	global_load_lds_dwordx4 v134, s[30:31]
	ds_read_b128 v[222:225], v155 offset:16384
	ds_read_b128 v[226:229], v155 offset:17408
	s_add_i32 m0, s2, 0x1f000
	s_nop 0
	global_load_lds_dwordx4 v130, s[30:31]
	ds_read_b128 v[230:233], v155 offset:18432
	ds_read_b128 v[234:237], v155 offset:19456
	ds_read_b128 v[238:241], v155 offset:20480
	ds_read_b128 v[242:245], v155 offset:21504
	ds_read_b128 v[246:249], v155 offset:22528
	ds_read_b128 v[250:253], v155 offset:23552
	s_add_u32 s28, s28, 0x80
	s_addc_u32 s29, s29, 0
	s_branch .Lp8k_done

; #define PG8_STAGE(bufoff, gbase, voff) do { _Pragma("unroll") for (int _i = 0; _i < 2; ++_i) \
;         __builtin_amdgcn_global_load_lds((const unsigned*)((const char*)(gbase) + (voff)[_i]), (PG8_LAS unsigned*)(lds + (bufoff) + ldsw + _i * 8192), 16, 0, 0); } while (0)
; #define PG8_LDA(dst, b, h) do { _Pragma("unroll") for (int m = 0; m < 4; ++m) _Pragma("unroll") for (int k = 0; k < 2; ++k) dst[m][k] = *(const PG8_LAS bf16x8*)(lds + PG8_SA(b, h) + aoff + m * 2048 + k * 1024); } while (0)
; #define PG8_LDB(dst, b, h) do { _Pragma("unroll") for (int n = 0; n < 2; ++n) _Pragma("unroll") for (int k = 0; k < 2; ++k) dst[n][k] = *(const PG8_LAS bf16x8*)(lds + PG8_SB(b, h) + boff + n * 2048 + k * 1024); } while (0)
; #define PG8_MMA(ai, bj, At, Bt) do { __builtin_amdgcn_s_setprio(1); _Pragma("unroll") for (int m = 0; m < 4; ++m) _Pragma("unroll") for (int n = 0; n < 2; ++n) _Pragma("unroll") for (int k = 0; k < 2; ++k) \
;         acc[ai][bj][m][n] = __builtin_amdgcn_mfma_f32_16x16x32_bf16(Bt[n][k], At[m][k], acc[ai][bj][m][n], 0, 0, 0); __builtin_amdgcn_s_setprio(0); } while (0)
; #define PG8_WAIT_V(n) asm volatile("s_waitcnt vmcnt(" #n ")" ::: "memory")
; template <class Epi, class Sched, bool ALIGN_EPI>
; __device__ __forceinline__ void gemm_phase(PG8_LAS unsigned char* lds, const Gemm g, const Sched& S, const Epi& E) {
;     ...
;             PG8_LDB(B0, 0, 0); PG8_LDB(B1, 0, 1); PG8_SCHED; PG8_LDA(At, 0, 0); PG8_STAGE(PG8_SA(1, 1), a1 + hstepA, voffA);
;             PG8_WAIT_V(8); PG8_WAIT_L(0); PG8_BAR; PG8_MMA(0, 0, At, B0); PG8_MMA(0, 1, At, B1); PG8_BAR; PG8_SCHED;
;             PG8_LDA(At, 0, 1); PG8_STAGE(PG8_SB(0, 0), b2, voffB); PG8_STAGE(PG8_SB(0, 1), b2 + hstepB, voffB); PG8_STAGE(PG8_SA(0, 0), a2, voffA);
;             PG8_WAIT_V(8); PG8_WAIT_L(0); PG8_BAR; PG8_MMA(1, 0, At, B0); PG8_MMA(1, 1, At, B1); PG8_BAR; PG8_SCHED;
;             PG8_LDB(B0, 1, 0); PG8_LDB(B1, 1, 1); PG8_SCHED; PG8_LDA(At, 1, 0); PG8_STAGE(PG8_SA(0, 1), a2 + hstepA, voffA);
;             PG8_WAIT_V(8); PG8_WAIT_L(0); PG8_BAR; PG8_MMA(0, 0, At, B0); PG8_MMA(0, 1, At, B1); PG8_BAR; PG8_SCHED;
;             PG8_LDA(At, 1, 1); PG8_STAGE(PG8_SB(1, 0), b3, voffB); PG8_STAGE(PG8_SB(1, 1), b3 + hstepB, voffB); PG8_STAGE(PG8_SA(1, 0), a3, voffA);
;             PG8_WAIT_V(8); PG8_WAIT_L(0); PG8_BAR; PG8_MMA(1, 0, At, B0); PG8_MMA(1, 1, At, B1); PG8_BAR; PG8_SCHED;
.Lp8k_B_nobar:
	ds_read_b128 v[190:193], v155 offset:0
	ds_read_b128 v[194:197], v155 offset:1024
	s_add_i32 m0, s2, 0xa000
	s_nop 0
	global_load_lds_dwordx4 v132, s[28:29]
	ds_read_b128 v[198:201], v155 offset:2048
	ds_read_b128 v[202:205], v155 offset:3072
	s_add_u32 s30, s28, 0x20000
	s_addc_u32 s31, s29, 0
	s_add_i32 m0, s2, 0xb000
	s_nop 0
	global_load_lds_dwordx4 v132, s[30:31]
	ds_read_b128 v[206:209], v155 offset:4096
	ds_read_b128 v[210:213], v155 offset:5120
	s_add_u32 s30, s28, 0x80000
	s_addc_u32 s31, s29, 0
	s_add_i32 m0, s2, 0xe000
	s_nop 0
	global_load_lds_dwordx4 v132, s[30:31]
	ds_read_b128 v[214:217], v155 offset:6144
	ds_read_b128 v[218:221], v155 offset:7168
	s_add_u32 s30, s28, 0xa0000
	s_addc_u32 s31, s29, 0
	s_add_i32 m0, s2, 0xf000
	s_nop 0
	global_load_lds_dwordx4 v132, s[30:31]
	ds_read_b128 v[156:159], v153 offset:0
	ds_read_b128 v[160:163], v153 offset:1024
	s_add_u32 s34, s28, 0x80
	s_addc_u32 s35, s29, 0
	s_cmp_eq_u32 s49, 15
	s_cselect_b32 s34, s50, s34
	s_cselect_b32 s35, s51, s35
	s_add_i32 m0, s2, 0x0
	s_nop 0
	global_load_lds_dwordx4 v136, s[34:35]
	ds_read_b128 v[164:167], v153 offset:2048
	ds_read_b128 v[168:171], v153 offset:3072
	s_add_u32 s30, s34, 0x20000
	s_addc_u32 s31, s35, 0
	s_add_i32 m0, s2, 0x1000
	s_nop 0
	global_load_lds_dwordx4 v136, s[30:31]
	ds_read_b128 v[174:177], v153 offset:16384
	ds_read_b128 v[178:181], v153 offset:17408
	s_add_u32 s30, s34, 0x80000
	s_addc_u32 s31, s35, 0
	s_add_i32 m0, s2, 0x4000
	s_nop 0
	global_load_lds_dwordx4 v136, s[30:31]
	ds_read_b128 v[182:185], v153 offset:18432
	ds_read_b128 v[186:189], v153 offset:19456
	s_add_u32 s30, s34, 0xa0000
	s_addc_u32 s31, s35, 0
	s_add_i32 m0, s2, 0x5000
	s_nop 0
	global_load_lds_dwordx4 v136, s[30:31]
	ds_read_b128 v[222:225], v155 offset:16384
	ds_read_b128 v[226:229], v155 offset:17408
	ds_read_b128 v[230:233], v155 offset:18432
	ds_read_b128 v[234:237], v155 offset:19456
	ds_read_b128 v[238:241], v155 offset:20480
	ds_read_b128 v[242:245], v155 offset:21504
	ds_read_b128 v[246:249], v155 offset:22528
	ds_read_b128 v[250:253], v155 offset:23552
	s_add_u32 s28, s28, 0x80
	s_addc_u32 s29, s29, 0
	s_waitcnt vmcnt(8) lgkmcnt(0)
	s_barrier
	v_mfma_f32_16x16x32_bf16 v[126:129], v[156:159], v[190:193], 0
	v_mfma_f32_16x16x32_bf16 v[126:129], v[160:163], v[194:197], v[126:129]
	v_mfma_f32_16x16x32_bf16 v[122:125], v[168:171], v[194:197], 0
	v_mfma_f32_16x16x32_bf16 v[122:125], v[164:167], v[190:193], v[122:125]
	v_mfma_f32_16x16x32_bf16 v[118:121], v[174:177], v[190:193], 0
	v_mfma_f32_16x16x32_bf16 v[118:121], v[178:181], v[194:197], v[118:121]
	v_mfma_f32_16x16x32_bf16 v[114:117], v[186:189], v[194:197], 0
	v_mfma_f32_16x16x32_bf16 v[114:117], v[182:185], v[190:193], v[114:117]
	v_mfma_f32_16x16x32_bf16 v[98:101], v[182:185], v[198:201], 0
	v_mfma_f32_16x16x32_bf16 v[98:101], v[186:189], v[202:205], v[98:101]
	v_mfma_f32_16x16x32_bf16 v[102:105], v[178:181], v[202:205], 0
	v_mfma_f32_16x16x32_bf16 v[102:105], v[174:177], v[198:201], v[102:105]
	v_mfma_f32_16x16x32_bf16 v[106:109], v[164:167], v[198:201], 0
	v_mfma_f32_16x16x32_bf16 v[106:109], v[168:171], v[202:205], v[106:109]
	v_mfma_f32_16x16x32_bf16 v[110:113], v[160:163], v[202:205], 0
	v_mfma_f32_16x16x32_bf16 v[110:113], v[156:159], v[198:201], v[110:113]
	v_mfma_f32_16x16x32_bf16 v[94:97], v[156:159], v[206:209], 0
	v_mfma_f32_16x16x32_bf16 v[94:97], v[160:163], v[210:213], v[94:97]
	v_mfma_f32_16x16x32_bf16 v[90:93], v[168:171], v[210:213], 0
	v_mfma_f32_16x16x32_bf16 v[90:93], v[164:167], v[206:209], v[90:93]
	v_mfma_f32_16x16x32_bf16 v[86:89], v[174:177], v[206:209], 0
	v_mfma_f32_16x16x32_bf16 v[86:89], v[178:181], v[210:213], v[86:89]
	v_mfma_f32_16x16x32_bf16 v[82:85], v[186:189], v[210:213], 0
	v_mfma_f32_16x16x32_bf16 v[82:85], v[182:185], v[206:209], v[82:85]
	v_mfma_f32_16x16x32_bf16 v[66:69], v[182:185], v[214:217], 0
	v_mfma_f32_16x16x32_bf16 v[66:69], v[186:189], v[218:221], v[66:69]
	v_mfma_f32_16x16x32_bf16 v[70:73], v[178:181], v[218:221], 0
	v_mfma_f32_16x16x32_bf16 v[70:73], v[174:177], v[214:217], v[70:73]
	v_mfma_f32_16x16x32_bf16 v[74:77], v[164:167], v[214:217], 0
	v_mfma_f32_16x16x32_bf16 v[74:77], v[168:171], v[218:221], v[74:77]
	v_mfma_f32_16x16x32_bf16 v[78:81], v[160:163], v[218:221], 0
	v_mfma_f32_16x16x32_bf16 v[78:81], v[156:159], v[214:217], v[78:81]
	v_mfma_f32_16x16x32_bf16 v[62:65], v[156:159], v[222:225], 0
	v_mfma_f32_16x16x32_bf16 v[62:65], v[160:163], v[226:229], v[62:65]
	v_mfma_f32_16x16x32_bf16 v[58:61], v[168:171], v[226:229], 0
	v_mfma_f32_16x16x32_bf16 v[58:61], v[164:167], v[222:225], v[58:61]
	v_mfma_f32_16x16x32_bf16 v[54:57], v[174:177], v[222:225], 0
	v_mfma_f32_16x16x32_bf16 v[54:57], v[178:181], v[226:229], v[54:57]
	v_mfma_f32_16x16x32_bf16 v[50:53], v[186:189], v[226:229], 0
	v_mfma_f32_16x16x32_bf16 v[50:53], v[182:185], v[222:225], v[50:53]
	v_mfma_f32_16x16x32_bf16 v[34:37], v[182:185], v[230:233], 0
	v_mfma_f32_16x16x32_bf16 v[34:37], v[186:189], v[234:237], v[34:37]
	v_mfma_f32_16x16x32_bf16 v[38:41], v[178:181], v[234:237], 0
	v_mfma_f32_16x16x32_bf16 v[38:41], v[174:177], v[230:233], v[38:41]
	v_mfma_f32_16x16x32_bf16 v[42:45], v[164:167], v[230:233], 0
	v_mfma_f32_16x16x32_bf16 v[42:45], v[168:171], v[234:237], v[42:45]
	v_mfma_f32_16x16x32_bf16 v[46:49], v[160:163], v[234:237], 0
	v_mfma_f32_16x16x32_bf16 v[46:49], v[156:159], v[230:233], v[46:49]
	v_mfma_f32_16x16x32_bf16 v[30:33], v[156:159], v[238:241], 0
	v_mfma_f32_16x16x32_bf16 v[30:33], v[160:163], v[242:245], v[30:33]
	v_mfma_f32_16x16x32_bf16 v[26:29], v[168:171], v[242:245], 0
	v_mfma_f32_16x16x32_bf16 v[26:29], v[164:167], v[238:241], v[26:29]
	v_mfma_f32_16x16x32_bf16 v[22:25], v[174:177], v[238:241], 0
	v_mfma_f32_16x16x32_bf16 v[22:25], v[178:181], v[242:245], v[22:25]
	v_mfma_f32_16x16x32_bf16 v[18:21], v[186:189], v[242:245], 0
	v_mfma_f32_16x16x32_bf16 v[18:21], v[182:185], v[238:241], v[18:21]
	v_mfma_f32_16x16x32_bf16 v[2:5], v[182:185], v[246:249], 0
	v_mfma_f32_16x16x32_bf16 v[2:5], v[186:189], v[250:253], v[2:5]
	v_mfma_f32_16x16x32_bf16 v[6:9], v[178:181], v[250:253], 0
	v_mfma_f32_16x16x32_bf16 v[6:9], v[174:177], v[246:249], v[6:9]
	v_mfma_f32_16x16x32_bf16 v[10:13], v[164:167], v[246:249], 0
	v_mfma_f32_16x16x32_bf16 v[10:13], v[168:171], v[250:253], v[10:13]
	v_mfma_f32_16x16x32_bf16 v[14:17], v[160:163], v[250:253], 0
	v_mfma_f32_16x16x32_bf16 v[14:17], v[156:159], v[246:249], v[14:17]
	s_waitcnt vmcnt(0)
	s_barrier
; #define PG8_STAGE(bufoff, gbase, voff) do { _Pragma("unroll") for (int _i = 0; _i < 2; ++_i) \
;         __builtin_amdgcn_global_load_lds((const unsigned*)((const char*)(gbase) + (voff)[_i]), (PG8_LAS unsigned*)(lds + (bufoff) + ldsw + _i * 8192), 16, 0, 0); } while (0)
; #define PG8_LDA(dst, b, h) do { _Pragma("unroll") for (int m = 0; m < 4; ++m) _Pragma("unroll") for (int k = 0; k < 2; ++k) dst[m][k] = *(const PG8_LAS bf16x8*)(lds + PG8_SA(b, h) + aoff + m * 2048 + k * 1024); } while (0)
; #define PG8_LDB(dst, b, h) do { _Pragma("unroll") for (int n = 0; n < 2; ++n) _Pragma("unroll") for (int k = 0; k < 2; ++k) dst[n][k] = *(const PG8_LAS bf16x8*)(lds + PG8_SB(b, h) + boff + n * 2048 + k * 1024); } while (0)
; #define PG8_MMA(ai, bj, At, Bt) do { __builtin_amdgcn_s_setprio(1); _Pragma("unroll") for (int m = 0; m < 4; ++m) _Pragma("unroll") for (int n = 0; n < 2; ++n) _Pragma("unroll") for (int k = 0; k < 2; ++k) \
;         acc[ai][bj][m][n] = __builtin_amdgcn_mfma_f32_16x16x32_bf16(Bt[n][k], At[m][k], acc[ai][bj][m][n], 0, 0, 0); __builtin_amdgcn_s_setprio(0); } while (0)
; #define PG8_WAIT_V(n) asm volatile("s_waitcnt vmcnt(" #n ")" ::: "memory")
; template <class Epi, class Sched, bool ALIGN_EPI>
; __device__ __forceinline__ void gemm_phase(PG8_LAS unsigned char* lds, const Gemm g, const Sched& S, const Epi& E) {
;     ...
;             PG8_LDB(B0, 0, 0); PG8_LDB(B1, 0, 1); PG8_SCHED; PG8_LDA(At, 0, 0); PG8_STAGE(PG8_SA(1, 1), a1 + hstepA, voffA);
;             PG8_WAIT_V(8); PG8_WAIT_L(0); PG8_BAR; PG8_MMA(0, 0, At, B0); PG8_MMA(0, 1, At, B1); PG8_BAR; PG8_SCHED;
;             PG8_LDA(At, 0, 1); PG8_STAGE(PG8_SB(0, 0), b2, voffB); PG8_STAGE(PG8_SB(0, 1), b2 + hstepB, voffB); PG8_STAGE(PG8_SA(0, 0), a2, voffA);
;             PG8_WAIT_V(8); PG8_WAIT_L(0); PG8_BAR; PG8_MMA(1, 0, At, B0); PG8_MMA(1, 1, At, B1); PG8_BAR; PG8_SCHED;
;             PG8_LDB(B0, 1, 0); PG8_LDB(B1, 1, 1); PG8_SCHED; PG8_LDA(At, 1, 0); PG8_STAGE(PG8_SA(0, 1), a2 + hstepA, voffA);
;             PG8_WAIT_V(8); PG8_WAIT_L(0); PG8_BAR; PG8_MMA(0, 0, At, B0); PG8_MMA(0, 1, At, B1); PG8_BAR; PG8_SCHED;
;             PG8_LDA(At, 1, 1); PG8_STAGE(PG8_SB(1, 0), b3, voffB); PG8_STAGE(PG8_SB(1, 1), b3 + hstepB, voffB); PG8_STAGE(PG8_SA(1, 0), a3, voffA);
;             PG8_WAIT_V(8); PG8_WAIT_L(0); PG8_BAR; PG8_MMA(1, 0, At, B0); PG8_MMA(1, 1, At, B1); PG8_BAR; PG8_SCHED;
	ds_read_b128 v[190:193], v155 offset:32768
	ds_read_b128 v[194:197], v155 offset:33792
	s_cmp_eq_u32 s49, 15
	s_cselect_b32 s28, s50, s28
	s_cselect_b32 s29, s51, s29
	s_add_i32 m0, s2, 0x2000
	s_nop 0
	global_load_lds_dwordx4 v132, s[28:29]
	ds_read_b128 v[198:201], v155 offset:34816
	ds_read_b128 v[202:205], v155 offset:35840
	s_add_u32 s30, s28, 0x20000
	s_addc_u32 s31, s29, 0
	s_add_i32 m0, s2, 0x3000
	s_nop 0
	global_load_lds_dwordx4 v132, s[30:31]
	ds_read_b128 v[206:209], v155 offset:36864
	ds_read_b128 v[210:213], v155 offset:37888
	s_add_u32 s30, s28, 0x80000
	s_addc_u32 s31, s29, 0
	s_add_i32 m0, s2, 0x6000
	s_nop 0
	global_load_lds_dwordx4 v132, s[30:31]
	ds_read_b128 v[214:217], v155 offset:38912
	ds_read_b128 v[218:221], v155 offset:39936
	s_add_u32 s30, s28, 0xa0000
	s_addc_u32 s31, s29, 0
	s_add_i32 m0, s2, 0x7000
	s_nop 0
	global_load_lds_dwordx4 v132, s[30:31]
	ds_read_b128 v[156:159], v153 offset:32768
	ds_read_b128 v[160:163], v153 offset:33792
	s_add_u32 s34, s28, 0x80
	s_addc_u32 s35, s29, 0
	s_add_i32 m0, s2, 0x8000
	s_nop 0
	global_load_lds_dwordx4 v136, s[34:35]
	ds_read_b128 v[164:167], v153 offset:34816
	ds_read_b128 v[168:171], v153 offset:35840
	s_add_u32 s30, s34, 0x20000
	s_addc_u32 s31, s35, 0
	s_add_i32 m0, s2, 0x9000
	s_nop 0
	global_load_lds_dwordx4 v136, s[30:31]
	ds_read_b128 v[174:177], v153 offset:49152
	ds_read_b128 v[178:181], v153 offset:50176
	s_add_u32 s30, s34, 0x80000
	s_addc_u32 s31, s35, 0
	s_add_i32 m0, s2, 0xc000
	s_nop 0
	global_load_lds_dwordx4 v136, s[30:31]
	ds_read_b128 v[182:185], v153 offset:51200
	ds_read_b128 v[186:189], v153 offset:52224
	s_add_u32 s30, s34, 0xa0000
	s_addc_u32 s31, s35, 0
	s_add_i32 m0, s2, 0xd000
	s_nop 0
	global_load_lds_dwordx4 v136, s[30:31]
	ds_read_b128 v[222:225], v155 offset:49152
	ds_read_b128 v[226:229], v155 offset:50176
	ds_read_b128 v[230:233], v155 offset:51200
	ds_read_b128 v[234:237], v155 offset:52224
	ds_read_b128 v[238:241], v155 offset:53248
	ds_read_b128 v[242:245], v155 offset:54272
	ds_read_b128 v[246:249], v155 offset:55296
	ds_read_b128 v[250:253], v155 offset:56320
	s_add_u32 s28, s28, 0x80
	s_addc_u32 s29, s29, 0
	s_waitcnt vmcnt(8) lgkmcnt(0)
	s_barrier
	v_mfma_f32_16x16x32_bf16 v[126:129], v[156:159], v[190:193], v[126:129]
	v_mfma_f32_16x16x32_bf16 v[126:129], v[160:163], v[194:197], v[126:129]
	v_mfma_f32_16x16x32_bf16 v[122:125], v[168:171], v[194:197], v[122:125]
	v_mfma_f32_16x16x32_bf16 v[122:125], v[164:167], v[190:193], v[122:125]
	v_mfma_f32_16x16x32_bf16 v[118:121], v[174:177], v[190:193], v[118:121]
	v_mfma_f32_16x16x32_bf16 v[118:121], v[178:181], v[194:197], v[118:121]
	v_mfma_f32_16x16x32_bf16 v[114:117], v[186:189], v[194:197], v[114:117]
	v_mfma_f32_16x16x32_bf16 v[114:117], v[182:185], v[190:193], v[114:117]
	v_mfma_f32_16x16x32_bf16 v[98:101], v[182:185], v[198:201], v[98:101]
	v_mfma_f32_16x16x32_bf16 v[98:101], v[186:189], v[202:205], v[98:101]
	v_mfma_f32_16x16x32_bf16 v[102:105], v[178:181], v[202:205], v[102:105]
	v_mfma_f32_16x16x32_bf16 v[102:105], v[174:177], v[198:201], v[102:105]
	v_mfma_f32_16x16x32_bf16 v[106:109], v[164:167], v[198:201], v[106:109]
	v_mfma_f32_16x16x32_bf16 v[106:109], v[168:171], v[202:205], v[106:109]
	v_mfma_f32_16x16x32_bf16 v[110:113], v[160:163], v[202:205], v[110:113]
	v_mfma_f32_16x16x32_bf16 v[110:113], v[156:159], v[198:201], v[110:113]
	v_mfma_f32_16x16x32_bf16 v[94:97], v[156:159], v[206:209], v[94:97]
	v_mfma_f32_16x16x32_bf16 v[94:97], v[160:163], v[210:213], v[94:97]
	v_mfma_f32_16x16x32_bf16 v[90:93], v[168:171], v[210:213], v[90:93]
	v_mfma_f32_16x16x32_bf16 v[90:93], v[164:167], v[206:209], v[90:93]
	v_mfma_f32_16x16x32_bf16 v[86:89], v[174:177], v[206:209], v[86:89]
	v_mfma_f32_16x16x32_bf16 v[86:89], v[178:181], v[210:213], v[86:89]
	v_mfma_f32_16x16x32_bf16 v[82:85], v[186:189], v[210:213], v[82:85]
	v_mfma_f32_16x16x32_bf16 v[82:85], v[182:185], v[206:209], v[82:85]
	v_mfma_f32_16x16x32_bf16 v[66:69], v[182:185], v[214:217], v[66:69]
	v_mfma_f32_16x16x32_bf16 v[66:69], v[186:189], v[218:221], v[66:69]
	v_mfma_f32_16x16x32_bf16 v[70:73], v[178:181], v[218:221], v[70:73]
	v_mfma_f32_16x16x32_bf16 v[70:73], v[174:177], v[214:217], v[70:73]
	v_mfma_f32_16x16x32_bf16 v[74:77], v[164:167], v[214:217], v[74:77]
	v_mfma_f32_16x16x32_bf16 v[74:77], v[168:171], v[218:221], v[74:77]
	v_mfma_f32_16x16x32_bf16 v[78:81], v[160:163], v[218:221], v[78:81]
	v_mfma_f32_16x16x32_bf16 v[78:81], v[156:159], v[214:217], v[78:81]
	v_mfma_f32_16x16x32_bf16 v[62:65], v[156:159], v[222:225], v[62:65]
	v_mfma_f32_16x16x32_bf16 v[62:65], v[160:163], v[226:229], v[62:65]
	v_mfma_f32_16x16x32_bf16 v[58:61], v[168:171], v[226:229], v[58:61]
	v_mfma_f32_16x16x32_bf16 v[58:61], v[164:167], v[222:225], v[58:61]
	v_mfma_f32_16x16x32_bf16 v[54:57], v[174:177], v[222:225], v[54:57]
	v_mfma_f32_16x16x32_bf16 v[54:57], v[178:181], v[226:229], v[54:57]
	v_mfma_f32_16x16x32_bf16 v[50:53], v[186:189], v[226:229], v[50:53]
	v_mfma_f32_16x16x32_bf16 v[50:53], v[182:185], v[222:225], v[50:53]
	v_mfma_f32_16x16x32_bf16 v[34:37], v[182:185], v[230:233], v[34:37]
	v_mfma_f32_16x16x32_bf16 v[34:37], v[186:189], v[234:237], v[34:37]
	v_mfma_f32_16x16x32_bf16 v[38:41], v[178:181], v[234:237], v[38:41]
	v_mfma_f32_16x16x32_bf16 v[38:41], v[174:177], v[230:233], v[38:41]
	v_mfma_f32_16x16x32_bf16 v[42:45], v[164:167], v[230:233], v[42:45]
	v_mfma_f32_16x16x32_bf16 v[42:45], v[168:171], v[234:237], v[42:45]
	v_mfma_f32_16x16x32_bf16 v[46:49], v[160:163], v[234:237], v[46:49]
	v_mfma_f32_16x16x32_bf16 v[46:49], v[156:159], v[230:233], v[46:49]
	v_mfma_f32_16x16x32_bf16 v[30:33], v[156:159], v[238:241], v[30:33]
	v_mfma_f32_16x16x32_bf16 v[30:33], v[160:163], v[242:245], v[30:33]
	v_mfma_f32_16x16x32_bf16 v[26:29], v[168:171], v[242:245], v[26:29]
	v_mfma_f32_16x16x32_bf16 v[26:29], v[164:167], v[238:241], v[26:29]
	v_mfma_f32_16x16x32_bf16 v[22:25], v[174:177], v[238:241], v[22:25]
	v_mfma_f32_16x16x32_bf16 v[22:25], v[178:181], v[242:245], v[22:25]
	v_mfma_f32_16x16x32_bf16 v[18:21], v[186:189], v[242:245], v[18:21]
	v_mfma_f32_16x16x32_bf16 v[18:21], v[182:185], v[238:241], v[18:21]
	v_mfma_f32_16x16x32_bf16 v[2:5], v[182:185], v[246:249], v[2:5]
	v_mfma_f32_16x16x32_bf16 v[2:5], v[186:189], v[250:253], v[2:5]
	v_mfma_f32_16x16x32_bf16 v[6:9], v[178:181], v[250:253], v[6:9]
	v_mfma_f32_16x16x32_bf16 v[6:9], v[174:177], v[246:249], v[6:9]
	v_mfma_f32_16x16x32_bf16 v[10:13], v[164:167], v[246:249], v[10:13]
	v_mfma_f32_16x16x32_bf16 v[10:13], v[168:171], v[250:253], v[10:13]
	v_mfma_f32_16x16x32_bf16 v[14:17], v[160:163], v[250:253], v[14:17]
	v_mfma_f32_16x16x32_bf16 v[14:17], v[156:159], v[246:249], v[14:17]
	s_waitcnt vmcnt(0)
	s_barrier
	s_add_i32 s49, s49, 1
; #define PG8_STAGE(bufoff, gbase, voff) do { _Pragma("unroll") for (int _i = 0; _i < 2; ++_i) \
;         __builtin_amdgcn_global_load_lds((const unsigned*)((const char*)(gbase) + (voff)[_i]), (PG8_LAS unsigned*)(lds + (bufoff) + ldsw + _i * 8192), 16, 0, 0); } while (0)
; #define PG8_LDA(dst, b, h) do { _Pragma("unroll") for (int m = 0; m < 4; ++m) _Pragma("unroll") for (int k = 0; k < 2; ++k) dst[m][k] = *(const PG8_LAS bf16x8*)(lds + PG8_SA(b, h) + aoff + m * 2048 + k * 1024); } while (0)
; #define PG8_LDB(dst, b, h) do { _Pragma("unroll") for (int n = 0; n < 2; ++n) _Pragma("unroll") for (int k = 0; k < 2; ++k) dst[n][k] = *(const PG8_LAS bf16x8*)(lds + PG8_SB(b, h) + boff + n * 2048 + k * 1024); } while (0)
; template <class Epi, class Sched, bool ALIGN_EPI>
; __device__ __forceinline__ void gemm_phase(PG8_LAS unsigned char* lds, const Gemm g, const Sched& S, const Epi& E) {
;     ...
;         for (int t = 0; t < nt; t += 2) {
;             if constexpr (Epi::MIDK) { if (t == (nt >> 1)) E.midk(acc, cur, wr, fr); }
;             const bool last = (t == nt - 2);
;             const char* a1 = cA + (size_t)(t + 1) * kstepA;
;             const char* a2 = last ? nA : cA + (size_t)(t + 2) * kstepA; const char* b2 = last ? nB : cB + (size_t)(t + 2) * kstep;
;             const char* a3 = a2 + kstepA; const char* b3 = b2 + kstep;
;             PG8_LDB(B0, 0, 0); PG8_LDB(B1, 0, 1); PG8_SCHED; PG8_LDA(At, 0, 0); PG8_STAGE(PG8_SA(1, 1), a1 + hstepA, voffA);
;             PG8_WAIT_V(8); PG8_WAIT_L(0); PG8_BAR; PG8_MMA(0, 0, At, B0); PG8_MMA(0, 1, At, B1); PG8_BAR; PG8_SCHED;
;             PG8_LDA(At, 0, 1); PG8_STAGE(PG8_SB(0, 0), b2, voffB); PG8_STAGE(PG8_SB(0, 1), b2 + hstepB, voffB); PG8_STAGE(PG8_SA(0, 0), a2, voffA);
;             PG8_WAIT_V(8); PG8_WAIT_L(0); PG8_BAR; PG8_MMA(1, 0, At, B0); PG8_MMA(1, 1, At, B1); PG8_BAR; PG8_SCHED;
;             PG8_LDB(B0, 1, 0); PG8_LDB(B1, 1, 1); PG8_SCHED; PG8_LDA(At, 1, 0); PG8_STAGE(PG8_SA(0, 1), a2 + hstepA, voffA);
;             PG8_WAIT_V(8); PG8_WAIT_L(0); PG8_BAR; PG8_MMA(0, 0, At, B0); PG8_MMA(0, 1, At, B1); PG8_BAR; PG8_SCHED;
;             PG8_LDA(At, 1, 1); PG8_STAGE(PG8_SB(1, 0), b3, voffB); PG8_STAGE(PG8_SB(1, 1), b3 + hstepB, voffB); PG8_STAGE(PG8_SA(1, 0), a3, voffA);
;             PG8_WAIT_V(8); PG8_WAIT_L(0); PG8_BAR; PG8_MMA(1, 0, At, B0); PG8_MMA(1, 1, At, B1); PG8_BAR; PG8_SCHED;
.Lp8k_B_loop:
	ds_read_b128 v[190:193], v155 offset:0
	ds_read_b128 v[194:197], v155 offset:1024
	s_add_i32 m0, s2, 0xa000
	s_nop 0
	global_load_lds_dwordx4 v132, s[28:29]
	ds_read_b128 v[198:201], v155 offset:2048
	ds_read_b128 v[202:205], v155 offset:3072
	s_add_u32 s30, s28, 0x20000
	s_addc_u32 s31, s29, 0
	s_add_i32 m0, s2, 0xb000
	s_nop 0
	global_load_lds_dwordx4 v132, s[30:31]
	ds_read_b128 v[206:209], v155 offset:4096
	ds_read_b128 v[210:213], v155 offset:5120
	s_add_u32 s30, s28, 0x80000
	s_addc_u32 s31, s29, 0
	s_add_i32 m0, s2, 0xe000
	s_nop 0
	global_load_lds_dwordx4 v132, s[30:31]
	ds_read_b128 v[214:217], v155 offset:6144
	ds_read_b128 v[218:221], v155 offset:7168
	s_add_u32 s30, s28, 0xa0000
	s_addc_u32 s31, s29, 0
	s_add_i32 m0, s2, 0xf000
	s_nop 0
	global_load_lds_dwordx4 v132, s[30:31]
	ds_read_b128 v[156:159], v153 offset:0
	ds_read_b128 v[160:163], v153 offset:1024
	s_add_u32 s34, s28, 0x80
	s_addc_u32 s35, s29, 0
	s_cmp_eq_u32 s49, 15
	s_cselect_b32 s34, s50, s34
	s_cselect_b32 s35, s51, s35
	s_add_i32 m0, s2, 0x0
	s_nop 0
	global_load_lds_dwordx4 v136, s[34:35]
	ds_read_b128 v[164:167], v153 offset:2048
	ds_read_b128 v[168:171], v153 offset:3072
	s_add_u32 s30, s34, 0x20000
	s_addc_u32 s31, s35, 0
	s_add_i32 m0, s2, 0x1000
	s_nop 0
	global_load_lds_dwordx4 v136, s[30:31]
	ds_read_b128 v[174:177], v153 offset:16384
	ds_read_b128 v[178:181], v153 offset:17408
	s_add_u32 s30, s34, 0x80000
	s_addc_u32 s31, s35, 0
	s_add_i32 m0, s2, 0x4000
	s_nop 0
	global_load_lds_dwordx4 v136, s[30:31]
	ds_read_b128 v[182:185], v153 offset:18432
	ds_read_b128 v[186:189], v153 offset:19456
	s_add_u32 s30, s34, 0xa0000
	s_addc_u32 s31, s35, 0
	s_add_i32 m0, s2, 0x5000
	s_nop 0
	global_load_lds_dwordx4 v136, s[30:31]
	ds_read_b128 v[222:225], v155 offset:16384
	ds_read_b128 v[226:229], v155 offset:17408
	ds_read_b128 v[230:233], v155 offset:18432
	ds_read_b128 v[234:237], v155 offset:19456
	ds_read_b128 v[238:241], v155 offset:20480
	ds_read_b128 v[242:245], v155 offset:21504
	ds_read_b128 v[246:249], v155 offset:22528
	ds_read_b128 v[250:253], v155 offset:23552
	s_add_u32 s28, s28, 0x80
	s_addc_u32 s29, s29, 0
	s_waitcnt vmcnt(8) lgkmcnt(0)
	s_barrier
	v_mfma_f32_16x16x32_bf16 v[126:129], v[156:159], v[190:193], v[126:129]
	v_mfma_f32_16x16x32_bf16 v[126:129], v[160:163], v[194:197], v[126:129]
	v_mfma_f32_16x16x32_bf16 v[122:125], v[168:171], v[194:197], v[122:125]
	v_mfma_f32_16x16x32_bf16 v[122:125], v[164:167], v[190:193], v[122:125]
	v_mfma_f32_16x16x32_bf16 v[118:121], v[174:177], v[190:193], v[118:121]
	v_mfma_f32_16x16x32_bf16 v[118:121], v[178:181], v[194:197], v[118:121]
	v_mfma_f32_16x16x32_bf16 v[114:117], v[186:189], v[194:197], v[114:117]
	v_mfma_f32_16x16x32_bf16 v[114:117], v[182:185], v[190:193], v[114:117]
	v_mfma_f32_16x16x32_bf16 v[98:101], v[182:185], v[198:201], v[98:101]
	v_mfma_f32_16x16x32_bf16 v[98:101], v[186:189], v[202:205], v[98:101]
	v_mfma_f32_16x16x32_bf16 v[102:105], v[178:181], v[202:205], v[102:105]
	v_mfma_f32_16x16x32_bf16 v[102:105], v[174:177], v[198:201], v[102:105]
	v_mfma_f32_16x16x32_bf16 v[106:109], v[164:167], v[198:201], v[106:109]
	v_mfma_f32_16x16x32_bf16 v[106:109], v[168:171], v[202:205], v[106:109]
	v_mfma_f32_16x16x32_bf16 v[110:113], v[160:163], v[202:205], v[110:113]
	v_mfma_f32_16x16x32_bf16 v[110:113], v[156:159], v[198:201], v[110:113]
	v_mfma_f32_16x16x32_bf16 v[94:97], v[156:159], v[206:209], v[94:97]
	v_mfma_f32_16x16x32_bf16 v[94:97], v[160:163], v[210:213], v[94:97]
	v_mfma_f32_16x16x32_bf16 v[90:93], v[168:171], v[210:213], v[90:93]
	v_mfma_f32_16x16x32_bf16 v[90:93], v[164:167], v[206:209], v[90:93]
	v_mfma_f32_16x16x32_bf16 v[86:89], v[174:177], v[206:209], v[86:89]
	v_mfma_f32_16x16x32_bf16 v[86:89], v[178:181], v[210:213], v[86:89]
	v_mfma_f32_16x16x32_bf16 v[82:85], v[186:189], v[210:213], v[82:85]
	v_mfma_f32_16x16x32_bf16 v[82:85], v[182:185], v[206:209], v[82:85]
	v_mfma_f32_16x16x32_bf16 v[66:69], v[182:185], v[214:217], v[66:69]
	v_mfma_f32_16x16x32_bf16 v[66:69], v[186:189], v[218:221], v[66:69]
	v_mfma_f32_16x16x32_bf16 v[70:73], v[178:181], v[218:221], v[70:73]
	v_mfma_f32_16x16x32_bf16 v[70:73], v[174:177], v[214:217], v[70:73]
	v_mfma_f32_16x16x32_bf16 v[74:77], v[164:167], v[214:217], v[74:77]
	v_mfma_f32_16x16x32_bf16 v[74:77], v[168:171], v[218:221], v[74:77]
	v_mfma_f32_16x16x32_bf16 v[78:81], v[160:163], v[218:221], v[78:81]
	v_mfma_f32_16x16x32_bf16 v[78:81], v[156:159], v[214:217], v[78:81]
	v_mfma_f32_16x16x32_bf16 v[62:65], v[156:159], v[222:225], v[62:65]
	v_mfma_f32_16x16x32_bf16 v[62:65], v[160:163], v[226:229], v[62:65]
	v_mfma_f32_16x16x32_bf16 v[58:61], v[168:171], v[226:229], v[58:61]
	v_mfma_f32_16x16x32_bf16 v[58:61], v[164:167], v[222:225], v[58:61]
	v_mfma_f32_16x16x32_bf16 v[54:57], v[174:177], v[222:225], v[54:57]
	v_mfma_f32_16x16x32_bf16 v[54:57], v[178:181], v[226:229], v[54:57]
	v_mfma_f32_16x16x32_bf16 v[50:53], v[186:189], v[226:229], v[50:53]
	v_mfma_f32_16x16x32_bf16 v[50:53], v[182:185], v[222:225], v[50:53]
	v_mfma_f32_16x16x32_bf16 v[34:37], v[182:185], v[230:233], v[34:37]
	v_mfma_f32_16x16x32_bf16 v[34:37], v[186:189], v[234:237], v[34:37]
	v_mfma_f32_16x16x32_bf16 v[38:41], v[178:181], v[234:237], v[38:41]
	v_mfma_f32_16x16x32_bf16 v[38:41], v[174:177], v[230:233], v[38:41]
	v_mfma_f32_16x16x32_bf16 v[42:45], v[164:167], v[230:233], v[42:45]
	v_mfma_f32_16x16x32_bf16 v[42:45], v[168:171], v[234:237], v[42:45]
	v_mfma_f32_16x16x32_bf16 v[46:49], v[160:163], v[234:237], v[46:49]
	v_mfma_f32_16x16x32_bf16 v[46:49], v[156:159], v[230:233], v[46:49]
	v_mfma_f32_16x16x32_bf16 v[30:33], v[156:159], v[238:241], v[30:33]
	v_mfma_f32_16x16x32_bf16 v[30:33], v[160:163], v[242:245], v[30:33]
	v_mfma_f32_16x16x32_bf16 v[26:29], v[168:171], v[242:245], v[26:29]
	v_mfma_f32_16x16x32_bf16 v[26:29], v[164:167], v[238:241], v[26:29]
	v_mfma_f32_16x16x32_bf16 v[22:25], v[174:177], v[238:241], v[22:25]
	v_mfma_f32_16x16x32_bf16 v[22:25], v[178:181], v[242:245], v[22:25]
	v_mfma_f32_16x16x32_bf16 v[18:21], v[186:189], v[242:245], v[18:21]
	v_mfma_f32_16x16x32_bf16 v[18:21], v[182:185], v[238:241], v[18:21]
	v_mfma_f32_16x16x32_bf16 v[2:5], v[182:185], v[246:249], v[2:5]
	v_mfma_f32_16x16x32_bf16 v[2:5], v[186:189], v[250:253], v[2:5]
	v_mfma_f32_16x16x32_bf16 v[6:9], v[178:181], v[250:253], v[6:9]
	v_mfma_f32_16x16x32_bf16 v[6:9], v[174:177], v[246:249], v[6:9]
	v_mfma_f32_16x16x32_bf16 v[10:13], v[164:167], v[246:249], v[10:13]
	v_mfma_f32_16x16x32_bf16 v[10:13], v[168:171], v[250:253], v[10:13]
	v_mfma_f32_16x16x32_bf16 v[14:17], v[160:163], v[250:253], v[14:17]
	v_mfma_f32_16x16x32_bf16 v[14:17], v[156:159], v[246:249], v[14:17]
	s_waitcnt vmcnt(0)
	s_barrier
; #define PG8_STAGE(bufoff, gbase, voff) do { _Pragma("unroll") for (int _i = 0; _i < 2; ++_i) \
;         __builtin_amdgcn_global_load_lds((const unsigned*)((const char*)(gbase) + (voff)[_i]), (PG8_LAS unsigned*)(lds + (bufoff) + ldsw + _i * 8192), 16, 0, 0); } while (0)
; #define PG8_LDA(dst, b, h) do { _Pragma("unroll") for (int m = 0; m < 4; ++m) _Pragma("unroll") for (int k = 0; k < 2; ++k) dst[m][k] = *(const PG8_LAS bf16x8*)(lds + PG8_SA(b, h) + aoff + m * 2048 + k * 1024); } while (0)
; #define PG8_LDB(dst, b, h) do { _Pragma("unroll") for (int n = 0; n < 2; ++n) _Pragma("unroll") for (int k = 0; k < 2; ++k) dst[n][k] = *(const PG8_LAS bf16x8*)(lds + PG8_SB(b, h) + boff + n * 2048 + k * 1024); } while (0)
; #define PG8_MMA(ai, bj, At, Bt) do { __builtin_amdgcn_s_setprio(1); _Pragma("unroll") for (int m = 0; m < 4; ++m) _Pragma("unroll") for (int n = 0; n < 2; ++n) _Pragma("unroll") for (int k = 0; k < 2; ++k) \
;         acc[ai][bj][m][n] = __builtin_amdgcn_mfma_f32_16x16x32_bf16(Bt[n][k], At[m][k], acc[ai][bj][m][n], 0, 0, 0); __builtin_amdgcn_s_setprio(0); } while (0)
; #define PG8_WAIT_V(n) asm volatile("s_waitcnt vmcnt(" #n ")" ::: "memory")
; template <class Epi, class Sched, bool ALIGN_EPI>
; __device__ __forceinline__ void gemm_phase(PG8_LAS unsigned char* lds, const Gemm g, const Sched& S, const Epi& E) {
;     ...
;             PG8_LDB(B0, 0, 0); PG8_LDB(B1, 0, 1); PG8_SCHED; PG8_LDA(At, 0, 0); PG8_STAGE(PG8_SA(1, 1), a1 + hstepA, voffA);
;             PG8_WAIT_V(8); PG8_WAIT_L(0); PG8_BAR; PG8_MMA(0, 0, At, B0); PG8_MMA(0, 1, At, B1); PG8_BAR; PG8_SCHED;
;             PG8_LDA(At, 0, 1); PG8_STAGE(PG8_SB(0, 0), b2, voffB); PG8_STAGE(PG8_SB(0, 1), b2 + hstepB, voffB); PG8_STAGE(PG8_SA(0, 0), a2, voffA);
;             PG8_WAIT_V(8); PG8_WAIT_L(0); PG8_BAR; PG8_MMA(1, 0, At, B0); PG8_MMA(1, 1, At, B1); PG8_BAR; PG8_SCHED;
;             PG8_LDB(B0, 1, 0); PG8_LDB(B1, 1, 1); PG8_SCHED; PG8_LDA(At, 1, 0); PG8_STAGE(PG8_SA(0, 1), a2 + hstepA, voffA);
;             PG8_WAIT_V(8); PG8_WAIT_L(0); PG8_BAR; PG8_MMA(0, 0, At, B0); PG8_MMA(0, 1, At, B1); PG8_BAR; PG8_SCHED;
;             PG8_LDA(At, 1, 1); PG8_STAGE(PG8_SB(1, 0), b3, voffB); PG8_STAGE(PG8_SB(1, 1), b3 + hstepB, voffB); PG8_STAGE(PG8_SA(1, 0), a3, voffA);
;             PG8_WAIT_V(8); PG8_WAIT_L(0); PG8_BAR; PG8_MMA(1, 0, At, B0); PG8_MMA(1, 1, At, B1); PG8_BAR; PG8_SCHED;
;         }
	ds_read_b128 v[190:193], v155 offset:32768
	ds_read_b128 v[194:197], v155 offset:33792
	s_cmp_eq_u32 s49, 15
	s_cselect_b32 s28, s50, s28
	s_cselect_b32 s29, s51, s29
	s_add_i32 m0, s2, 0x2000
	s_nop 0
	global_load_lds_dwordx4 v132, s[28:29]
	ds_read_b128 v[198:201], v155 offset:34816
	ds_read_b128 v[202:205], v155 offset:35840
	s_add_u32 s30, s28, 0x20000
	s_addc_u32 s31, s29, 0
	s_add_i32 m0, s2, 0x3000
	s_nop 0
	global_load_lds_dwordx4 v132, s[30:31]
	ds_read_b128 v[206:209], v155 offset:36864
	ds_read_b128 v[210:213], v155 offset:37888
	s_add_u32 s30, s28, 0x80000
	s_addc_u32 s31, s29, 0
	s_add_i32 m0, s2, 0x6000
	s_nop 0
	global_load_lds_dwordx4 v132, s[30:31]
	ds_read_b128 v[214:217], v155 offset:38912
	ds_read_b128 v[218:221], v155 offset:39936
	s_add_u32 s30, s28, 0xa0000
	s_addc_u32 s31, s29, 0
	s_add_i32 m0, s2, 0x7000
	s_nop 0
	global_load_lds_dwordx4 v132, s[30:31]
	ds_read_b128 v[156:159], v153 offset:32768
	ds_read_b128 v[160:163], v153 offset:33792
	s_add_u32 s34, s28, 0x80
	s_addc_u32 s35, s29, 0
	s_add_i32 m0, s2, 0x8000
	s_nop 0
	global_load_lds_dwordx4 v136, s[34:35]
	ds_read_b128 v[164:167], v153 offset:34816
	ds_read_b128 v[168:171], v153 offset:35840
	s_add_u32 s30, s34, 0x20000
	s_addc_u32 s31, s35, 0
	s_add_i32 m0, s2, 0x9000
	s_nop 0
	global_load_lds_dwordx4 v136, s[30:31]
	ds_read_b128 v[174:177], v153 offset:49152
	ds_read_b128 v[178:181], v153 offset:50176
	s_add_u32 s30, s34, 0x80000
	s_addc_u32 s31, s35, 0
	s_add_i32 m0, s2, 0xc000
	s_nop 0
	global_load_lds_dwordx4 v136, s[30:31]
	ds_read_b128 v[182:185], v153 offset:51200
	ds_read_b128 v[186:189], v153 offset:52224
	s_add_u32 s30, s34, 0xa0000
	s_addc_u32 s31, s35, 0
	s_add_i32 m0, s2, 0xd000
	s_nop 0
	global_load_lds_dwordx4 v136, s[30:31]
	ds_read_b128 v[222:225], v155 offset:49152
	ds_read_b128 v[226:229], v155 offset:50176
	ds_read_b128 v[230:233], v155 offset:51200
	ds_read_b128 v[234:237], v155 offset:52224
	ds_read_b128 v[238:241], v155 offset:53248
	ds_read_b128 v[242:245], v155 offset:54272
	ds_read_b128 v[246:249], v155 offset:55296
	ds_read_b128 v[250:253], v155 offset:56320
	s_add_u32 s28, s28, 0x80
	s_addc_u32 s29, s29, 0
	s_waitcnt vmcnt(8) lgkmcnt(0)
	s_barrier
	v_mfma_f32_16x16x32_bf16 v[126:129], v[156:159], v[190:193], v[126:129]
	v_mfma_f32_16x16x32_bf16 v[126:129], v[160:163], v[194:197], v[126:129]
	v_mfma_f32_16x16x32_bf16 v[122:125], v[168:171], v[194:197], v[122:125]
	v_mfma_f32_16x16x32_bf16 v[122:125], v[164:167], v[190:193], v[122:125]
	v_mfma_f32_16x16x32_bf16 v[118:121], v[174:177], v[190:193], v[118:121]
	v_mfma_f32_16x16x32_bf16 v[118:121], v[178:181], v[194:197], v[118:121]
	v_mfma_f32_16x16x32_bf16 v[114:117], v[186:189], v[194:197], v[114:117]
	v_mfma_f32_16x16x32_bf16 v[114:117], v[182:185], v[190:193], v[114:117]
	v_mfma_f32_16x16x32_bf16 v[98:101], v[182:185], v[198:201], v[98:101]
	v_mfma_f32_16x16x32_bf16 v[98:101], v[186:189], v[202:205], v[98:101]
	v_mfma_f32_16x16x32_bf16 v[102:105], v[178:181], v[202:205], v[102:105]
	v_mfma_f32_16x16x32_bf16 v[102:105], v[174:177], v[198:201], v[102:105]
	v_mfma_f32_16x16x32_bf16 v[106:109], v[164:167], v[198:201], v[106:109]
	v_mfma_f32_16x16x32_bf16 v[106:109], v[168:171], v[202:205], v[106:109]
	v_mfma_f32_16x16x32_bf16 v[110:113], v[160:163], v[202:205], v[110:113]
	v_mfma_f32_16x16x32_bf16 v[110:113], v[156:159], v[198:201], v[110:113]
	v_mfma_f32_16x16x32_bf16 v[94:97], v[156:159], v[206:209], v[94:97]
	v_mfma_f32_16x16x32_bf16 v[94:97], v[160:163], v[210:213], v[94:97]
	v_mfma_f32_16x16x32_bf16 v[90:93], v[168:171], v[210:213], v[90:93]
	v_mfma_f32_16x16x32_bf16 v[90:93], v[164:167], v[206:209], v[90:93]
	v_mfma_f32_16x16x32_bf16 v[86:89], v[174:177], v[206:209], v[86:89]
	v_mfma_f32_16x16x32_bf16 v[86:89], v[178:181], v[210:213], v[86:89]
	v_mfma_f32_16x16x32_bf16 v[82:85], v[186:189], v[210:213], v[82:85]
	v_mfma_f32_16x16x32_bf16 v[82:85], v[182:185], v[206:209], v[82:85]
	v_mfma_f32_16x16x32_bf16 v[66:69], v[182:185], v[214:217], v[66:69]
	v_mfma_f32_16x16x32_bf16 v[66:69], v[186:189], v[218:221], v[66:69]
	v_mfma_f32_16x16x32_bf16 v[70:73], v[178:181], v[218:221], v[70:73]
	v_mfma_f32_16x16x32_bf16 v[70:73], v[174:177], v[214:217], v[70:73]
	v_mfma_f32_16x16x32_bf16 v[74:77], v[164:167], v[214:217], v[74:77]
	v_mfma_f32_16x16x32_bf16 v[74:77], v[168:171], v[218:221], v[74:77]
	v_mfma_f32_16x16x32_bf16 v[78:81], v[160:163], v[218:221], v[78:81]
	v_mfma_f32_16x16x32_bf16 v[78:81], v[156:159], v[214:217], v[78:81]
	v_mfma_f32_16x16x32_bf16 v[62:65], v[156:159], v[222:225], v[62:65]
	v_mfma_f32_16x16x32_bf16 v[62:65], v[160:163], v[226:229], v[62:65]
	v_mfma_f32_16x16x32_bf16 v[58:61], v[168:171], v[226:229], v[58:61]
	v_mfma_f32_16x16x32_bf16 v[58:61], v[164:167], v[222:225], v[58:61]
	v_mfma_f32_16x16x32_bf16 v[54:57], v[174:177], v[222:225], v[54:57]
	v_mfma_f32_16x16x32_bf16 v[54:57], v[178:181], v[226:229], v[54:57]
	v_mfma_f32_16x16x32_bf16 v[50:53], v[186:189], v[226:229], v[50:53]
	v_mfma_f32_16x16x32_bf16 v[50:53], v[182:185], v[222:225], v[50:53]
	v_mfma_f32_16x16x32_bf16 v[34:37], v[182:185], v[230:233], v[34:37]
	v_mfma_f32_16x16x32_bf16 v[34:37], v[186:189], v[234:237], v[34:37]
	v_mfma_f32_16x16x32_bf16 v[38:41], v[178:181], v[234:237], v[38:41]
	v_mfma_f32_16x16x32_bf16 v[38:41], v[174:177], v[230:233], v[38:41]
	v_mfma_f32_16x16x32_bf16 v[42:45], v[164:167], v[230:233], v[42:45]
	v_mfma_f32_16x16x32_bf16 v[42:45], v[168:171], v[234:237], v[42:45]
	v_mfma_f32_16x16x32_bf16 v[46:49], v[160:163], v[234:237], v[46:49]
	v_mfma_f32_16x16x32_bf16 v[46:49], v[156:159], v[230:233], v[46:49]
	v_mfma_f32_16x16x32_bf16 v[30:33], v[156:159], v[238:241], v[30:33]
	v_mfma_f32_16x16x32_bf16 v[30:33], v[160:163], v[242:245], v[30:33]
	v_mfma_f32_16x16x32_bf16 v[26:29], v[168:171], v[242:245], v[26:29]
	v_mfma_f32_16x16x32_bf16 v[26:29], v[164:167], v[238:241], v[26:29]
	v_mfma_f32_16x16x32_bf16 v[22:25], v[174:177], v[238:241], v[22:25]
	v_mfma_f32_16x16x32_bf16 v[22:25], v[178:181], v[242:245], v[22:25]
	v_mfma_f32_16x16x32_bf16 v[18:21], v[186:189], v[242:245], v[18:21]
	v_mfma_f32_16x16x32_bf16 v[18:21], v[182:185], v[238:241], v[18:21]
	v_mfma_f32_16x16x32_bf16 v[2:5], v[182:185], v[246:249], v[2:5]
	v_mfma_f32_16x16x32_bf16 v[2:5], v[186:189], v[250:253], v[2:5]
	v_mfma_f32_16x16x32_bf16 v[6:9], v[178:181], v[250:253], v[6:9]
	v_mfma_f32_16x16x32_bf16 v[6:9], v[174:177], v[246:249], v[6:9]
	v_mfma_f32_16x16x32_bf16 v[10:13], v[164:167], v[246:249], v[10:13]
	v_mfma_f32_16x16x32_bf16 v[10:13], v[168:171], v[250:253], v[10:13]
	v_mfma_f32_16x16x32_bf16 v[14:17], v[160:163], v[250:253], v[14:17]
	v_mfma_f32_16x16x32_bf16 v[14:17], v[156:159], v[246:249], v[14:17]
	s_waitcnt vmcnt(0)
	s_add_i32 s49, s49, 1
	s_cmp_lt_u32 s49, 16
	s_cbranch_scc0 .Lp8k_B_exit
	s_barrier
	s_branch .Lp8k_B_loop

; #define PG8_STAGE(bufoff, gbase, voff) do { _Pragma("unroll") for (int _i = 0; _i < 2; ++_i) \
;         __builtin_amdgcn_global_load_lds((const unsigned*)((const char*)(gbase) + (voff)[_i]), (PG8_LAS unsigned*)(lds + (bufoff) + ldsw + _i * 8192), 16, 0, 0); } while (0)
; #define PG8_LDA(dst, b, h) do { _Pragma("unroll") for (int m = 0; m < 4; ++m) _Pragma("unroll") for (int k = 0; k < 2; ++k) dst[m][k] = *(const PG8_LAS bf16x8*)(lds + PG8_SA(b, h) + aoff + m * 2048 + k * 1024); } while (0)
; #define PG8_LDB(dst, b, h) do { _Pragma("unroll") for (int n = 0; n < 2; ++n) _Pragma("unroll") for (int k = 0; k < 2; ++k) dst[n][k] = *(const PG8_LAS bf16x8*)(lds + PG8_SB(b, h) + boff + n * 2048 + k * 1024); } while (0)
; #define PG8_MMA(ai, bj, At, Bt) do { __builtin_amdgcn_s_setprio(1); _Pragma("unroll") for (int m = 0; m < 4; ++m) _Pragma("unroll") for (int n = 0; n < 2; ++n) _Pragma("unroll") for (int k = 0; k < 2; ++k) \
;         acc[ai][bj][m][n] = __builtin_amdgcn_mfma_f32_16x16x32_bf16(Bt[n][k], At[m][k], acc[ai][bj][m][n], 0, 0, 0); __builtin_amdgcn_s_setprio(0); } while (0)
; #define PG8_WAIT_V(n) asm volatile("s_waitcnt vmcnt(" #n ")" ::: "memory")
; template <class Epi, class Sched, bool ALIGN_EPI>
; __device__ __forceinline__ void gemm_phase(PG8_LAS unsigned char* lds, const Gemm g, const Sched& S, const Epi& E) {
;     ...
;             PG8_LDB(B0, 0, 0); PG8_LDB(B1, 0, 1); PG8_SCHED; PG8_LDA(At, 0, 0); PG8_STAGE(PG8_SA(1, 1), a1 + hstepA, voffA);
;             PG8_WAIT_V(8); PG8_WAIT_L(0); PG8_BAR; PG8_MMA(0, 0, At, B0); PG8_MMA(0, 1, At, B1); PG8_BAR; PG8_SCHED;
;             PG8_LDA(At, 0, 1); PG8_STAGE(PG8_SB(0, 0), b2, voffB); PG8_STAGE(PG8_SB(0, 1), b2 + hstepB, voffB); PG8_STAGE(PG8_SA(0, 0), a2, voffA);
;             PG8_WAIT_V(8); PG8_WAIT_L(0); PG8_BAR; PG8_MMA(1, 0, At, B0); PG8_MMA(1, 1, At, B1); PG8_BAR; PG8_SCHED;
;             PG8_LDB(B0, 1, 0); PG8_LDB(B1, 1, 1); PG8_SCHED; PG8_LDA(At, 1, 0); PG8_STAGE(PG8_SA(0, 1), a2 + hstepA, voffA);
;             PG8_WAIT_V(8); PG8_WAIT_L(0); PG8_BAR; PG8_MMA(0, 0, At, B0); PG8_MMA(0, 1, At, B1); PG8_BAR; PG8_SCHED;
;             PG8_LDA(At, 1, 1); PG8_STAGE(PG8_SB(1, 0), b3, voffB); PG8_STAGE(PG8_SB(1, 1), b3 + hstepB, voffB); PG8_STAGE(PG8_SA(1, 0), a3, voffA);
;             PG8_WAIT_V(8); PG8_WAIT_L(0); PG8_BAR; PG8_MMA(1, 0, At, B0); PG8_MMA(1, 1, At, B1); PG8_BAR; PG8_SCHED;
.Lp9k_A_first:
	s_add_u32 s28, s28, 0x80
	s_addc_u32 s29, s29, 0
	ds_read_b128 v[194:197], v157 offset:0
	ds_read_b128 v[198:201], v157 offset:1024
	s_add_i32 m0, s60, 0x18000
	s_nop 0
	global_load_lds_dwordx4 v132, s[28:29]
	ds_read_b128 v[202:205], v157 offset:2048
	ds_read_b128 v[206:209], v157 offset:3072
	s_add_i32 m0, s60, 0x1a000
	s_nop 0
	global_load_lds_dwordx4 v136, s[28:29]
	ds_read_b128 v[210:213], v157 offset:4096
	ds_read_b128 v[214:217], v157 offset:5120
	s_add_u32 s30, s28, 0x58000
	s_addc_u32 s31, s29, 0
	s_add_i32 m0, s60, 0x19000
	s_nop 0
	global_load_lds_dwordx4 v132, s[30:31]
	ds_read_b128 v[218:221], v157 offset:6144
	ds_read_b128 v[222:225], v157 offset:7168
	s_add_i32 m0, s60, 0x1b000
	s_nop 0
	global_load_lds_dwordx4 v136, s[30:31]
	ds_read_b128 v[158:161], v155 offset:0
	ds_read_b128 v[162:165], v155 offset:1024
	s_add_u32 s30, s28, 0x160000
	s_addc_u32 s31, s29, 0
	s_add_i32 m0, s60, 0x1c000
	s_nop 0
	global_load_lds_dwordx4 v132, s[30:31]
	ds_read_b128 v[166:169], v155 offset:2048
	ds_read_b128 v[174:177], v155 offset:3072
	s_add_i32 m0, s60, 0x1e000
	s_nop 0
	global_load_lds_dwordx4 v136, s[30:31]
	ds_read_b128 v[178:181], v155 offset:16384
	ds_read_b128 v[182:185], v155 offset:17408
	s_add_u32 s30, s28, 0x1b8000
	s_addc_u32 s31, s29, 0
	s_add_i32 m0, s60, 0x1d000
	s_nop 0
	global_load_lds_dwordx4 v132, s[30:31]
	ds_read_b128 v[186:189], v155 offset:18432
	ds_read_b128 v[190:193], v155 offset:19456
	s_add_i32 m0, s60, 0x1f000
	s_nop 0
	global_load_lds_dwordx4 v136, s[30:31]
	ds_read_b128 v[226:229], v157 offset:16384
	ds_read_b128 v[230:233], v157 offset:17408
	ds_read_b128 v[234:237], v157 offset:18432
	ds_read_b128 v[238:241], v157 offset:19456
	ds_read_b128 v[242:245], v157 offset:20480
	ds_read_b128 v[246:249], v157 offset:21504
	ds_read_b128 v[250:253], v157 offset:22528
	ds_read_b128 v[142:145], v157 offset:23552
	s_add_u32 s28, s28, 0x80
	s_addc_u32 s29, s29, 0
.Lp9k_A_entry:
	s_waitcnt vmcnt(8) lgkmcnt(0)
	s_barrier
	v_mfma_f32_16x16x32_bf16 v[126:129], v[158:161], v[194:197], 0
	v_mfma_f32_16x16x32_bf16 v[126:129], v[162:165], v[198:201], v[126:129]
	v_mfma_f32_16x16x32_bf16 v[122:125], v[174:177], v[198:201], 0
	v_mfma_f32_16x16x32_bf16 v[122:125], v[166:169], v[194:197], v[122:125]
	v_mfma_f32_16x16x32_bf16 v[114:117], v[178:181], v[194:197], 0
	v_mfma_f32_16x16x32_bf16 v[114:117], v[182:185], v[198:201], v[114:117]
	v_mfma_f32_16x16x32_bf16 v[106:109], v[190:193], v[198:201], 0
	v_mfma_f32_16x16x32_bf16 v[106:109], v[186:189], v[194:197], v[106:109]
	v_mfma_f32_16x16x32_bf16 v[90:93], v[186:189], v[202:205], 0
	v_mfma_f32_16x16x32_bf16 v[90:93], v[190:193], v[206:209], v[90:93]
	v_mfma_f32_16x16x32_bf16 v[98:101], v[182:185], v[206:209], 0
	v_mfma_f32_16x16x32_bf16 v[98:101], v[178:181], v[202:205], v[98:101]
	v_mfma_f32_16x16x32_bf16 v[110:113], v[166:169], v[202:205], 0
	v_mfma_f32_16x16x32_bf16 v[110:113], v[174:177], v[206:209], v[110:113]
	v_mfma_f32_16x16x32_bf16 v[118:121], v[162:165], v[206:209], 0
	v_mfma_f32_16x16x32_bf16 v[118:121], v[158:161], v[202:205], v[118:121]
	v_mfma_f32_16x16x32_bf16 v[102:105], v[158:161], v[210:213], 0
	v_mfma_f32_16x16x32_bf16 v[102:105], v[162:165], v[214:217], v[102:105]
	v_mfma_f32_16x16x32_bf16 v[94:97], v[174:177], v[214:217], 0
	v_mfma_f32_16x16x32_bf16 v[94:97], v[166:169], v[210:213], v[94:97]
	v_mfma_f32_16x16x32_bf16 v[82:85], v[178:181], v[210:213], 0
	v_mfma_f32_16x16x32_bf16 v[82:85], v[182:185], v[214:217], v[82:85]
	v_mfma_f32_16x16x32_bf16 v[74:77], v[190:193], v[214:217], 0
	v_mfma_f32_16x16x32_bf16 v[74:77], v[186:189], v[210:213], v[74:77]
	v_mfma_f32_16x16x32_bf16 v[66:69], v[186:189], v[218:221], 0
	v_mfma_f32_16x16x32_bf16 v[66:69], v[190:193], v[222:225], v[66:69]
	v_mfma_f32_16x16x32_bf16 v[70:73], v[182:185], v[222:225], 0
	v_mfma_f32_16x16x32_bf16 v[70:73], v[178:181], v[218:221], v[70:73]
	v_mfma_f32_16x16x32_bf16 v[78:81], v[166:169], v[218:221], 0
	v_mfma_f32_16x16x32_bf16 v[78:81], v[174:177], v[222:225], v[78:81]
	v_mfma_f32_16x16x32_bf16 v[86:89], v[162:165], v[222:225], 0
	v_mfma_f32_16x16x32_bf16 v[86:89], v[158:161], v[218:221], v[86:89]
	v_mfma_f32_16x16x32_bf16 v[62:65], v[158:161], v[226:229], 0
	v_mfma_f32_16x16x32_bf16 v[62:65], v[162:165], v[230:233], v[62:65]
	v_mfma_f32_16x16x32_bf16 v[58:61], v[174:177], v[230:233], 0
	v_mfma_f32_16x16x32_bf16 v[58:61], v[166:169], v[226:229], v[58:61]
	v_mfma_f32_16x16x32_bf16 v[50:53], v[178:181], v[226:229], 0
	v_mfma_f32_16x16x32_bf16 v[50:53], v[182:185], v[230:233], v[50:53]
	v_mfma_f32_16x16x32_bf16 v[42:45], v[190:193], v[230:233], 0
	v_mfma_f32_16x16x32_bf16 v[42:45], v[186:189], v[226:229], v[42:45]
	v_mfma_f32_16x16x32_bf16 v[26:29], v[186:189], v[234:237], 0
	v_mfma_f32_16x16x32_bf16 v[26:29], v[190:193], v[238:241], v[26:29]
	v_mfma_f32_16x16x32_bf16 v[34:37], v[182:185], v[238:241], 0
	v_mfma_f32_16x16x32_bf16 v[34:37], v[178:181], v[234:237], v[34:37]
	v_mfma_f32_16x16x32_bf16 v[46:49], v[166:169], v[234:237], 0
	v_mfma_f32_16x16x32_bf16 v[46:49], v[174:177], v[238:241], v[46:49]
	v_mfma_f32_16x16x32_bf16 v[54:57], v[162:165], v[238:241], 0
	v_mfma_f32_16x16x32_bf16 v[54:57], v[158:161], v[234:237], v[54:57]
	v_mfma_f32_16x16x32_bf16 v[38:41], v[158:161], v[242:245], 0
	v_mfma_f32_16x16x32_bf16 v[38:41], v[162:165], v[246:249], v[38:41]
	v_mfma_f32_16x16x32_bf16 v[30:33], v[174:177], v[246:249], 0
	v_mfma_f32_16x16x32_bf16 v[30:33], v[166:169], v[242:245], v[30:33]
	v_mfma_f32_16x16x32_bf16 v[18:21], v[178:181], v[242:245], 0
	v_mfma_f32_16x16x32_bf16 v[18:21], v[182:185], v[246:249], v[18:21]
	v_mfma_f32_16x16x32_bf16 v[10:13], v[190:193], v[246:249], 0
	v_mfma_f32_16x16x32_bf16 v[10:13], v[186:189], v[242:245], v[10:13]
	v_mfma_f32_16x16x32_bf16 v[2:5], v[186:189], v[250:253], 0
	v_mfma_f32_16x16x32_bf16 v[2:5], v[190:193], v[142:145], v[2:5]
	v_mfma_f32_16x16x32_bf16 v[6:9], v[182:185], v[142:145], 0
	v_mfma_f32_16x16x32_bf16 v[6:9], v[178:181], v[250:253], v[6:9]
	v_mfma_f32_16x16x32_bf16 v[14:17], v[166:169], v[250:253], 0
	v_mfma_f32_16x16x32_bf16 v[14:17], v[174:177], v[142:145], v[14:17]
	v_mfma_f32_16x16x32_bf16 v[22:25], v[162:165], v[142:145], 0
	v_mfma_f32_16x16x32_bf16 v[22:25], v[158:161], v[250:253], v[22:25]
	s_waitcnt vmcnt(0)
	s_barrier
; #define PG8_STAGE(bufoff, gbase, voff) do { _Pragma("unroll") for (int _i = 0; _i < 2; ++_i) \
;         __builtin_amdgcn_global_load_lds((const unsigned*)((const char*)(gbase) + (voff)[_i]), (PG8_LAS unsigned*)(lds + (bufoff) + ldsw + _i * 8192), 16, 0, 0); } while (0)
; #define PG8_LDA(dst, b, h) do { _Pragma("unroll") for (int m = 0; m < 4; ++m) _Pragma("unroll") for (int k = 0; k < 2; ++k) dst[m][k] = *(const PG8_LAS bf16x8*)(lds + PG8_SA(b, h) + aoff + m * 2048 + k * 1024); } while (0)
; #define PG8_LDB(dst, b, h) do { _Pragma("unroll") for (int n = 0; n < 2; ++n) _Pragma("unroll") for (int k = 0; k < 2; ++k) dst[n][k] = *(const PG8_LAS bf16x8*)(lds + PG8_SB(b, h) + boff + n * 2048 + k * 1024); } while (0)
; #define PG8_MMA(ai, bj, At, Bt) do { __builtin_amdgcn_s_setprio(1); _Pragma("unroll") for (int m = 0; m < 4; ++m) _Pragma("unroll") for (int n = 0; n < 2; ++n) _Pragma("unroll") for (int k = 0; k < 2; ++k) \
;         acc[ai][bj][m][n] = __builtin_amdgcn_mfma_f32_16x16x32_bf16(Bt[n][k], At[m][k], acc[ai][bj][m][n], 0, 0, 0); __builtin_amdgcn_s_setprio(0); } while (0)
; #define PG8_WAIT_V(n) asm volatile("s_waitcnt vmcnt(" #n ")" ::: "memory")
; template <class Epi, class Sched, bool ALIGN_EPI>
; __device__ __forceinline__ void gemm_phase(PG8_LAS unsigned char* lds, const Gemm g, const Sched& S, const Epi& E) {
;     ...
;             PG8_LDB(B0, 0, 0); PG8_LDB(B1, 0, 1); PG8_SCHED; PG8_LDA(At, 0, 0); PG8_STAGE(PG8_SA(1, 1), a1 + hstepA, voffA);
;             PG8_WAIT_V(8); PG8_WAIT_L(0); PG8_BAR; PG8_MMA(0, 0, At, B0); PG8_MMA(0, 1, At, B1); PG8_BAR; PG8_SCHED;
;             PG8_LDA(At, 0, 1); PG8_STAGE(PG8_SB(0, 0), b2, voffB); PG8_STAGE(PG8_SB(0, 1), b2 + hstepB, voffB); PG8_STAGE(PG8_SA(0, 0), a2, voffA);
;             PG8_WAIT_V(8); PG8_WAIT_L(0); PG8_BAR; PG8_MMA(1, 0, At, B0); PG8_MMA(1, 1, At, B1); PG8_BAR; PG8_SCHED;
;             PG8_LDB(B0, 1, 0); PG8_LDB(B1, 1, 1); PG8_SCHED; PG8_LDA(At, 1, 0); PG8_STAGE(PG8_SA(0, 1), a2 + hstepA, voffA);
;             PG8_WAIT_V(8); PG8_WAIT_L(0); PG8_BAR; PG8_MMA(0, 0, At, B0); PG8_MMA(0, 1, At, B1); PG8_BAR; PG8_SCHED;
;             PG8_LDA(At, 1, 1); PG8_STAGE(PG8_SB(1, 0), b3, voffB); PG8_STAGE(PG8_SB(1, 1), b3 + hstepB, voffB); PG8_STAGE(PG8_SA(1, 0), a3, voffA);
;             PG8_WAIT_V(8); PG8_WAIT_L(0); PG8_BAR; PG8_MMA(1, 0, At, B0); PG8_MMA(1, 1, At, B1); PG8_BAR; PG8_SCHED;
	ds_read_b128 v[194:197], v157 offset:32768
	ds_read_b128 v[198:201], v157 offset:33792
	s_cmp_eq_u32 s57, 43
	s_cselect_b32 s28, s58, s28
	s_cselect_b32 s29, s59, s29
	s_add_i32 m0, s60, 0x10000
	s_nop 0
	global_load_lds_dwordx4 v132, s[28:29]
	ds_read_b128 v[202:205], v157 offset:34816
	ds_read_b128 v[206:209], v157 offset:35840
	s_add_i32 m0, s60, 0x12000
	s_nop 0
	global_load_lds_dwordx4 v136, s[28:29]
	ds_read_b128 v[210:213], v157 offset:36864
	ds_read_b128 v[214:217], v157 offset:37888
	s_add_u32 s30, s28, 0x58000
	s_addc_u32 s31, s29, 0
	s_add_i32 m0, s60, 0x11000
	s_nop 0
	global_load_lds_dwordx4 v132, s[30:31]
	ds_read_b128 v[218:221], v157 offset:38912
	ds_read_b128 v[222:225], v157 offset:39936
	s_add_i32 m0, s60, 0x13000
	s_nop 0
	global_load_lds_dwordx4 v136, s[30:31]
	ds_read_b128 v[158:161], v155 offset:32768
	ds_read_b128 v[162:165], v155 offset:33792
	s_add_u32 s30, s28, 0x160000
	s_addc_u32 s31, s29, 0
	s_add_i32 m0, s60, 0x14000
	s_nop 0
	global_load_lds_dwordx4 v132, s[30:31]
	ds_read_b128 v[166:169], v155 offset:34816
	ds_read_b128 v[174:177], v155 offset:35840
	s_add_i32 m0, s60, 0x16000
	s_nop 0
	global_load_lds_dwordx4 v136, s[30:31]
	ds_read_b128 v[178:181], v155 offset:49152
	ds_read_b128 v[182:185], v155 offset:50176
	s_add_u32 s30, s28, 0x1b8000
	s_addc_u32 s31, s29, 0
	s_add_i32 m0, s60, 0x15000
	s_nop 0
	global_load_lds_dwordx4 v132, s[30:31]
	ds_read_b128 v[186:189], v155 offset:51200
	ds_read_b128 v[190:193], v155 offset:52224
	s_add_i32 m0, s60, 0x17000
	s_nop 0
	global_load_lds_dwordx4 v136, s[30:31]
	ds_read_b128 v[226:229], v157 offset:49152
	ds_read_b128 v[230:233], v157 offset:50176
	ds_read_b128 v[234:237], v157 offset:51200
	ds_read_b128 v[238:241], v157 offset:52224
	ds_read_b128 v[242:245], v157 offset:53248
	ds_read_b128 v[246:249], v157 offset:54272
	ds_read_b128 v[250:253], v157 offset:55296
	ds_read_b128 v[142:145], v157 offset:56320
	s_add_u32 s28, s28, 0x80
	s_addc_u32 s29, s29, 0
	s_waitcnt vmcnt(8) lgkmcnt(0)
	s_barrier
	v_mfma_f32_16x16x32_bf16 v[126:129], v[158:161], v[194:197], v[126:129]
	v_mfma_f32_16x16x32_bf16 v[126:129], v[162:165], v[198:201], v[126:129]
	v_mfma_f32_16x16x32_bf16 v[122:125], v[174:177], v[198:201], v[122:125]
	v_mfma_f32_16x16x32_bf16 v[122:125], v[166:169], v[194:197], v[122:125]
	v_mfma_f32_16x16x32_bf16 v[114:117], v[178:181], v[194:197], v[114:117]
	v_mfma_f32_16x16x32_bf16 v[114:117], v[182:185], v[198:201], v[114:117]
	v_mfma_f32_16x16x32_bf16 v[106:109], v[190:193], v[198:201], v[106:109]
	v_mfma_f32_16x16x32_bf16 v[106:109], v[186:189], v[194:197], v[106:109]
	v_mfma_f32_16x16x32_bf16 v[90:93], v[186:189], v[202:205], v[90:93]
	v_mfma_f32_16x16x32_bf16 v[90:93], v[190:193], v[206:209], v[90:93]
	v_mfma_f32_16x16x32_bf16 v[98:101], v[182:185], v[206:209], v[98:101]
	v_mfma_f32_16x16x32_bf16 v[98:101], v[178:181], v[202:205], v[98:101]
	v_mfma_f32_16x16x32_bf16 v[110:113], v[166:169], v[202:205], v[110:113]
	v_mfma_f32_16x16x32_bf16 v[110:113], v[174:177], v[206:209], v[110:113]
	v_mfma_f32_16x16x32_bf16 v[118:121], v[162:165], v[206:209], v[118:121]
	v_mfma_f32_16x16x32_bf16 v[118:121], v[158:161], v[202:205], v[118:121]
	v_mfma_f32_16x16x32_bf16 v[102:105], v[158:161], v[210:213], v[102:105]
	v_mfma_f32_16x16x32_bf16 v[102:105], v[162:165], v[214:217], v[102:105]
	v_mfma_f32_16x16x32_bf16 v[94:97], v[174:177], v[214:217], v[94:97]
	v_mfma_f32_16x16x32_bf16 v[94:97], v[166:169], v[210:213], v[94:97]
	v_mfma_f32_16x16x32_bf16 v[82:85], v[178:181], v[210:213], v[82:85]
	v_mfma_f32_16x16x32_bf16 v[82:85], v[182:185], v[214:217], v[82:85]
	v_mfma_f32_16x16x32_bf16 v[74:77], v[190:193], v[214:217], v[74:77]
	v_mfma_f32_16x16x32_bf16 v[74:77], v[186:189], v[210:213], v[74:77]
	v_mfma_f32_16x16x32_bf16 v[66:69], v[186:189], v[218:221], v[66:69]
	v_mfma_f32_16x16x32_bf16 v[66:69], v[190:193], v[222:225], v[66:69]
	v_mfma_f32_16x16x32_bf16 v[70:73], v[182:185], v[222:225], v[70:73]
	v_mfma_f32_16x16x32_bf16 v[70:73], v[178:181], v[218:221], v[70:73]
	v_mfma_f32_16x16x32_bf16 v[78:81], v[166:169], v[218:221], v[78:81]
	v_mfma_f32_16x16x32_bf16 v[78:81], v[174:177], v[222:225], v[78:81]
	v_mfma_f32_16x16x32_bf16 v[86:89], v[162:165], v[222:225], v[86:89]
	v_mfma_f32_16x16x32_bf16 v[86:89], v[158:161], v[218:221], v[86:89]
	v_mfma_f32_16x16x32_bf16 v[62:65], v[158:161], v[226:229], v[62:65]
	v_mfma_f32_16x16x32_bf16 v[62:65], v[162:165], v[230:233], v[62:65]
	v_mfma_f32_16x16x32_bf16 v[58:61], v[174:177], v[230:233], v[58:61]
	v_mfma_f32_16x16x32_bf16 v[58:61], v[166:169], v[226:229], v[58:61]
	v_mfma_f32_16x16x32_bf16 v[50:53], v[178:181], v[226:229], v[50:53]
	v_mfma_f32_16x16x32_bf16 v[50:53], v[182:185], v[230:233], v[50:53]
	v_mfma_f32_16x16x32_bf16 v[42:45], v[190:193], v[230:233], v[42:45]
	v_mfma_f32_16x16x32_bf16 v[42:45], v[186:189], v[226:229], v[42:45]
	v_mfma_f32_16x16x32_bf16 v[26:29], v[186:189], v[234:237], v[26:29]
	v_mfma_f32_16x16x32_bf16 v[26:29], v[190:193], v[238:241], v[26:29]
	v_mfma_f32_16x16x32_bf16 v[34:37], v[182:185], v[238:241], v[34:37]
	v_mfma_f32_16x16x32_bf16 v[34:37], v[178:181], v[234:237], v[34:37]
	v_mfma_f32_16x16x32_bf16 v[46:49], v[166:169], v[234:237], v[46:49]
	v_mfma_f32_16x16x32_bf16 v[46:49], v[174:177], v[238:241], v[46:49]
	v_mfma_f32_16x16x32_bf16 v[54:57], v[162:165], v[238:241], v[54:57]
	v_mfma_f32_16x16x32_bf16 v[54:57], v[158:161], v[234:237], v[54:57]
	v_mfma_f32_16x16x32_bf16 v[38:41], v[158:161], v[242:245], v[38:41]
	v_mfma_f32_16x16x32_bf16 v[38:41], v[162:165], v[246:249], v[38:41]
	v_mfma_f32_16x16x32_bf16 v[30:33], v[174:177], v[246:249], v[30:33]
	v_mfma_f32_16x16x32_bf16 v[30:33], v[166:169], v[242:245], v[30:33]
	v_mfma_f32_16x16x32_bf16 v[18:21], v[178:181], v[242:245], v[18:21]
	v_mfma_f32_16x16x32_bf16 v[18:21], v[182:185], v[246:249], v[18:21]
	v_mfma_f32_16x16x32_bf16 v[10:13], v[190:193], v[246:249], v[10:13]
	v_mfma_f32_16x16x32_bf16 v[10:13], v[186:189], v[242:245], v[10:13]
	v_mfma_f32_16x16x32_bf16 v[2:5], v[186:189], v[250:253], v[2:5]
	v_mfma_f32_16x16x32_bf16 v[2:5], v[190:193], v[142:145], v[2:5]
	v_mfma_f32_16x16x32_bf16 v[6:9], v[182:185], v[142:145], v[6:9]
	v_mfma_f32_16x16x32_bf16 v[6:9], v[178:181], v[250:253], v[6:9]
	v_mfma_f32_16x16x32_bf16 v[14:17], v[166:169], v[250:253], v[14:17]
	v_mfma_f32_16x16x32_bf16 v[14:17], v[174:177], v[142:145], v[14:17]
	v_mfma_f32_16x16x32_bf16 v[22:25], v[162:165], v[142:145], v[22:25]
	v_mfma_f32_16x16x32_bf16 v[22:25], v[158:161], v[250:253], v[22:25]
	s_waitcnt vmcnt(0)
	s_barrier
	s_add_i32 s57, s57, 1
; #define PG8_STAGE(bufoff, gbase, voff) do { _Pragma("unroll") for (int _i = 0; _i < 2; ++_i) \
;         __builtin_amdgcn_global_load_lds((const unsigned*)((const char*)(gbase) + (voff)[_i]), (PG8_LAS unsigned*)(lds + (bufoff) + ldsw + _i * 8192), 16, 0, 0); } while (0)
; #define PG8_LDA(dst, b, h) do { _Pragma("unroll") for (int m = 0; m < 4; ++m) _Pragma("unroll") for (int k = 0; k < 2; ++k) dst[m][k] = *(const PG8_LAS bf16x8*)(lds + PG8_SA(b, h) + aoff + m * 2048 + k * 1024); } while (0)
; #define PG8_LDB(dst, b, h) do { _Pragma("unroll") for (int n = 0; n < 2; ++n) _Pragma("unroll") for (int k = 0; k < 2; ++k) dst[n][k] = *(const PG8_LAS bf16x8*)(lds + PG8_SB(b, h) + boff + n * 2048 + k * 1024); } while (0)
; template <class Epi, class Sched, bool ALIGN_EPI>
; __device__ __forceinline__ void gemm_phase(PG8_LAS unsigned char* lds, const Gemm g, const Sched& S, const Epi& E) {
;     ...
;         for (int t = 0; t < nt; t += 2) {
;             if constexpr (Epi::MIDK) { if (t == (nt >> 1)) E.midk(acc, cur, wr, fr); }
;             const bool last = (t == nt - 2);
;             const char* a1 = cA + (size_t)(t + 1) * kstepA;
;             const char* a2 = last ? nA : cA + (size_t)(t + 2) * kstepA; const char* b2 = last ? nB : cB + (size_t)(t + 2) * kstep;
;             const char* a3 = a2 + kstepA; const char* b3 = b2 + kstep;
;             PG8_LDB(B0, 0, 0); PG8_LDB(B1, 0, 1); PG8_SCHED; PG8_LDA(At, 0, 0); PG8_STAGE(PG8_SA(1, 1), a1 + hstepA, voffA);
;             PG8_WAIT_V(8); PG8_WAIT_L(0); PG8_BAR; PG8_MMA(0, 0, At, B0); PG8_MMA(0, 1, At, B1); PG8_BAR; PG8_SCHED;
;             PG8_LDA(At, 0, 1); PG8_STAGE(PG8_SB(0, 0), b2, voffB); PG8_STAGE(PG8_SB(0, 1), b2 + hstepB, voffB); PG8_STAGE(PG8_SA(0, 0), a2, voffA);
;             PG8_WAIT_V(8); PG8_WAIT_L(0); PG8_BAR; PG8_MMA(1, 0, At, B0); PG8_MMA(1, 1, At, B1); PG8_BAR; PG8_SCHED;
;             PG8_LDB(B0, 1, 0); PG8_LDB(B1, 1, 1); PG8_SCHED; PG8_LDA(At, 1, 0); PG8_STAGE(PG8_SA(0, 1), a2 + hstepA, voffA);
;             PG8_WAIT_V(8); PG8_WAIT_L(0); PG8_BAR; PG8_MMA(0, 0, At, B0); PG8_MMA(0, 1, At, B1); PG8_BAR; PG8_SCHED;
;             PG8_LDA(At, 1, 1); PG8_STAGE(PG8_SB(1, 0), b3, voffB); PG8_STAGE(PG8_SB(1, 1), b3 + hstepB, voffB); PG8_STAGE(PG8_SA(1, 0), a3, voffA);
;             PG8_WAIT_V(8); PG8_WAIT_L(0); PG8_BAR; PG8_MMA(1, 0, At, B0); PG8_MMA(1, 1, At, B1); PG8_BAR; PG8_SCHED;
.Lp9k_A_loop:
	ds_read_b128 v[194:197], v157 offset:0
	ds_read_b128 v[198:201], v157 offset:1024
	s_add_i32 m0, s60, 0x18000
	s_nop 0
	global_load_lds_dwordx4 v132, s[28:29]
	ds_read_b128 v[202:205], v157 offset:2048
	ds_read_b128 v[206:209], v157 offset:3072
	s_add_i32 m0, s60, 0x1a000
	s_nop 0
	global_load_lds_dwordx4 v136, s[28:29]
	ds_read_b128 v[210:213], v157 offset:4096
	ds_read_b128 v[214:217], v157 offset:5120
	s_add_u32 s30, s28, 0x58000
	s_addc_u32 s31, s29, 0
	s_add_i32 m0, s60, 0x19000
	s_nop 0
	global_load_lds_dwordx4 v132, s[30:31]
	ds_read_b128 v[218:221], v157 offset:6144
	ds_read_b128 v[222:225], v157 offset:7168
	s_add_i32 m0, s60, 0x1b000
	s_nop 0
	global_load_lds_dwordx4 v136, s[30:31]
	ds_read_b128 v[158:161], v155 offset:0
	ds_read_b128 v[162:165], v155 offset:1024
	s_add_u32 s30, s28, 0x160000
	s_addc_u32 s31, s29, 0
	s_add_i32 m0, s60, 0x1c000
	s_nop 0
	global_load_lds_dwordx4 v132, s[30:31]
	ds_read_b128 v[166:169], v155 offset:2048
	ds_read_b128 v[174:177], v155 offset:3072
	s_add_i32 m0, s60, 0x1e000
	s_nop 0
	global_load_lds_dwordx4 v136, s[30:31]
	ds_read_b128 v[178:181], v155 offset:16384
	ds_read_b128 v[182:185], v155 offset:17408
	s_add_u32 s30, s28, 0x1b8000
	s_addc_u32 s31, s29, 0
	s_add_i32 m0, s60, 0x1d000
	s_nop 0
	global_load_lds_dwordx4 v132, s[30:31]
	ds_read_b128 v[186:189], v155 offset:18432
	ds_read_b128 v[190:193], v155 offset:19456
	s_add_i32 m0, s60, 0x1f000
	s_nop 0
	global_load_lds_dwordx4 v136, s[30:31]
	ds_read_b128 v[226:229], v157 offset:16384
	ds_read_b128 v[230:233], v157 offset:17408
	ds_read_b128 v[234:237], v157 offset:18432
	ds_read_b128 v[238:241], v157 offset:19456
	ds_read_b128 v[242:245], v157 offset:20480
	ds_read_b128 v[246:249], v157 offset:21504
	ds_read_b128 v[250:253], v157 offset:22528
	ds_read_b128 v[142:145], v157 offset:23552
	s_add_u32 s28, s28, 0x80
	s_addc_u32 s29, s29, 0
	s_waitcnt vmcnt(8) lgkmcnt(0)
	s_barrier
	v_mfma_f32_16x16x32_bf16 v[126:129], v[158:161], v[194:197], v[126:129]
	v_mfma_f32_16x16x32_bf16 v[126:129], v[162:165], v[198:201], v[126:129]
	v_mfma_f32_16x16x32_bf16 v[122:125], v[174:177], v[198:201], v[122:125]
	v_mfma_f32_16x16x32_bf16 v[122:125], v[166:169], v[194:197], v[122:125]
	v_mfma_f32_16x16x32_bf16 v[114:117], v[178:181], v[194:197], v[114:117]
	v_mfma_f32_16x16x32_bf16 v[114:117], v[182:185], v[198:201], v[114:117]
	v_mfma_f32_16x16x32_bf16 v[106:109], v[190:193], v[198:201], v[106:109]
	v_mfma_f32_16x16x32_bf16 v[106:109], v[186:189], v[194:197], v[106:109]
	v_mfma_f32_16x16x32_bf16 v[90:93], v[186:189], v[202:205], v[90:93]
	v_mfma_f32_16x16x32_bf16 v[90:93], v[190:193], v[206:209], v[90:93]
	v_mfma_f32_16x16x32_bf16 v[98:101], v[182:185], v[206:209], v[98:101]
	v_mfma_f32_16x16x32_bf16 v[98:101], v[178:181], v[202:205], v[98:101]
	v_mfma_f32_16x16x32_bf16 v[110:113], v[166:169], v[202:205], v[110:113]
	v_mfma_f32_16x16x32_bf16 v[110:113], v[174:177], v[206:209], v[110:113]
	v_mfma_f32_16x16x32_bf16 v[118:121], v[162:165], v[206:209], v[118:121]
	v_mfma_f32_16x16x32_bf16 v[118:121], v[158:161], v[202:205], v[118:121]
	v_mfma_f32_16x16x32_bf16 v[102:105], v[158:161], v[210:213], v[102:105]
	v_mfma_f32_16x16x32_bf16 v[102:105], v[162:165], v[214:217], v[102:105]
	v_mfma_f32_16x16x32_bf16 v[94:97], v[174:177], v[214:217], v[94:97]
	v_mfma_f32_16x16x32_bf16 v[94:97], v[166:169], v[210:213], v[94:97]
	v_mfma_f32_16x16x32_bf16 v[82:85], v[178:181], v[210:213], v[82:85]
	v_mfma_f32_16x16x32_bf16 v[82:85], v[182:185], v[214:217], v[82:85]
	v_mfma_f32_16x16x32_bf16 v[74:77], v[190:193], v[214:217], v[74:77]
	v_mfma_f32_16x16x32_bf16 v[74:77], v[186:189], v[210:213], v[74:77]
	v_mfma_f32_16x16x32_bf16 v[66:69], v[186:189], v[218:221], v[66:69]
	v_mfma_f32_16x16x32_bf16 v[66:69], v[190:193], v[222:225], v[66:69]
	v_mfma_f32_16x16x32_bf16 v[70:73], v[182:185], v[222:225], v[70:73]
	v_mfma_f32_16x16x32_bf16 v[70:73], v[178:181], v[218:221], v[70:73]
	v_mfma_f32_16x16x32_bf16 v[78:81], v[166:169], v[218:221], v[78:81]
	v_mfma_f32_16x16x32_bf16 v[78:81], v[174:177], v[222:225], v[78:81]
	v_mfma_f32_16x16x32_bf16 v[86:89], v[162:165], v[222:225], v[86:89]
	v_mfma_f32_16x16x32_bf16 v[86:89], v[158:161], v[218:221], v[86:89]
	v_mfma_f32_16x16x32_bf16 v[62:65], v[158:161], v[226:229], v[62:65]
	v_mfma_f32_16x16x32_bf16 v[62:65], v[162:165], v[230:233], v[62:65]
	v_mfma_f32_16x16x32_bf16 v[58:61], v[174:177], v[230:233], v[58:61]
	v_mfma_f32_16x16x32_bf16 v[58:61], v[166:169], v[226:229], v[58:61]
	v_mfma_f32_16x16x32_bf16 v[50:53], v[178:181], v[226:229], v[50:53]
	v_mfma_f32_16x16x32_bf16 v[50:53], v[182:185], v[230:233], v[50:53]
	v_mfma_f32_16x16x32_bf16 v[42:45], v[190:193], v[230:233], v[42:45]
	v_mfma_f32_16x16x32_bf16 v[42:45], v[186:189], v[226:229], v[42:45]
	v_mfma_f32_16x16x32_bf16 v[26:29], v[186:189], v[234:237], v[26:29]
	v_mfma_f32_16x16x32_bf16 v[26:29], v[190:193], v[238:241], v[26:29]
	v_mfma_f32_16x16x32_bf16 v[34:37], v[182:185], v[238:241], v[34:37]
	v_mfma_f32_16x16x32_bf16 v[34:37], v[178:181], v[234:237], v[34:37]
	v_mfma_f32_16x16x32_bf16 v[46:49], v[166:169], v[234:237], v[46:49]
	v_mfma_f32_16x16x32_bf16 v[46:49], v[174:177], v[238:241], v[46:49]
	v_mfma_f32_16x16x32_bf16 v[54:57], v[162:165], v[238:241], v[54:57]
	v_mfma_f32_16x16x32_bf16 v[54:57], v[158:161], v[234:237], v[54:57]
	v_mfma_f32_16x16x32_bf16 v[38:41], v[158:161], v[242:245], v[38:41]
	v_mfma_f32_16x16x32_bf16 v[38:41], v[162:165], v[246:249], v[38:41]
	v_mfma_f32_16x16x32_bf16 v[30:33], v[174:177], v[246:249], v[30:33]
	v_mfma_f32_16x16x32_bf16 v[30:33], v[166:169], v[242:245], v[30:33]
	v_mfma_f32_16x16x32_bf16 v[18:21], v[178:181], v[242:245], v[18:21]
	v_mfma_f32_16x16x32_bf16 v[18:21], v[182:185], v[246:249], v[18:21]
	v_mfma_f32_16x16x32_bf16 v[10:13], v[190:193], v[246:249], v[10:13]
	v_mfma_f32_16x16x32_bf16 v[10:13], v[186:189], v[242:245], v[10:13]
	v_mfma_f32_16x16x32_bf16 v[2:5], v[186:189], v[250:253], v[2:5]
	v_mfma_f32_16x16x32_bf16 v[2:5], v[190:193], v[142:145], v[2:5]
	v_mfma_f32_16x16x32_bf16 v[6:9], v[182:185], v[142:145], v[6:9]
	v_mfma_f32_16x16x32_bf16 v[6:9], v[178:181], v[250:253], v[6:9]
	v_mfma_f32_16x16x32_bf16 v[14:17], v[166:169], v[250:253], v[14:17]
	v_mfma_f32_16x16x32_bf16 v[14:17], v[174:177], v[142:145], v[14:17]
	v_mfma_f32_16x16x32_bf16 v[22:25], v[162:165], v[142:145], v[22:25]
	v_mfma_f32_16x16x32_bf16 v[22:25], v[158:161], v[250:253], v[22:25]
	s_waitcnt vmcnt(0)
	s_barrier
; #define PG8_STAGE(bufoff, gbase, voff) do { _Pragma("unroll") for (int _i = 0; _i < 2; ++_i) \
;         __builtin_amdgcn_global_load_lds((const unsigned*)((const char*)(gbase) + (voff)[_i]), (PG8_LAS unsigned*)(lds + (bufoff) + ldsw + _i * 8192), 16, 0, 0); } while (0)
; #define PG8_LDA(dst, b, h) do { _Pragma("unroll") for (int m = 0; m < 4; ++m) _Pragma("unroll") for (int k = 0; k < 2; ++k) dst[m][k] = *(const PG8_LAS bf16x8*)(lds + PG8_SA(b, h) + aoff + m * 2048 + k * 1024); } while (0)
; #define PG8_LDB(dst, b, h) do { _Pragma("unroll") for (int n = 0; n < 2; ++n) _Pragma("unroll") for (int k = 0; k < 2; ++k) dst[n][k] = *(const PG8_LAS bf16x8*)(lds + PG8_SB(b, h) + boff + n * 2048 + k * 1024); } while (0)
; #define PG8_MMA(ai, bj, At, Bt) do { __builtin_amdgcn_s_setprio(1); _Pragma("unroll") for (int m = 0; m < 4; ++m) _Pragma("unroll") for (int n = 0; n < 2; ++n) _Pragma("unroll") for (int k = 0; k < 2; ++k) \
;         acc[ai][bj][m][n] = __builtin_amdgcn_mfma_f32_16x16x32_bf16(Bt[n][k], At[m][k], acc[ai][bj][m][n], 0, 0, 0); __builtin_amdgcn_s_setprio(0); } while (0)
; #define PG8_WAIT_V(n) asm volatile("s_waitcnt vmcnt(" #n ")" ::: "memory")
; template <class Epi, class Sched, bool ALIGN_EPI>
; __device__ __forceinline__ void gemm_phase(PG8_LAS unsigned char* lds, const Gemm g, const Sched& S, const Epi& E) {
;     ...
;             PG8_LDB(B0, 0, 0); PG8_LDB(B1, 0, 1); PG8_SCHED; PG8_LDA(At, 0, 0); PG8_STAGE(PG8_SA(1, 1), a1 + hstepA, voffA);
;             PG8_WAIT_V(8); PG8_WAIT_L(0); PG8_BAR; PG8_MMA(0, 0, At, B0); PG8_MMA(0, 1, At, B1); PG8_BAR; PG8_SCHED;
;             PG8_LDA(At, 0, 1); PG8_STAGE(PG8_SB(0, 0), b2, voffB); PG8_STAGE(PG8_SB(0, 1), b2 + hstepB, voffB); PG8_STAGE(PG8_SA(0, 0), a2, voffA);
;             PG8_WAIT_V(8); PG8_WAIT_L(0); PG8_BAR; PG8_MMA(1, 0, At, B0); PG8_MMA(1, 1, At, B1); PG8_BAR; PG8_SCHED;
;             PG8_LDB(B0, 1, 0); PG8_LDB(B1, 1, 1); PG8_SCHED; PG8_LDA(At, 1, 0); PG8_STAGE(PG8_SA(0, 1), a2 + hstepA, voffA);
;             PG8_WAIT_V(8); PG8_WAIT_L(0); PG8_BAR; PG8_MMA(0, 0, At, B0); PG8_MMA(0, 1, At, B1); PG8_BAR; PG8_SCHED;
;             PG8_LDA(At, 1, 1); PG8_STAGE(PG8_SB(1, 0), b3, voffB); PG8_STAGE(PG8_SB(1, 1), b3 + hstepB, voffB); PG8_STAGE(PG8_SA(1, 0), a3, voffA);
;             PG8_WAIT_V(8); PG8_WAIT_L(0); PG8_BAR; PG8_MMA(1, 0, At, B0); PG8_MMA(1, 1, At, B1); PG8_BAR; PG8_SCHED;
	ds_read_b128 v[194:197], v157 offset:32768
	ds_read_b128 v[198:201], v157 offset:33792
	s_cmp_eq_u32 s57, 43
	s_cselect_b32 s28, s58, s28
	s_cselect_b32 s29, s59, s29
	s_add_i32 m0, s60, 0x10000
	s_nop 0
	global_load_lds_dwordx4 v132, s[28:29]
	ds_read_b128 v[202:205], v157 offset:34816
	ds_read_b128 v[206:209], v157 offset:35840
	s_add_i32 m0, s60, 0x12000
	s_nop 0
	global_load_lds_dwordx4 v136, s[28:29]
	ds_read_b128 v[210:213], v157 offset:36864
	ds_read_b128 v[214:217], v157 offset:37888
	s_add_u32 s30, s28, 0x58000
	s_addc_u32 s31, s29, 0
	s_add_i32 m0, s60, 0x11000
	s_nop 0
	global_load_lds_dwordx4 v132, s[30:31]
	ds_read_b128 v[218:221], v157 offset:38912
	ds_read_b128 v[222:225], v157 offset:39936
	s_add_i32 m0, s60, 0x13000
	s_nop 0
	global_load_lds_dwordx4 v136, s[30:31]
	ds_read_b128 v[158:161], v155 offset:32768
	ds_read_b128 v[162:165], v155 offset:33792
	s_add_u32 s30, s28, 0x160000
	s_addc_u32 s31, s29, 0
	s_add_i32 m0, s60, 0x14000
	s_nop 0
	global_load_lds_dwordx4 v132, s[30:31]
	ds_read_b128 v[166:169], v155 offset:34816
	ds_read_b128 v[174:177], v155 offset:35840
	s_add_i32 m0, s60, 0x16000
	s_nop 0
	global_load_lds_dwordx4 v136, s[30:31]
	ds_read_b128 v[178:181], v155 offset:49152
	ds_read_b128 v[182:185], v155 offset:50176
	s_add_u32 s30, s28, 0x1b8000
	s_addc_u32 s31, s29, 0
	s_add_i32 m0, s60, 0x15000
	s_nop 0
	global_load_lds_dwordx4 v132, s[30:31]
	ds_read_b128 v[186:189], v155 offset:51200
	ds_read_b128 v[190:193], v155 offset:52224
	s_add_i32 m0, s60, 0x17000
	s_nop 0
	global_load_lds_dwordx4 v136, s[30:31]
	ds_read_b128 v[226:229], v157 offset:49152
	ds_read_b128 v[230:233], v157 offset:50176
	ds_read_b128 v[234:237], v157 offset:51200
	ds_read_b128 v[238:241], v157 offset:52224
	ds_read_b128 v[242:245], v157 offset:53248
	ds_read_b128 v[246:249], v157 offset:54272
	ds_read_b128 v[250:253], v157 offset:55296
	ds_read_b128 v[142:145], v157 offset:56320
	s_add_u32 s28, s28, 0x80
	s_addc_u32 s29, s29, 0
	s_waitcnt vmcnt(8) lgkmcnt(0)
	s_barrier
; #define PG8_STAGE(bufoff, gbase, voff) do { _Pragma("unroll") for (int _i = 0; _i < 2; ++_i) \
;         __builtin_amdgcn_global_load_lds((const unsigned*)((const char*)(gbase) + (voff)[_i]), (PG8_LAS unsigned*)(lds + (bufoff) + ldsw + _i * 8192), 16, 0, 0); } while (0)
; #define PG8_LDA(dst, b, h) do { _Pragma("unroll") for (int m = 0; m < 4; ++m) _Pragma("unroll") for (int k = 0; k < 2; ++k) dst[m][k] = *(const PG8_LAS bf16x8*)(lds + PG8_SA(b, h) + aoff + m * 2048 + k * 1024); } while (0)
; #define PG8_LDB(dst, b, h) do { _Pragma("unroll") for (int n = 0; n < 2; ++n) _Pragma("unroll") for (int k = 0; k < 2; ++k) dst[n][k] = *(const PG8_LAS bf16x8*)(lds + PG8_SB(b, h) + boff + n * 2048 + k * 1024); } while (0)
; #define PG8_MMA(ai, bj, At, Bt) do { __builtin_amdgcn_s_setprio(1); _Pragma("unroll") for (int m = 0; m < 4; ++m) _Pragma("unroll") for (int n = 0; n < 2; ++n) _Pragma("unroll") for (int k = 0; k < 2; ++k) \
;         acc[ai][bj][m][n] = __builtin_amdgcn_mfma_f32_16x16x32_bf16(Bt[n][k], At[m][k], acc[ai][bj][m][n], 0, 0, 0); __builtin_amdgcn_s_setprio(0); } while (0)
; #define PG8_WAIT_V(n) asm volatile("s_waitcnt vmcnt(" #n ")" ::: "memory")
; template <class Epi, class Sched, bool ALIGN_EPI>
; __device__ __forceinline__ void gemm_phase(PG8_LAS unsigned char* lds, const Gemm g, const Sched& S, const Epi& E) {
;     ...
;             PG8_LDB(B0, 0, 0); PG8_LDB(B1, 0, 1); PG8_SCHED; PG8_LDA(At, 0, 0); PG8_STAGE(PG8_SA(1, 1), a1 + hstepA, voffA);
;             PG8_WAIT_V(8); PG8_WAIT_L(0); PG8_BAR; PG8_MMA(0, 0, At, B0); PG8_MMA(0, 1, At, B1); PG8_BAR; PG8_SCHED;
;             PG8_LDA(At, 0, 1); PG8_STAGE(PG8_SB(0, 0), b2, voffB); PG8_STAGE(PG8_SB(0, 1), b2 + hstepB, voffB); PG8_STAGE(PG8_SA(0, 0), a2, voffA);
;             PG8_WAIT_V(8); PG8_WAIT_L(0); PG8_BAR; PG8_MMA(1, 0, At, B0); PG8_MMA(1, 1, At, B1); PG8_BAR; PG8_SCHED;
;             PG8_LDB(B0, 1, 0); PG8_LDB(B1, 1, 1); PG8_SCHED; PG8_LDA(At, 1, 0); PG8_STAGE(PG8_SA(0, 1), a2 + hstepA, voffA);
;             PG8_WAIT_V(8); PG8_WAIT_L(0); PG8_BAR; PG8_MMA(0, 0, At, B0); PG8_MMA(0, 1, At, B1); PG8_BAR; PG8_SCHED;
;             PG8_LDA(At, 1, 1); PG8_STAGE(PG8_SB(1, 0), b3, voffB); PG8_STAGE(PG8_SB(1, 1), b3 + hstepB, voffB); PG8_STAGE(PG8_SA(1, 0), a3, voffA);
;             PG8_WAIT_V(8); PG8_WAIT_L(0); PG8_BAR; PG8_MMA(1, 0, At, B0); PG8_MMA(1, 1, At, B1); PG8_BAR; PG8_SCHED;
;         }
	v_mfma_f32_16x16x32_bf16 v[126:129], v[158:161], v[194:197], v[126:129]
	v_mfma_f32_16x16x32_bf16 v[126:129], v[162:165], v[198:201], v[126:129]
	v_mfma_f32_16x16x32_bf16 v[122:125], v[174:177], v[198:201], v[122:125]
	v_mfma_f32_16x16x32_bf16 v[122:125], v[166:169], v[194:197], v[122:125]
	v_mfma_f32_16x16x32_bf16 v[114:117], v[178:181], v[194:197], v[114:117]
	v_mfma_f32_16x16x32_bf16 v[114:117], v[182:185], v[198:201], v[114:117]
	v_mfma_f32_16x16x32_bf16 v[106:109], v[190:193], v[198:201], v[106:109]
	v_mfma_f32_16x16x32_bf16 v[106:109], v[186:189], v[194:197], v[106:109]
	v_mfma_f32_16x16x32_bf16 v[90:93], v[186:189], v[202:205], v[90:93]
	v_mfma_f32_16x16x32_bf16 v[90:93], v[190:193], v[206:209], v[90:93]
	v_mfma_f32_16x16x32_bf16 v[98:101], v[182:185], v[206:209], v[98:101]
	v_mfma_f32_16x16x32_bf16 v[98:101], v[178:181], v[202:205], v[98:101]
	v_mfma_f32_16x16x32_bf16 v[110:113], v[166:169], v[202:205], v[110:113]
	v_mfma_f32_16x16x32_bf16 v[110:113], v[174:177], v[206:209], v[110:113]
	v_mfma_f32_16x16x32_bf16 v[118:121], v[162:165], v[206:209], v[118:121]
	v_mfma_f32_16x16x32_bf16 v[118:121], v[158:161], v[202:205], v[118:121]
	v_mfma_f32_16x16x32_bf16 v[102:105], v[158:161], v[210:213], v[102:105]
	v_mfma_f32_16x16x32_bf16 v[102:105], v[162:165], v[214:217], v[102:105]
	v_mfma_f32_16x16x32_bf16 v[94:97], v[174:177], v[214:217], v[94:97]
	v_mfma_f32_16x16x32_bf16 v[94:97], v[166:169], v[210:213], v[94:97]
	v_mfma_f32_16x16x32_bf16 v[82:85], v[178:181], v[210:213], v[82:85]
	v_mfma_f32_16x16x32_bf16 v[82:85], v[182:185], v[214:217], v[82:85]
	v_mfma_f32_16x16x32_bf16 v[74:77], v[190:193], v[214:217], v[74:77]
	v_mfma_f32_16x16x32_bf16 v[74:77], v[186:189], v[210:213], v[74:77]
	v_mfma_f32_16x16x32_bf16 v[66:69], v[186:189], v[218:221], v[66:69]
	v_mfma_f32_16x16x32_bf16 v[66:69], v[190:193], v[222:225], v[66:69]
	v_mfma_f32_16x16x32_bf16 v[70:73], v[182:185], v[222:225], v[70:73]
	v_mfma_f32_16x16x32_bf16 v[70:73], v[178:181], v[218:221], v[70:73]
	v_mfma_f32_16x16x32_bf16 v[78:81], v[166:169], v[218:221], v[78:81]
	v_mfma_f32_16x16x32_bf16 v[78:81], v[174:177], v[222:225], v[78:81]
	v_mfma_f32_16x16x32_bf16 v[86:89], v[162:165], v[222:225], v[86:89]
	v_mfma_f32_16x16x32_bf16 v[86:89], v[158:161], v[218:221], v[86:89]
	v_mfma_f32_16x16x32_bf16 v[62:65], v[158:161], v[226:229], v[62:65]
	v_mfma_f32_16x16x32_bf16 v[62:65], v[162:165], v[230:233], v[62:65]
	v_mfma_f32_16x16x32_bf16 v[58:61], v[174:177], v[230:233], v[58:61]
	v_mfma_f32_16x16x32_bf16 v[58:61], v[166:169], v[226:229], v[58:61]
	v_mfma_f32_16x16x32_bf16 v[50:53], v[178:181], v[226:229], v[50:53]
	v_mfma_f32_16x16x32_bf16 v[50:53], v[182:185], v[230:233], v[50:53]
	v_mfma_f32_16x16x32_bf16 v[42:45], v[190:193], v[230:233], v[42:45]
	v_mfma_f32_16x16x32_bf16 v[42:45], v[186:189], v[226:229], v[42:45]
	v_mfma_f32_16x16x32_bf16 v[26:29], v[186:189], v[234:237], v[26:29]
	v_mfma_f32_16x16x32_bf16 v[26:29], v[190:193], v[238:241], v[26:29]
	v_mfma_f32_16x16x32_bf16 v[34:37], v[182:185], v[238:241], v[34:37]
	v_mfma_f32_16x16x32_bf16 v[34:37], v[178:181], v[234:237], v[34:37]
	v_mfma_f32_16x16x32_bf16 v[46:49], v[166:169], v[234:237], v[46:49]
	v_mfma_f32_16x16x32_bf16 v[46:49], v[174:177], v[238:241], v[46:49]
	v_mfma_f32_16x16x32_bf16 v[54:57], v[162:165], v[238:241], v[54:57]
	v_mfma_f32_16x16x32_bf16 v[54:57], v[158:161], v[234:237], v[54:57]
	v_mfma_f32_16x16x32_bf16 v[38:41], v[158:161], v[242:245], v[38:41]
	v_mfma_f32_16x16x32_bf16 v[38:41], v[162:165], v[246:249], v[38:41]
	v_mfma_f32_16x16x32_bf16 v[30:33], v[174:177], v[246:249], v[30:33]
	v_mfma_f32_16x16x32_bf16 v[30:33], v[166:169], v[242:245], v[30:33]
	v_mfma_f32_16x16x32_bf16 v[18:21], v[178:181], v[242:245], v[18:21]
	v_mfma_f32_16x16x32_bf16 v[18:21], v[182:185], v[246:249], v[18:21]
	v_mfma_f32_16x16x32_bf16 v[10:13], v[190:193], v[246:249], v[10:13]
	v_mfma_f32_16x16x32_bf16 v[10:13], v[186:189], v[242:245], v[10:13]
	v_mfma_f32_16x16x32_bf16 v[2:5], v[186:189], v[250:253], v[2:5]
	v_mfma_f32_16x16x32_bf16 v[2:5], v[190:193], v[142:145], v[2:5]
	v_mfma_f32_16x16x32_bf16 v[6:9], v[182:185], v[142:145], v[6:9]
	v_mfma_f32_16x16x32_bf16 v[6:9], v[178:181], v[250:253], v[6:9]
	v_mfma_f32_16x16x32_bf16 v[14:17], v[166:169], v[250:253], v[14:17]
	v_mfma_f32_16x16x32_bf16 v[14:17], v[174:177], v[142:145], v[14:17]
	v_mfma_f32_16x16x32_bf16 v[22:25], v[162:165], v[142:145], v[22:25]
	v_mfma_f32_16x16x32_bf16 v[22:25], v[158:161], v[250:253], v[22:25]
	s_waitcnt vmcnt(0)
	s_barrier
	s_add_i32 s57, s57, 1
	s_cmp_lt_u32 s57, 44
	s_cbranch_scc1 .Lp9k_A_loop
	ds_read_b128 v[194:197], v157 offset:0
	ds_read_b128 v[198:201], v157 offset:1024
	s_add_i32 m0, s60, 0x18000
	s_nop 0
	global_load_lds_dwordx4 v132, s[28:29]
	ds_read_b128 v[202:205], v157 offset:2048
	ds_read_b128 v[206:209], v157 offset:3072
	s_add_i32 m0, s60, 0x1a000
	s_nop 0
	global_load_lds_dwordx4 v136, s[28:29]
	ds_read_b128 v[210:213], v157 offset:4096
	ds_read_b128 v[214:217], v157 offset:5120
	s_add_u32 s30, s28, 0x58000
	s_addc_u32 s31, s29, 0
	s_add_i32 m0, s60, 0x19000
	s_nop 0
	global_load_lds_dwordx4 v132, s[30:31]
	ds_read_b128 v[218:221], v157 offset:6144
	ds_read_b128 v[222:225], v157 offset:7168
	s_add_i32 m0, s60, 0x1b000
	s_nop 0
	global_load_lds_dwordx4 v136, s[30:31]
	ds_read_b128 v[166:169], v155 offset:2048
	ds_read_b128 v[174:177], v155 offset:3072
	s_add_u32 s30, s28, 0x160000
	s_addc_u32 s31, s29, 0
	s_add_i32 m0, s60, 0x1c000
	s_nop 0
	global_load_lds_dwordx4 v132, s[30:31]
	ds_read_b128 v[178:181], v155 offset:16384
	ds_read_b128 v[182:185], v155 offset:17408
	s_add_i32 m0, s60, 0x1e000
	s_nop 0
	global_load_lds_dwordx4 v136, s[30:31]
	ds_read_b128 v[186:189], v155 offset:18432
	ds_read_b128 v[190:193], v155 offset:19456
	s_add_u32 s30, s28, 0x1b8000
	s_addc_u32 s31, s29, 0
	s_add_i32 m0, s60, 0x1d000
	s_nop 0
	global_load_lds_dwordx4 v132, s[30:31]
	ds_read_b128 v[226:229], v157 offset:16384
	ds_read_b128 v[230:233], v157 offset:17408
	s_add_i32 m0, s60, 0x1f000
	s_nop 0
	global_load_lds_dwordx4 v136, s[30:31]
	ds_read_b128 v[234:237], v157 offset:18432
	ds_read_b128 v[238:241], v157 offset:19456
	ds_read_b128 v[242:245], v157 offset:20480
	ds_read_b128 v[246:249], v157 offset:21504
	ds_read_b128 v[250:253], v157 offset:22528
	s_add_u32 s28, s28, 0x80
	s_addc_u32 s29, s29, 0
	s_branch .Lp9k_done

; #define PG8_STAGE(bufoff, gbase, voff) do { _Pragma("unroll") for (int _i = 0; _i < 2; ++_i) \
;         __builtin_amdgcn_global_load_lds((const unsigned*)((const char*)(gbase) + (voff)[_i]), (PG8_LAS unsigned*)(lds + (bufoff) + ldsw + _i * 8192), 16, 0, 0); } while (0)
; #define PG8_LDA(dst, b, h) do { _Pragma("unroll") for (int m = 0; m < 4; ++m) _Pragma("unroll") for (int k = 0; k < 2; ++k) dst[m][k] = *(const PG8_LAS bf16x8*)(lds + PG8_SA(b, h) + aoff + m * 2048 + k * 1024); } while (0)
; #define PG8_LDB(dst, b, h) do { _Pragma("unroll") for (int n = 0; n < 2; ++n) _Pragma("unroll") for (int k = 0; k < 2; ++k) dst[n][k] = *(const PG8_LAS bf16x8*)(lds + PG8_SB(b, h) + boff + n * 2048 + k * 1024); } while (0)
; #define PG8_MMA(ai, bj, At, Bt) do { __builtin_amdgcn_s_setprio(1); _Pragma("unroll") for (int m = 0; m < 4; ++m) _Pragma("unroll") for (int n = 0; n < 2; ++n) _Pragma("unroll") for (int k = 0; k < 2; ++k) \
;         acc[ai][bj][m][n] = __builtin_amdgcn_mfma_f32_16x16x32_bf16(Bt[n][k], At[m][k], acc[ai][bj][m][n], 0, 0, 0); __builtin_amdgcn_s_setprio(0); } while (0)
; #define PG8_WAIT_V(n) asm volatile("s_waitcnt vmcnt(" #n ")" ::: "memory")
; template <class Epi, class Sched, bool ALIGN_EPI>
; __device__ __forceinline__ void gemm_phase(PG8_LAS unsigned char* lds, const Gemm g, const Sched& S, const Epi& E) {
;     ...
;             PG8_LDB(B0, 0, 0); PG8_LDB(B1, 0, 1); PG8_SCHED; PG8_LDA(At, 0, 0); PG8_STAGE(PG8_SA(1, 1), a1 + hstepA, voffA);
;             PG8_WAIT_V(8); PG8_WAIT_L(0); PG8_BAR; PG8_MMA(0, 0, At, B0); PG8_MMA(0, 1, At, B1); PG8_BAR; PG8_SCHED;
;             PG8_LDA(At, 0, 1); PG8_STAGE(PG8_SB(0, 0), b2, voffB); PG8_STAGE(PG8_SB(0, 1), b2 + hstepB, voffB); PG8_STAGE(PG8_SA(0, 0), a2, voffA);
;             PG8_WAIT_V(8); PG8_WAIT_L(0); PG8_BAR; PG8_MMA(1, 0, At, B0); PG8_MMA(1, 1, At, B1); PG8_BAR; PG8_SCHED;
;             PG8_LDB(B0, 1, 0); PG8_LDB(B1, 1, 1); PG8_SCHED; PG8_LDA(At, 1, 0); PG8_STAGE(PG8_SA(0, 1), a2 + hstepA, voffA);
;             PG8_WAIT_V(8); PG8_WAIT_L(0); PG8_BAR; PG8_MMA(0, 0, At, B0); PG8_MMA(0, 1, At, B1); PG8_BAR; PG8_SCHED;
;             PG8_LDA(At, 1, 1); PG8_STAGE(PG8_SB(1, 0), b3, voffB); PG8_STAGE(PG8_SB(1, 1), b3 + hstepB, voffB); PG8_STAGE(PG8_SA(1, 0), a3, voffA);
;             PG8_WAIT_V(8); PG8_WAIT_L(0); PG8_BAR; PG8_MMA(1, 0, At, B0); PG8_MMA(1, 1, At, B1); PG8_BAR; PG8_SCHED;
.Lp9k_B_nobar:
	ds_read_b128 v[194:197], v157 offset:0
	ds_read_b128 v[198:201], v157 offset:1024
	s_add_i32 m0, s60, 0xa000
	s_nop 0
	global_load_lds_dwordx4 v134, s[28:29]
	ds_read_b128 v[202:205], v157 offset:2048
	ds_read_b128 v[206:209], v157 offset:3072
	s_add_u32 s30, s28, 0x58000
	s_addc_u32 s31, s29, 0
	s_add_i32 m0, s60, 0xb000
	s_nop 0
	global_load_lds_dwordx4 v134, s[30:31]
	ds_read_b128 v[210:213], v157 offset:4096
	ds_read_b128 v[214:217], v157 offset:5120
	s_add_u32 s30, s28, 0x160000
	s_addc_u32 s31, s29, 0
	s_add_i32 m0, s60, 0xe000
	s_nop 0
	global_load_lds_dwordx4 v134, s[30:31]
	ds_read_b128 v[218:221], v157 offset:6144
	ds_read_b128 v[222:225], v157 offset:7168
	s_add_u32 s30, s28, 0x1b8000
	s_addc_u32 s31, s29, 0
	s_add_i32 m0, s60, 0xf000
	s_nop 0
	global_load_lds_dwordx4 v134, s[30:31]
	ds_read_b128 v[158:161], v155 offset:0
	ds_read_b128 v[162:165], v155 offset:1024
	s_add_u32 s34, s28, 0x80
	s_addc_u32 s35, s29, 0
	s_cmp_eq_u32 s57, 43
	s_cselect_b32 s34, s58, s34
	s_cselect_b32 s35, s59, s35
	s_add_i32 m0, s60, 0x0
	s_nop 0
	global_load_lds_dwordx4 v130, s[34:35]
	ds_read_b128 v[166:169], v155 offset:2048
	ds_read_b128 v[174:177], v155 offset:3072
	s_add_u32 s30, s34, 0x58000
	s_addc_u32 s31, s35, 0
	s_add_i32 m0, s60, 0x1000
	s_nop 0
	global_load_lds_dwordx4 v130, s[30:31]
	ds_read_b128 v[178:181], v155 offset:16384
	ds_read_b128 v[182:185], v155 offset:17408
	s_add_u32 s30, s34, 0x160000
	s_addc_u32 s31, s35, 0
	s_add_i32 m0, s60, 0x4000
	s_nop 0
	global_load_lds_dwordx4 v130, s[30:31]
	ds_read_b128 v[186:189], v155 offset:18432
	ds_read_b128 v[190:193], v155 offset:19456
	s_add_u32 s30, s34, 0x1b8000
	s_addc_u32 s31, s35, 0
	s_add_i32 m0, s60, 0x5000
	s_nop 0
	global_load_lds_dwordx4 v130, s[30:31]
	ds_read_b128 v[226:229], v157 offset:16384
	ds_read_b128 v[230:233], v157 offset:17408
	ds_read_b128 v[234:237], v157 offset:18432
	ds_read_b128 v[238:241], v157 offset:19456
	ds_read_b128 v[242:245], v157 offset:20480
	ds_read_b128 v[246:249], v157 offset:21504
	ds_read_b128 v[250:253], v157 offset:22528
	ds_read_b128 v[142:145], v157 offset:23552
	s_add_u32 s28, s28, 0x80
	s_addc_u32 s29, s29, 0
	s_waitcnt vmcnt(8) lgkmcnt(0)
	s_barrier
	v_mfma_f32_16x16x32_bf16 v[126:129], v[158:161], v[194:197], 0
	v_mfma_f32_16x16x32_bf16 v[126:129], v[162:165], v[198:201], v[126:129]
	v_mfma_f32_16x16x32_bf16 v[122:125], v[174:177], v[198:201], 0
	v_mfma_f32_16x16x32_bf16 v[122:125], v[166:169], v[194:197], v[122:125]
	v_mfma_f32_16x16x32_bf16 v[114:117], v[178:181], v[194:197], 0
	v_mfma_f32_16x16x32_bf16 v[114:117], v[182:185], v[198:201], v[114:117]
	v_mfma_f32_16x16x32_bf16 v[106:109], v[190:193], v[198:201], 0
	v_mfma_f32_16x16x32_bf16 v[106:109], v[186:189], v[194:197], v[106:109]
	v_mfma_f32_16x16x32_bf16 v[90:93], v[186:189], v[202:205], 0
	v_mfma_f32_16x16x32_bf16 v[90:93], v[190:193], v[206:209], v[90:93]
	v_mfma_f32_16x16x32_bf16 v[98:101], v[182:185], v[206:209], 0
	v_mfma_f32_16x16x32_bf16 v[98:101], v[178:181], v[202:205], v[98:101]
	v_mfma_f32_16x16x32_bf16 v[110:113], v[166:169], v[202:205], 0
	v_mfma_f32_16x16x32_bf16 v[110:113], v[174:177], v[206:209], v[110:113]
	v_mfma_f32_16x16x32_bf16 v[118:121], v[162:165], v[206:209], 0
	v_mfma_f32_16x16x32_bf16 v[118:121], v[158:161], v[202:205], v[118:121]
	v_mfma_f32_16x16x32_bf16 v[102:105], v[158:161], v[210:213], 0
	v_mfma_f32_16x16x32_bf16 v[102:105], v[162:165], v[214:217], v[102:105]
	v_mfma_f32_16x16x32_bf16 v[94:97], v[174:177], v[214:217], 0
	v_mfma_f32_16x16x32_bf16 v[94:97], v[166:169], v[210:213], v[94:97]
	v_mfma_f32_16x16x32_bf16 v[82:85], v[178:181], v[210:213], 0
	v_mfma_f32_16x16x32_bf16 v[82:85], v[182:185], v[214:217], v[82:85]
	v_mfma_f32_16x16x32_bf16 v[74:77], v[190:193], v[214:217], 0
	v_mfma_f32_16x16x32_bf16 v[74:77], v[186:189], v[210:213], v[74:77]
	v_mfma_f32_16x16x32_bf16 v[66:69], v[186:189], v[218:221], 0
	v_mfma_f32_16x16x32_bf16 v[66:69], v[190:193], v[222:225], v[66:69]
	v_mfma_f32_16x16x32_bf16 v[70:73], v[182:185], v[222:225], 0
	v_mfma_f32_16x16x32_bf16 v[70:73], v[178:181], v[218:221], v[70:73]
	v_mfma_f32_16x16x32_bf16 v[78:81], v[166:169], v[218:221], 0
	v_mfma_f32_16x16x32_bf16 v[78:81], v[174:177], v[222:225], v[78:81]
	v_mfma_f32_16x16x32_bf16 v[86:89], v[162:165], v[222:225], 0
	v_mfma_f32_16x16x32_bf16 v[86:89], v[158:161], v[218:221], v[86:89]
	v_mfma_f32_16x16x32_bf16 v[62:65], v[158:161], v[226:229], 0
	v_mfma_f32_16x16x32_bf16 v[62:65], v[162:165], v[230:233], v[62:65]
	v_mfma_f32_16x16x32_bf16 v[58:61], v[174:177], v[230:233], 0
	v_mfma_f32_16x16x32_bf16 v[58:61], v[166:169], v[226:229], v[58:61]
	v_mfma_f32_16x16x32_bf16 v[50:53], v[178:181], v[226:229], 0
	v_mfma_f32_16x16x32_bf16 v[50:53], v[182:185], v[230:233], v[50:53]
	v_mfma_f32_16x16x32_bf16 v[42:45], v[190:193], v[230:233], 0
	v_mfma_f32_16x16x32_bf16 v[42:45], v[186:189], v[226:229], v[42:45]
	v_mfma_f32_16x16x32_bf16 v[26:29], v[186:189], v[234:237], 0
	v_mfma_f32_16x16x32_bf16 v[26:29], v[190:193], v[238:241], v[26:29]
	v_mfma_f32_16x16x32_bf16 v[34:37], v[182:185], v[238:241], 0
	v_mfma_f32_16x16x32_bf16 v[34:37], v[178:181], v[234:237], v[34:37]
	v_mfma_f32_16x16x32_bf16 v[46:49], v[166:169], v[234:237], 0
	v_mfma_f32_16x16x32_bf16 v[46:49], v[174:177], v[238:241], v[46:49]
	v_mfma_f32_16x16x32_bf16 v[54:57], v[162:165], v[238:241], 0
	v_mfma_f32_16x16x32_bf16 v[54:57], v[158:161], v[234:237], v[54:57]
	v_mfma_f32_16x16x32_bf16 v[38:41], v[158:161], v[242:245], 0
	v_mfma_f32_16x16x32_bf16 v[38:41], v[162:165], v[246:249], v[38:41]
	v_mfma_f32_16x16x32_bf16 v[30:33], v[174:177], v[246:249], 0
	v_mfma_f32_16x16x32_bf16 v[30:33], v[166:169], v[242:245], v[30:33]
	v_mfma_f32_16x16x32_bf16 v[18:21], v[178:181], v[242:245], 0
	v_mfma_f32_16x16x32_bf16 v[18:21], v[182:185], v[246:249], v[18:21]
	v_mfma_f32_16x16x32_bf16 v[10:13], v[190:193], v[246:249], 0
	v_mfma_f32_16x16x32_bf16 v[10:13], v[186:189], v[242:245], v[10:13]
	v_mfma_f32_16x16x32_bf16 v[2:5], v[186:189], v[250:253], 0
	v_mfma_f32_16x16x32_bf16 v[2:5], v[190:193], v[142:145], v[2:5]
	v_mfma_f32_16x16x32_bf16 v[6:9], v[182:185], v[142:145], 0
	v_mfma_f32_16x16x32_bf16 v[6:9], v[178:181], v[250:253], v[6:9]
	v_mfma_f32_16x16x32_bf16 v[14:17], v[166:169], v[250:253], 0
	v_mfma_f32_16x16x32_bf16 v[14:17], v[174:177], v[142:145], v[14:17]
	v_mfma_f32_16x16x32_bf16 v[22:25], v[162:165], v[142:145], 0
	v_mfma_f32_16x16x32_bf16 v[22:25], v[158:161], v[250:253], v[22:25]
	s_waitcnt vmcnt(0)
	s_barrier
; #define PG8_STAGE(bufoff, gbase, voff) do { _Pragma("unroll") for (int _i = 0; _i < 2; ++_i) \
;         __builtin_amdgcn_global_load_lds((const unsigned*)((const char*)(gbase) + (voff)[_i]), (PG8_LAS unsigned*)(lds + (bufoff) + ldsw + _i * 8192), 16, 0, 0); } while (0)
; #define PG8_LDA(dst, b, h) do { _Pragma("unroll") for (int m = 0; m < 4; ++m) _Pragma("unroll") for (int k = 0; k < 2; ++k) dst[m][k] = *(const PG8_LAS bf16x8*)(lds + PG8_SA(b, h) + aoff + m * 2048 + k * 1024); } while (0)
; #define PG8_LDB(dst, b, h) do { _Pragma("unroll") for (int n = 0; n < 2; ++n) _Pragma("unroll") for (int k = 0; k < 2; ++k) dst[n][k] = *(const PG8_LAS bf16x8*)(lds + PG8_SB(b, h) + boff + n * 2048 + k * 1024); } while (0)
; #define PG8_MMA(ai, bj, At, Bt) do { __builtin_amdgcn_s_setprio(1); _Pragma("unroll") for (int m = 0; m < 4; ++m) _Pragma("unroll") for (int n = 0; n < 2; ++n) _Pragma("unroll") for (int k = 0; k < 2; ++k) \
;         acc[ai][bj][m][n] = __builtin_amdgcn_mfma_f32_16x16x32_bf16(Bt[n][k], At[m][k], acc[ai][bj][m][n], 0, 0, 0); __builtin_amdgcn_s_setprio(0); } while (0)
; #define PG8_WAIT_V(n) asm volatile("s_waitcnt vmcnt(" #n ")" ::: "memory")
; template <class Epi, class Sched, bool ALIGN_EPI>
; __device__ __forceinline__ void gemm_phase(PG8_LAS unsigned char* lds, const Gemm g, const Sched& S, const Epi& E) {
;     ...
;             PG8_LDB(B0, 0, 0); PG8_LDB(B1, 0, 1); PG8_SCHED; PG8_LDA(At, 0, 0); PG8_STAGE(PG8_SA(1, 1), a1 + hstepA, voffA);
;             PG8_WAIT_V(8); PG8_WAIT_L(0); PG8_BAR; PG8_MMA(0, 0, At, B0); PG8_MMA(0, 1, At, B1); PG8_BAR; PG8_SCHED;
;             PG8_LDA(At, 0, 1); PG8_STAGE(PG8_SB(0, 0), b2, voffB); PG8_STAGE(PG8_SB(0, 1), b2 + hstepB, voffB); PG8_STAGE(PG8_SA(0, 0), a2, voffA);
;             PG8_WAIT_V(8); PG8_WAIT_L(0); PG8_BAR; PG8_MMA(1, 0, At, B0); PG8_MMA(1, 1, At, B1); PG8_BAR; PG8_SCHED;
;             PG8_LDB(B0, 1, 0); PG8_LDB(B1, 1, 1); PG8_SCHED; PG8_LDA(At, 1, 0); PG8_STAGE(PG8_SA(0, 1), a2 + hstepA, voffA);
;             PG8_WAIT_V(8); PG8_WAIT_L(0); PG8_BAR; PG8_MMA(0, 0, At, B0); PG8_MMA(0, 1, At, B1); PG8_BAR; PG8_SCHED;
;             PG8_LDA(At, 1, 1); PG8_STAGE(PG8_SB(1, 0), b3, voffB); PG8_STAGE(PG8_SB(1, 1), b3 + hstepB, voffB); PG8_STAGE(PG8_SA(1, 0), a3, voffA);
;             PG8_WAIT_V(8); PG8_WAIT_L(0); PG8_BAR; PG8_MMA(1, 0, At, B0); PG8_MMA(1, 1, At, B1); PG8_BAR; PG8_SCHED;
	ds_read_b128 v[194:197], v157 offset:32768
	ds_read_b128 v[198:201], v157 offset:33792
	s_cmp_eq_u32 s57, 43
	s_cselect_b32 s28, s58, s28
	s_cselect_b32 s29, s59, s29
	s_add_i32 m0, s60, 0x2000
	s_nop 0
	global_load_lds_dwordx4 v134, s[28:29]
	ds_read_b128 v[202:205], v157 offset:34816
	ds_read_b128 v[206:209], v157 offset:35840
	s_add_u32 s30, s28, 0x58000
	s_addc_u32 s31, s29, 0
	s_add_i32 m0, s60, 0x3000
	s_nop 0
	global_load_lds_dwordx4 v134, s[30:31]
	ds_read_b128 v[210:213], v157 offset:36864
	ds_read_b128 v[214:217], v157 offset:37888
	s_add_u32 s30, s28, 0x160000
	s_addc_u32 s31, s29, 0
	s_add_i32 m0, s60, 0x6000
	s_nop 0
	global_load_lds_dwordx4 v134, s[30:31]
	ds_read_b128 v[218:221], v157 offset:38912
	ds_read_b128 v[222:225], v157 offset:39936
	s_add_u32 s30, s28, 0x1b8000
	s_addc_u32 s31, s29, 0
	s_add_i32 m0, s60, 0x7000
	s_nop 0
	global_load_lds_dwordx4 v134, s[30:31]
	ds_read_b128 v[158:161], v155 offset:32768
	ds_read_b128 v[162:165], v155 offset:33792
	s_add_u32 s34, s28, 0x80
	s_addc_u32 s35, s29, 0
	s_add_i32 m0, s60, 0x8000
	s_nop 0
	global_load_lds_dwordx4 v130, s[34:35]
	ds_read_b128 v[166:169], v155 offset:34816
	ds_read_b128 v[174:177], v155 offset:35840
	s_add_u32 s30, s34, 0x58000
	s_addc_u32 s31, s35, 0
	s_add_i32 m0, s60, 0x9000
	s_nop 0
	global_load_lds_dwordx4 v130, s[30:31]
	ds_read_b128 v[178:181], v155 offset:49152
	ds_read_b128 v[182:185], v155 offset:50176
	s_add_u32 s30, s34, 0x160000
	s_addc_u32 s31, s35, 0
	s_add_i32 m0, s60, 0xc000
	s_nop 0
	global_load_lds_dwordx4 v130, s[30:31]
	ds_read_b128 v[186:189], v155 offset:51200
	ds_read_b128 v[190:193], v155 offset:52224
	s_add_u32 s30, s34, 0x1b8000
	s_addc_u32 s31, s35, 0
	s_add_i32 m0, s60, 0xd000
	s_nop 0
	global_load_lds_dwordx4 v130, s[30:31]
	ds_read_b128 v[226:229], v157 offset:49152
	ds_read_b128 v[230:233], v157 offset:50176
	ds_read_b128 v[234:237], v157 offset:51200
	ds_read_b128 v[238:241], v157 offset:52224
	ds_read_b128 v[242:245], v157 offset:53248
	ds_read_b128 v[246:249], v157 offset:54272
	ds_read_b128 v[250:253], v157 offset:55296
	ds_read_b128 v[142:145], v157 offset:56320
	s_add_u32 s28, s28, 0x80
	s_addc_u32 s29, s29, 0
	s_waitcnt vmcnt(8) lgkmcnt(0)
	s_barrier
	v_mfma_f32_16x16x32_bf16 v[126:129], v[158:161], v[194:197], v[126:129]
	v_mfma_f32_16x16x32_bf16 v[126:129], v[162:165], v[198:201], v[126:129]
	v_mfma_f32_16x16x32_bf16 v[122:125], v[174:177], v[198:201], v[122:125]
	v_mfma_f32_16x16x32_bf16 v[122:125], v[166:169], v[194:197], v[122:125]
	v_mfma_f32_16x16x32_bf16 v[114:117], v[178:181], v[194:197], v[114:117]
	v_mfma_f32_16x16x32_bf16 v[114:117], v[182:185], v[198:201], v[114:117]
	v_mfma_f32_16x16x32_bf16 v[106:109], v[190:193], v[198:201], v[106:109]
	v_mfma_f32_16x16x32_bf16 v[106:109], v[186:189], v[194:197], v[106:109]
	v_mfma_f32_16x16x32_bf16 v[90:93], v[186:189], v[202:205], v[90:93]
	v_mfma_f32_16x16x32_bf16 v[90:93], v[190:193], v[206:209], v[90:93]
	v_mfma_f32_16x16x32_bf16 v[98:101], v[182:185], v[206:209], v[98:101]
	v_mfma_f32_16x16x32_bf16 v[98:101], v[178:181], v[202:205], v[98:101]
	v_mfma_f32_16x16x32_bf16 v[110:113], v[166:169], v[202:205], v[110:113]
	v_mfma_f32_16x16x32_bf16 v[110:113], v[174:177], v[206:209], v[110:113]
	v_mfma_f32_16x16x32_bf16 v[118:121], v[162:165], v[206:209], v[118:121]
	v_mfma_f32_16x16x32_bf16 v[118:121], v[158:161], v[202:205], v[118:121]
	v_mfma_f32_16x16x32_bf16 v[102:105], v[158:161], v[210:213], v[102:105]
	v_mfma_f32_16x16x32_bf16 v[102:105], v[162:165], v[214:217], v[102:105]
	v_mfma_f32_16x16x32_bf16 v[94:97], v[174:177], v[214:217], v[94:97]
	v_mfma_f32_16x16x32_bf16 v[94:97], v[166:169], v[210:213], v[94:97]
	v_mfma_f32_16x16x32_bf16 v[82:85], v[178:181], v[210:213], v[82:85]
	v_mfma_f32_16x16x32_bf16 v[82:85], v[182:185], v[214:217], v[82:85]
	v_mfma_f32_16x16x32_bf16 v[74:77], v[190:193], v[214:217], v[74:77]
	v_mfma_f32_16x16x32_bf16 v[74:77], v[186:189], v[210:213], v[74:77]
	v_mfma_f32_16x16x32_bf16 v[66:69], v[186:189], v[218:221], v[66:69]
	v_mfma_f32_16x16x32_bf16 v[66:69], v[190:193], v[222:225], v[66:69]
	v_mfma_f32_16x16x32_bf16 v[70:73], v[182:185], v[222:225], v[70:73]
	v_mfma_f32_16x16x32_bf16 v[70:73], v[178:181], v[218:221], v[70:73]
	v_mfma_f32_16x16x32_bf16 v[78:81], v[166:169], v[218:221], v[78:81]
	v_mfma_f32_16x16x32_bf16 v[78:81], v[174:177], v[222:225], v[78:81]
	v_mfma_f32_16x16x32_bf16 v[86:89], v[162:165], v[222:225], v[86:89]
	v_mfma_f32_16x16x32_bf16 v[86:89], v[158:161], v[218:221], v[86:89]
	v_mfma_f32_16x16x32_bf16 v[62:65], v[158:161], v[226:229], v[62:65]
	v_mfma_f32_16x16x32_bf16 v[62:65], v[162:165], v[230:233], v[62:65]
	v_mfma_f32_16x16x32_bf16 v[58:61], v[174:177], v[230:233], v[58:61]
	v_mfma_f32_16x16x32_bf16 v[58:61], v[166:169], v[226:229], v[58:61]
	v_mfma_f32_16x16x32_bf16 v[50:53], v[178:181], v[226:229], v[50:53]
	v_mfma_f32_16x16x32_bf16 v[50:53], v[182:185], v[230:233], v[50:53]
	v_mfma_f32_16x16x32_bf16 v[42:45], v[190:193], v[230:233], v[42:45]
	v_mfma_f32_16x16x32_bf16 v[42:45], v[186:189], v[226:229], v[42:45]
	v_mfma_f32_16x16x32_bf16 v[26:29], v[186:189], v[234:237], v[26:29]
	v_mfma_f32_16x16x32_bf16 v[26:29], v[190:193], v[238:241], v[26:29]
	v_mfma_f32_16x16x32_bf16 v[34:37], v[182:185], v[238:241], v[34:37]
	v_mfma_f32_16x16x32_bf16 v[34:37], v[178:181], v[234:237], v[34:37]
	v_mfma_f32_16x16x32_bf16 v[46:49], v[166:169], v[234:237], v[46:49]
	v_mfma_f32_16x16x32_bf16 v[46:49], v[174:177], v[238:241], v[46:49]
	v_mfma_f32_16x16x32_bf16 v[54:57], v[162:165], v[238:241], v[54:57]
	v_mfma_f32_16x16x32_bf16 v[54:57], v[158:161], v[234:237], v[54:57]
	v_mfma_f32_16x16x32_bf16 v[38:41], v[158:161], v[242:245], v[38:41]
	v_mfma_f32_16x16x32_bf16 v[38:41], v[162:165], v[246:249], v[38:41]
	v_mfma_f32_16x16x32_bf16 v[30:33], v[174:177], v[246:249], v[30:33]
	v_mfma_f32_16x16x32_bf16 v[30:33], v[166:169], v[242:245], v[30:33]
	v_mfma_f32_16x16x32_bf16 v[18:21], v[178:181], v[242:245], v[18:21]
	v_mfma_f32_16x16x32_bf16 v[18:21], v[182:185], v[246:249], v[18:21]
	v_mfma_f32_16x16x32_bf16 v[10:13], v[190:193], v[246:249], v[10:13]
	v_mfma_f32_16x16x32_bf16 v[10:13], v[186:189], v[242:245], v[10:13]
	v_mfma_f32_16x16x32_bf16 v[2:5], v[186:189], v[250:253], v[2:5]
	v_mfma_f32_16x16x32_bf16 v[2:5], v[190:193], v[142:145], v[2:5]
	v_mfma_f32_16x16x32_bf16 v[6:9], v[182:185], v[142:145], v[6:9]
	v_mfma_f32_16x16x32_bf16 v[6:9], v[178:181], v[250:253], v[6:9]
	v_mfma_f32_16x16x32_bf16 v[14:17], v[166:169], v[250:253], v[14:17]
	v_mfma_f32_16x16x32_bf16 v[14:17], v[174:177], v[142:145], v[14:17]
	v_mfma_f32_16x16x32_bf16 v[22:25], v[162:165], v[142:145], v[22:25]
	v_mfma_f32_16x16x32_bf16 v[22:25], v[158:161], v[250:253], v[22:25]
	s_waitcnt vmcnt(0)
	s_barrier
	s_add_i32 s57, s57, 1
; #define PG8_STAGE(bufoff, gbase, voff) do { _Pragma("unroll") for (int _i = 0; _i < 2; ++_i) \
;         __builtin_amdgcn_global_load_lds((const unsigned*)((const char*)(gbase) + (voff)[_i]), (PG8_LAS unsigned*)(lds + (bufoff) + ldsw + _i * 8192), 16, 0, 0); } while (0)
; #define PG8_LDA(dst, b, h) do { _Pragma("unroll") for (int m = 0; m < 4; ++m) _Pragma("unroll") for (int k = 0; k < 2; ++k) dst[m][k] = *(const PG8_LAS bf16x8*)(lds + PG8_SA(b, h) + aoff + m * 2048 + k * 1024); } while (0)
; #define PG8_LDB(dst, b, h) do { _Pragma("unroll") for (int n = 0; n < 2; ++n) _Pragma("unroll") for (int k = 0; k < 2; ++k) dst[n][k] = *(const PG8_LAS bf16x8*)(lds + PG8_SB(b, h) + boff + n * 2048 + k * 1024); } while (0)
; template <class Epi, class Sched, bool ALIGN_EPI>
; __device__ __forceinline__ void gemm_phase(PG8_LAS unsigned char* lds, const Gemm g, const Sched& S, const Epi& E) {
;     ...
;         for (int t = 0; t < nt; t += 2) {
;             if constexpr (Epi::MIDK) { if (t == (nt >> 1)) E.midk(acc, cur, wr, fr); }
;             const bool last = (t == nt - 2);
;             const char* a1 = cA + (size_t)(t + 1) * kstepA;
;             const char* a2 = last ? nA : cA + (size_t)(t + 2) * kstepA; const char* b2 = last ? nB : cB + (size_t)(t + 2) * kstep;
;             const char* a3 = a2 + kstepA; const char* b3 = b2 + kstep;
;             PG8_LDB(B0, 0, 0); PG8_LDB(B1, 0, 1); PG8_SCHED; PG8_LDA(At, 0, 0); PG8_STAGE(PG8_SA(1, 1), a1 + hstepA, voffA);
;             PG8_WAIT_V(8); PG8_WAIT_L(0); PG8_BAR; PG8_MMA(0, 0, At, B0); PG8_MMA(0, 1, At, B1); PG8_BAR; PG8_SCHED;
;             PG8_LDA(At, 0, 1); PG8_STAGE(PG8_SB(0, 0), b2, voffB); PG8_STAGE(PG8_SB(0, 1), b2 + hstepB, voffB); PG8_STAGE(PG8_SA(0, 0), a2, voffA);
;             PG8_WAIT_V(8); PG8_WAIT_L(0); PG8_BAR; PG8_MMA(1, 0, At, B0); PG8_MMA(1, 1, At, B1); PG8_BAR; PG8_SCHED;
;             PG8_LDB(B0, 1, 0); PG8_LDB(B1, 1, 1); PG8_SCHED; PG8_LDA(At, 1, 0); PG8_STAGE(PG8_SA(0, 1), a2 + hstepA, voffA);
;             PG8_WAIT_V(8); PG8_WAIT_L(0); PG8_BAR; PG8_MMA(0, 0, At, B0); PG8_MMA(0, 1, At, B1); PG8_BAR; PG8_SCHED;
;             PG8_LDA(At, 1, 1); PG8_STAGE(PG8_SB(1, 0), b3, voffB); PG8_STAGE(PG8_SB(1, 1), b3 + hstepB, voffB); PG8_STAGE(PG8_SA(1, 0), a3, voffA);
;             PG8_WAIT_V(8); PG8_WAIT_L(0); PG8_BAR; PG8_MMA(1, 0, At, B0); PG8_MMA(1, 1, At, B1); PG8_BAR; PG8_SCHED;
.Lp9k_B_loop:
	ds_read_b128 v[194:197], v157 offset:0
	ds_read_b128 v[198:201], v157 offset:1024
	s_add_i32 m0, s60, 0xa000
	s_nop 0
	global_load_lds_dwordx4 v134, s[28:29]
	ds_read_b128 v[202:205], v157 offset:2048
	ds_read_b128 v[206:209], v157 offset:3072
	s_add_u32 s30, s28, 0x58000
	s_addc_u32 s31, s29, 0
	s_add_i32 m0, s60, 0xb000
	s_nop 0
	global_load_lds_dwordx4 v134, s[30:31]
	ds_read_b128 v[210:213], v157 offset:4096
	ds_read_b128 v[214:217], v157 offset:5120
	s_add_u32 s30, s28, 0x160000
	s_addc_u32 s31, s29, 0
	s_add_i32 m0, s60, 0xe000
	s_nop 0
	global_load_lds_dwordx4 v134, s[30:31]
	ds_read_b128 v[218:221], v157 offset:6144
	ds_read_b128 v[222:225], v157 offset:7168
	s_add_u32 s30, s28, 0x1b8000
	s_addc_u32 s31, s29, 0
	s_add_i32 m0, s60, 0xf000
	s_nop 0
	global_load_lds_dwordx4 v134, s[30:31]
	ds_read_b128 v[158:161], v155 offset:0
	ds_read_b128 v[162:165], v155 offset:1024
	s_add_u32 s34, s28, 0x80
	s_addc_u32 s35, s29, 0
	s_cmp_eq_u32 s57, 43
	s_cselect_b32 s34, s58, s34
	s_cselect_b32 s35, s59, s35
	s_add_i32 m0, s60, 0x0
	s_nop 0
	global_load_lds_dwordx4 v130, s[34:35]
	ds_read_b128 v[166:169], v155 offset:2048
	ds_read_b128 v[174:177], v155 offset:3072
	s_add_u32 s30, s34, 0x58000
	s_addc_u32 s31, s35, 0
	s_add_i32 m0, s60, 0x1000
	s_nop 0
	global_load_lds_dwordx4 v130, s[30:31]
	ds_read_b128 v[178:181], v155 offset:16384
	ds_read_b128 v[182:185], v155 offset:17408
	s_add_u32 s30, s34, 0x160000
	s_addc_u32 s31, s35, 0
	s_add_i32 m0, s60, 0x4000
	s_nop 0
	global_load_lds_dwordx4 v130, s[30:31]
	ds_read_b128 v[186:189], v155 offset:18432
	ds_read_b128 v[190:193], v155 offset:19456
	s_add_u32 s30, s34, 0x1b8000
	s_addc_u32 s31, s35, 0
	s_add_i32 m0, s60, 0x5000
	s_nop 0
	global_load_lds_dwordx4 v130, s[30:31]
	ds_read_b128 v[226:229], v157 offset:16384
	ds_read_b128 v[230:233], v157 offset:17408
	ds_read_b128 v[234:237], v157 offset:18432
	ds_read_b128 v[238:241], v157 offset:19456
	ds_read_b128 v[242:245], v157 offset:20480
	ds_read_b128 v[246:249], v157 offset:21504
	ds_read_b128 v[250:253], v157 offset:22528
	ds_read_b128 v[142:145], v157 offset:23552
	s_add_u32 s28, s28, 0x80
	s_addc_u32 s29, s29, 0
	s_waitcnt vmcnt(8) lgkmcnt(0)
	s_barrier
	v_mfma_f32_16x16x32_bf16 v[126:129], v[158:161], v[194:197], v[126:129]
	v_mfma_f32_16x16x32_bf16 v[126:129], v[162:165], v[198:201], v[126:129]
	v_mfma_f32_16x16x32_bf16 v[122:125], v[174:177], v[198:201], v[122:125]
	v_mfma_f32_16x16x32_bf16 v[122:125], v[166:169], v[194:197], v[122:125]
	v_mfma_f32_16x16x32_bf16 v[114:117], v[178:181], v[194:197], v[114:117]
	v_mfma_f32_16x16x32_bf16 v[114:117], v[182:185], v[198:201], v[114:117]
	v_mfma_f32_16x16x32_bf16 v[106:109], v[190:193], v[198:201], v[106:109]
	v_mfma_f32_16x16x32_bf16 v[106:109], v[186:189], v[194:197], v[106:109]
	v_mfma_f32_16x16x32_bf16 v[90:93], v[186:189], v[202:205], v[90:93]
	v_mfma_f32_16x16x32_bf16 v[90:93], v[190:193], v[206:209], v[90:93]
	v_mfma_f32_16x16x32_bf16 v[98:101], v[182:185], v[206:209], v[98:101]
	v_mfma_f32_16x16x32_bf16 v[98:101], v[178:181], v[202:205], v[98:101]
	v_mfma_f32_16x16x32_bf16 v[110:113], v[166:169], v[202:205], v[110:113]
	v_mfma_f32_16x16x32_bf16 v[110:113], v[174:177], v[206:209], v[110:113]
	v_mfma_f32_16x16x32_bf16 v[118:121], v[162:165], v[206:209], v[118:121]
	v_mfma_f32_16x16x32_bf16 v[118:121], v[158:161], v[202:205], v[118:121]
	v_mfma_f32_16x16x32_bf16 v[102:105], v[158:161], v[210:213], v[102:105]
	v_mfma_f32_16x16x32_bf16 v[102:105], v[162:165], v[214:217], v[102:105]
	v_mfma_f32_16x16x32_bf16 v[94:97], v[174:177], v[214:217], v[94:97]
	v_mfma_f32_16x16x32_bf16 v[94:97], v[166:169], v[210:213], v[94:97]
	v_mfma_f32_16x16x32_bf16 v[82:85], v[178:181], v[210:213], v[82:85]
	v_mfma_f32_16x16x32_bf16 v[82:85], v[182:185], v[214:217], v[82:85]
	v_mfma_f32_16x16x32_bf16 v[74:77], v[190:193], v[214:217], v[74:77]
	v_mfma_f32_16x16x32_bf16 v[74:77], v[186:189], v[210:213], v[74:77]
	v_mfma_f32_16x16x32_bf16 v[66:69], v[186:189], v[218:221], v[66:69]
	v_mfma_f32_16x16x32_bf16 v[66:69], v[190:193], v[222:225], v[66:69]
	v_mfma_f32_16x16x32_bf16 v[70:73], v[182:185], v[222:225], v[70:73]
	v_mfma_f32_16x16x32_bf16 v[70:73], v[178:181], v[218:221], v[70:73]
	v_mfma_f32_16x16x32_bf16 v[78:81], v[166:169], v[218:221], v[78:81]
	v_mfma_f32_16x16x32_bf16 v[78:81], v[174:177], v[222:225], v[78:81]
	v_mfma_f32_16x16x32_bf16 v[86:89], v[162:165], v[222:225], v[86:89]
	v_mfma_f32_16x16x32_bf16 v[86:89], v[158:161], v[218:221], v[86:89]
	v_mfma_f32_16x16x32_bf16 v[62:65], v[158:161], v[226:229], v[62:65]
	v_mfma_f32_16x16x32_bf16 v[62:65], v[162:165], v[230:233], v[62:65]
	v_mfma_f32_16x16x32_bf16 v[58:61], v[174:177], v[230:233], v[58:61]
	v_mfma_f32_16x16x32_bf16 v[58:61], v[166:169], v[226:229], v[58:61]
	v_mfma_f32_16x16x32_bf16 v[50:53], v[178:181], v[226:229], v[50:53]
	v_mfma_f32_16x16x32_bf16 v[50:53], v[182:185], v[230:233], v[50:53]
	v_mfma_f32_16x16x32_bf16 v[42:45], v[190:193], v[230:233], v[42:45]
	v_mfma_f32_16x16x32_bf16 v[42:45], v[186:189], v[226:229], v[42:45]
	v_mfma_f32_16x16x32_bf16 v[26:29], v[186:189], v[234:237], v[26:29]
	v_mfma_f32_16x16x32_bf16 v[26:29], v[190:193], v[238:241], v[26:29]
	v_mfma_f32_16x16x32_bf16 v[34:37], v[182:185], v[238:241], v[34:37]
	v_mfma_f32_16x16x32_bf16 v[34:37], v[178:181], v[234:237], v[34:37]
	v_mfma_f32_16x16x32_bf16 v[46:49], v[166:169], v[234:237], v[46:49]
	v_mfma_f32_16x16x32_bf16 v[46:49], v[174:177], v[238:241], v[46:49]
	v_mfma_f32_16x16x32_bf16 v[54:57], v[162:165], v[238:241], v[54:57]
	v_mfma_f32_16x16x32_bf16 v[54:57], v[158:161], v[234:237], v[54:57]
	v_mfma_f32_16x16x32_bf16 v[38:41], v[158:161], v[242:245], v[38:41]
	v_mfma_f32_16x16x32_bf16 v[38:41], v[162:165], v[246:249], v[38:41]
	v_mfma_f32_16x16x32_bf16 v[30:33], v[174:177], v[246:249], v[30:33]
	v_mfma_f32_16x16x32_bf16 v[30:33], v[166:169], v[242:245], v[30:33]
	v_mfma_f32_16x16x32_bf16 v[18:21], v[178:181], v[242:245], v[18:21]
	v_mfma_f32_16x16x32_bf16 v[18:21], v[182:185], v[246:249], v[18:21]
	v_mfma_f32_16x16x32_bf16 v[10:13], v[190:193], v[246:249], v[10:13]
	v_mfma_f32_16x16x32_bf16 v[10:13], v[186:189], v[242:245], v[10:13]
	v_mfma_f32_16x16x32_bf16 v[2:5], v[186:189], v[250:253], v[2:5]
	v_mfma_f32_16x16x32_bf16 v[2:5], v[190:193], v[142:145], v[2:5]
	v_mfma_f32_16x16x32_bf16 v[6:9], v[182:185], v[142:145], v[6:9]
	v_mfma_f32_16x16x32_bf16 v[6:9], v[178:181], v[250:253], v[6:9]
	v_mfma_f32_16x16x32_bf16 v[14:17], v[166:169], v[250:253], v[14:17]
	v_mfma_f32_16x16x32_bf16 v[14:17], v[174:177], v[142:145], v[14:17]
	v_mfma_f32_16x16x32_bf16 v[22:25], v[162:165], v[142:145], v[22:25]
	v_mfma_f32_16x16x32_bf16 v[22:25], v[158:161], v[250:253], v[22:25]
	s_waitcnt vmcnt(0)
	s_barrier
; #define PG8_STAGE(bufoff, gbase, voff) do { _Pragma("unroll") for (int _i = 0; _i < 2; ++_i) \
;         __builtin_amdgcn_global_load_lds((const unsigned*)((const char*)(gbase) + (voff)[_i]), (PG8_LAS unsigned*)(lds + (bufoff) + ldsw + _i * 8192), 16, 0, 0); } while (0)
; #define PG8_LDA(dst, b, h) do { _Pragma("unroll") for (int m = 0; m < 4; ++m) _Pragma("unroll") for (int k = 0; k < 2; ++k) dst[m][k] = *(const PG8_LAS bf16x8*)(lds + PG8_SA(b, h) + aoff + m * 2048 + k * 1024); } while (0)
; #define PG8_LDB(dst, b, h) do { _Pragma("unroll") for (int n = 0; n < 2; ++n) _Pragma("unroll") for (int k = 0; k < 2; ++k) dst[n][k] = *(const PG8_LAS bf16x8*)(lds + PG8_SB(b, h) + boff + n * 2048 + k * 1024); } while (0)
; #define PG8_MMA(ai, bj, At, Bt) do { __builtin_amdgcn_s_setprio(1); _Pragma("unroll") for (int m = 0; m < 4; ++m) _Pragma("unroll") for (int n = 0; n < 2; ++n) _Pragma("unroll") for (int k = 0; k < 2; ++k) \
;         acc[ai][bj][m][n] = __builtin_amdgcn_mfma_f32_16x16x32_bf16(Bt[n][k], At[m][k], acc[ai][bj][m][n], 0, 0, 0); __builtin_amdgcn_s_setprio(0); } while (0)
; #define PG8_WAIT_V(n) asm volatile("s_waitcnt vmcnt(" #n ")" ::: "memory")
; template <class Epi, class Sched, bool ALIGN_EPI>
; __device__ __forceinline__ void gemm_phase(PG8_LAS unsigned char* lds, const Gemm g, const Sched& S, const Epi& E) {
;     ...
;             PG8_LDB(B0, 0, 0); PG8_LDB(B1, 0, 1); PG8_SCHED; PG8_LDA(At, 0, 0); PG8_STAGE(PG8_SA(1, 1), a1 + hstepA, voffA);
;             PG8_WAIT_V(8); PG8_WAIT_L(0); PG8_BAR; PG8_MMA(0, 0, At, B0); PG8_MMA(0, 1, At, B1); PG8_BAR; PG8_SCHED;
;             PG8_LDA(At, 0, 1); PG8_STAGE(PG8_SB(0, 0), b2, voffB); PG8_STAGE(PG8_SB(0, 1), b2 + hstepB, voffB); PG8_STAGE(PG8_SA(0, 0), a2, voffA);
;             PG8_WAIT_V(8); PG8_WAIT_L(0); PG8_BAR; PG8_MMA(1, 0, At, B0); PG8_MMA(1, 1, At, B1); PG8_BAR; PG8_SCHED;
;             PG8_LDB(B0, 1, 0); PG8_LDB(B1, 1, 1); PG8_SCHED; PG8_LDA(At, 1, 0); PG8_STAGE(PG8_SA(0, 1), a2 + hstepA, voffA);
;             PG8_WAIT_V(8); PG8_WAIT_L(0); PG8_BAR; PG8_MMA(0, 0, At, B0); PG8_MMA(0, 1, At, B1); PG8_BAR; PG8_SCHED;
;             PG8_LDA(At, 1, 1); PG8_STAGE(PG8_SB(1, 0), b3, voffB); PG8_STAGE(PG8_SB(1, 1), b3 + hstepB, voffB); PG8_STAGE(PG8_SA(1, 0), a3, voffA);
;             PG8_WAIT_V(8); PG8_WAIT_L(0); PG8_BAR; PG8_MMA(1, 0, At, B0); PG8_MMA(1, 1, At, B1); PG8_BAR; PG8_SCHED;
;         }
	ds_read_b128 v[194:197], v157 offset:32768
	ds_read_b128 v[198:201], v157 offset:33792
	s_cmp_eq_u32 s57, 43
	s_cselect_b32 s28, s58, s28
	s_cselect_b32 s29, s59, s29
	s_add_i32 m0, s60, 0x2000
	s_nop 0
	global_load_lds_dwordx4 v134, s[28:29]
	ds_read_b128 v[202:205], v157 offset:34816
	ds_read_b128 v[206:209], v157 offset:35840
	s_add_u32 s30, s28, 0x58000
	s_addc_u32 s31, s29, 0
	s_add_i32 m0, s60, 0x3000
	s_nop 0
	global_load_lds_dwordx4 v134, s[30:31]
	ds_read_b128 v[210:213], v157 offset:36864
	ds_read_b128 v[214:217], v157 offset:37888
	s_add_u32 s30, s28, 0x160000
	s_addc_u32 s31, s29, 0
	s_add_i32 m0, s60, 0x6000
	s_nop 0
	global_load_lds_dwordx4 v134, s[30:31]
	ds_read_b128 v[218:221], v157 offset:38912
	ds_read_b128 v[222:225], v157 offset:39936
	s_add_u32 s30, s28, 0x1b8000
	s_addc_u32 s31, s29, 0
	s_add_i32 m0, s60, 0x7000
	s_nop 0
	global_load_lds_dwordx4 v134, s[30:31]
	ds_read_b128 v[158:161], v155 offset:32768
	ds_read_b128 v[162:165], v155 offset:33792
	s_add_u32 s34, s28, 0x80
	s_addc_u32 s35, s29, 0
	s_add_i32 m0, s60, 0x8000
	s_nop 0
	global_load_lds_dwordx4 v130, s[34:35]
	ds_read_b128 v[166:169], v155 offset:34816
	ds_read_b128 v[174:177], v155 offset:35840
	s_add_u32 s30, s34, 0x58000
	s_addc_u32 s31, s35, 0
	s_add_i32 m0, s60, 0x9000
	s_nop 0
	global_load_lds_dwordx4 v130, s[30:31]
	ds_read_b128 v[178:181], v155 offset:49152
	ds_read_b128 v[182:185], v155 offset:50176
	s_add_u32 s30, s34, 0x160000
	s_addc_u32 s31, s35, 0
	s_add_i32 m0, s60, 0xc000
	s_nop 0
	global_load_lds_dwordx4 v130, s[30:31]
	ds_read_b128 v[186:189], v155 offset:51200
	ds_read_b128 v[190:193], v155 offset:52224
	s_add_u32 s30, s34, 0x1b8000
	s_addc_u32 s31, s35, 0
	s_add_i32 m0, s60, 0xd000
	s_nop 0
	global_load_lds_dwordx4 v130, s[30:31]
	ds_read_b128 v[226:229], v157 offset:49152
	ds_read_b128 v[230:233], v157 offset:50176
	ds_read_b128 v[234:237], v157 offset:51200
	ds_read_b128 v[238:241], v157 offset:52224
	ds_read_b128 v[242:245], v157 offset:53248
	ds_read_b128 v[246:249], v157 offset:54272
	ds_read_b128 v[250:253], v157 offset:55296
	ds_read_b128 v[142:145], v157 offset:56320
	s_add_u32 s28, s28, 0x80
	s_addc_u32 s29, s29, 0
	s_waitcnt vmcnt(8) lgkmcnt(0)
	s_barrier
	v_mfma_f32_16x16x32_bf16 v[126:129], v[158:161], v[194:197], v[126:129]
	v_mfma_f32_16x16x32_bf16 v[126:129], v[162:165], v[198:201], v[126:129]
	v_mfma_f32_16x16x32_bf16 v[122:125], v[174:177], v[198:201], v[122:125]
	v_mfma_f32_16x16x32_bf16 v[122:125], v[166:169], v[194:197], v[122:125]
	v_mfma_f32_16x16x32_bf16 v[114:117], v[178:181], v[194:197], v[114:117]
	v_mfma_f32_16x16x32_bf16 v[114:117], v[182:185], v[198:201], v[114:117]
	v_mfma_f32_16x16x32_bf16 v[106:109], v[190:193], v[198:201], v[106:109]
	v_mfma_f32_16x16x32_bf16 v[106:109], v[186:189], v[194:197], v[106:109]
	v_mfma_f32_16x16x32_bf16 v[90:93], v[186:189], v[202:205], v[90:93]
	v_mfma_f32_16x16x32_bf16 v[90:93], v[190:193], v[206:209], v[90:93]
	v_mfma_f32_16x16x32_bf16 v[98:101], v[182:185], v[206:209], v[98:101]
	v_mfma_f32_16x16x32_bf16 v[98:101], v[178:181], v[202:205], v[98:101]
	v_mfma_f32_16x16x32_bf16 v[110:113], v[166:169], v[202:205], v[110:113]
	v_mfma_f32_16x16x32_bf16 v[110:113], v[174:177], v[206:209], v[110:113]
	v_mfma_f32_16x16x32_bf16 v[118:121], v[162:165], v[206:209], v[118:121]
	v_mfma_f32_16x16x32_bf16 v[118:121], v[158:161], v[202:205], v[118:121]
	v_mfma_f32_16x16x32_bf16 v[102:105], v[158:161], v[210:213], v[102:105]
	v_mfma_f32_16x16x32_bf16 v[102:105], v[162:165], v[214:217], v[102:105]
	v_mfma_f32_16x16x32_bf16 v[94:97], v[174:177], v[214:217], v[94:97]
	v_mfma_f32_16x16x32_bf16 v[94:97], v[166:169], v[210:213], v[94:97]
	v_mfma_f32_16x16x32_bf16 v[82:85], v[178:181], v[210:213], v[82:85]
	v_mfma_f32_16x16x32_bf16 v[82:85], v[182:185], v[214:217], v[82:85]
	v_mfma_f32_16x16x32_bf16 v[74:77], v[190:193], v[214:217], v[74:77]
	v_mfma_f32_16x16x32_bf16 v[74:77], v[186:189], v[210:213], v[74:77]
	v_mfma_f32_16x16x32_bf16 v[66:69], v[186:189], v[218:221], v[66:69]
	v_mfma_f32_16x16x32_bf16 v[66:69], v[190:193], v[222:225], v[66:69]
	v_mfma_f32_16x16x32_bf16 v[70:73], v[182:185], v[222:225], v[70:73]
	v_mfma_f32_16x16x32_bf16 v[70:73], v[178:181], v[218:221], v[70:73]
	v_mfma_f32_16x16x32_bf16 v[78:81], v[166:169], v[218:221], v[78:81]
	v_mfma_f32_16x16x32_bf16 v[78:81], v[174:177], v[222:225], v[78:81]
	v_mfma_f32_16x16x32_bf16 v[86:89], v[162:165], v[222:225], v[86:89]
	v_mfma_f32_16x16x32_bf16 v[86:89], v[158:161], v[218:221], v[86:89]
	v_mfma_f32_16x16x32_bf16 v[62:65], v[158:161], v[226:229], v[62:65]
	v_mfma_f32_16x16x32_bf16 v[62:65], v[162:165], v[230:233], v[62:65]
	v_mfma_f32_16x16x32_bf16 v[58:61], v[174:177], v[230:233], v[58:61]
	v_mfma_f32_16x16x32_bf16 v[58:61], v[166:169], v[226:229], v[58:61]
	v_mfma_f32_16x16x32_bf16 v[50:53], v[178:181], v[226:229], v[50:53]
	v_mfma_f32_16x16x32_bf16 v[50:53], v[182:185], v[230:233], v[50:53]
	v_mfma_f32_16x16x32_bf16 v[42:45], v[190:193], v[230:233], v[42:45]
	v_mfma_f32_16x16x32_bf16 v[42:45], v[186:189], v[226:229], v[42:45]
	v_mfma_f32_16x16x32_bf16 v[26:29], v[186:189], v[234:237], v[26:29]
	v_mfma_f32_16x16x32_bf16 v[26:29], v[190:193], v[238:241], v[26:29]
	v_mfma_f32_16x16x32_bf16 v[34:37], v[182:185], v[238:241], v[34:37]
	v_mfma_f32_16x16x32_bf16 v[34:37], v[178:181], v[234:237], v[34:37]
	v_mfma_f32_16x16x32_bf16 v[46:49], v[166:169], v[234:237], v[46:49]
	v_mfma_f32_16x16x32_bf16 v[46:49], v[174:177], v[238:241], v[46:49]
	v_mfma_f32_16x16x32_bf16 v[54:57], v[162:165], v[238:241], v[54:57]
	v_mfma_f32_16x16x32_bf16 v[54:57], v[158:161], v[234:237], v[54:57]
	v_mfma_f32_16x16x32_bf16 v[38:41], v[158:161], v[242:245], v[38:41]
	v_mfma_f32_16x16x32_bf16 v[38:41], v[162:165], v[246:249], v[38:41]
	v_mfma_f32_16x16x32_bf16 v[30:33], v[174:177], v[246:249], v[30:33]
	v_mfma_f32_16x16x32_bf16 v[30:33], v[166:169], v[242:245], v[30:33]
	v_mfma_f32_16x16x32_bf16 v[18:21], v[178:181], v[242:245], v[18:21]
	v_mfma_f32_16x16x32_bf16 v[18:21], v[182:185], v[246:249], v[18:21]
	v_mfma_f32_16x16x32_bf16 v[10:13], v[190:193], v[246:249], v[10:13]
	v_mfma_f32_16x16x32_bf16 v[10:13], v[186:189], v[242:245], v[10:13]
	v_mfma_f32_16x16x32_bf16 v[2:5], v[186:189], v[250:253], v[2:5]
	v_mfma_f32_16x16x32_bf16 v[2:5], v[190:193], v[142:145], v[2:5]
	v_mfma_f32_16x16x32_bf16 v[6:9], v[182:185], v[142:145], v[6:9]
	v_mfma_f32_16x16x32_bf16 v[6:9], v[178:181], v[250:253], v[6:9]
	v_mfma_f32_16x16x32_bf16 v[14:17], v[166:169], v[250:253], v[14:17]
	v_mfma_f32_16x16x32_bf16 v[14:17], v[174:177], v[142:145], v[14:17]
	v_mfma_f32_16x16x32_bf16 v[22:25], v[162:165], v[142:145], v[22:25]
	v_mfma_f32_16x16x32_bf16 v[22:25], v[158:161], v[250:253], v[22:25]
	s_waitcnt vmcnt(0)
	s_add_i32 s57, s57, 1
	s_cmp_lt_u32 s57, 44
	s_cbranch_scc0 .Lp9k_B_exit
	s_barrier
	s_branch .Lp9k_B_loop
